# K-loop MMA blocks: full snake order - every consecutive MFMA pair is either an accumulate chain or shares one operand fragment (also across the two accumulator groups)
# baseline (speedup 1.0000x reference)
.LBB0_322:
	s_ashr_i32 s43, s42, 31
	s_lshl_b64 s[46:47], s[42:43], 19
	s_add_u32 s46, s12, s46
	s_addc_u32 s47, s13, s47
	s_and_b64 s[48:49], s[4:5], exec
	s_cselect_b32 s18, s47, s7
	s_cselect_b32 s43, s46, s6
	s_ashr_i32 s45, s44, 31
	s_lshl_b64 s[48:49], s[44:45], 19
	s_add_u32 s48, s59, s48
	s_addc_u32 s49, s60, s49
	s_and_b64 s[50:51], s[4:5], exec
	s_cselect_b32 s45, s49, s9
	s_cselect_b32 s55, s48, s8
	s_add_u32 s6, s6, 0x40080
	s_addc_u32 s7, s7, 0
	s_add_u32 s56, s8, 0x100
	s_addc_u32 s57, s9, 0
	s_mov_b32 s78, -2
	ds_read_b128 v[96:99], v209
	ds_read_b128 v[100:103], v209 offset:1024
	ds_read_b128 v[120:123], v209 offset:2048
	ds_read_b128 v[124:127], v209 offset:3072
	ds_read_b128 v[144:147], v210
	ds_read_b128 v[148:151], v210 offset:1024
	ds_read_b128 v[152:155], v210 offset:2048
	ds_read_b128 v[156:159], v210 offset:3072
	s_add_u32 s8, s6, 0xfffc0080
	s_addc_u32 s9, s7, -1
	s_cmp_eq_u32 s78, 12
	s_cselect_b32 s51, s18, s9
	s_cselect_b32 s50, s43, s8
	s_cselect_b32 s9, s45, s57
	s_cselect_b32 s8, s55, s56
	v_lshl_add_u64 v[206:207], s[6:7], 0, v[170:171]
	s_add_i32 m0, s17, 0xc000
	ds_read_b128 v[178:181], v211
	ds_read_b128 v[182:185], v211 offset:1024
	ds_read_b128 v[186:189], v211 offset:2048
	ds_read_b128 v[190:193], v211 offset:3072
	ds_read_b128 v[194:197], v211 offset:4096
	ds_read_b128 v[198:201], v211 offset:5120
	ds_read_b128 v[202:205], v211 offset:6144
	ds_read_b128 v[218:221], v211 offset:7168
	global_load_lds_dwordx4 v[206:207], off
	s_add_i32 m0, s17, 0xe000
	v_lshl_add_u64 v[206:207], s[6:7], 0, v[172:173]
	global_load_lds_dwordx4 v[206:207], off
	s_waitcnt vmcnt(8) lgkmcnt(0)
	s_barrier
	s_setprio 1
	v_mfma_f32_16x16x32_bf16 v[140:143], v[96:99], v[178:181], 0
	v_mfma_f32_16x16x32_bf16 v[140:143], v[100:103], v[182:185], v[140:143]
	v_mfma_f32_16x16x32_bf16 v[116:119], v[100:103], v[190:193], 0
	v_mfma_f32_16x16x32_bf16 v[116:119], v[96:99], v[186:189], v[116:119]
	v_mfma_f32_16x16x32_bf16 v[92:95], v[96:99], v[194:197], 0
	v_mfma_f32_16x16x32_bf16 v[92:95], v[100:103], v[198:201], v[92:95]
	v_mfma_f32_16x16x32_bf16 v[76:79], v[100:103], v[218:221], 0
	v_mfma_f32_16x16x32_bf16 v[76:79], v[96:99], v[202:205], v[76:79]
	v_mfma_f32_16x16x32_bf16 v[72:75], v[120:123], v[202:205], 0
	v_mfma_f32_16x16x32_bf16 v[72:75], v[124:127], v[218:221], v[72:75]
	v_mfma_f32_16x16x32_bf16 v[88:91], v[124:127], v[198:201], 0
	v_mfma_f32_16x16x32_bf16 v[88:91], v[120:123], v[194:197], v[88:91]
	v_mfma_f32_16x16x32_bf16 v[112:115], v[120:123], v[186:189], 0
	v_mfma_f32_16x16x32_bf16 v[112:115], v[124:127], v[190:193], v[112:115]
	v_mfma_f32_16x16x32_bf16 v[136:139], v[124:127], v[182:185], 0
	v_mfma_f32_16x16x32_bf16 v[136:139], v[120:123], v[178:181], v[136:139]
	v_mfma_f32_16x16x32_bf16 v[132:135], v[144:147], v[178:181], 0
	v_mfma_f32_16x16x32_bf16 v[132:135], v[148:151], v[182:185], v[132:135]
	v_mfma_f32_16x16x32_bf16 v[108:111], v[148:151], v[190:193], 0
	v_mfma_f32_16x16x32_bf16 v[108:111], v[144:147], v[186:189], v[108:111]
	v_mfma_f32_16x16x32_bf16 v[84:87], v[144:147], v[194:197], 0
	v_mfma_f32_16x16x32_bf16 v[84:87], v[148:151], v[198:201], v[84:87]
	v_mfma_f32_16x16x32_bf16 v[68:71], v[148:151], v[218:221], 0
	v_mfma_f32_16x16x32_bf16 v[68:71], v[144:147], v[202:205], v[68:71]
	v_mfma_f32_16x16x32_bf16 v[64:67], v[152:155], v[202:205], 0
	v_mfma_f32_16x16x32_bf16 v[64:67], v[156:159], v[218:221], v[64:67]
	v_mfma_f32_16x16x32_bf16 v[80:83], v[156:159], v[198:201], 0
	v_mfma_f32_16x16x32_bf16 v[80:83], v[152:155], v[194:197], v[80:83]
	s_setprio 2
	s_barrier
	v_mfma_f32_16x16x32_bf16 v[104:107], v[152:155], v[186:189], 0
	v_mfma_f32_16x16x32_bf16 v[104:107], v[156:159], v[190:193], v[104:107]
	v_mfma_f32_16x16x32_bf16 v[128:131], v[156:159], v[182:185], 0
	v_mfma_f32_16x16x32_bf16 v[128:131], v[152:155], v[178:181], v[128:131]
	s_setprio 2
	s_add_i32 s79, s73, s61
	v_lshl_add_u64 v[206:207], s[8:9], 0, v[162:163]
	s_mov_b32 m0, s79
	ds_read_b128 v[178:181], v211 offset:16384
	ds_read_b128 v[182:185], v211 offset:17408
	ds_read_b128 v[186:189], v211 offset:18432
	ds_read_b128 v[190:193], v211 offset:19456
	ds_read_b128 v[194:197], v211 offset:20480
	ds_read_b128 v[198:201], v211 offset:21504
	ds_read_b128 v[202:205], v211 offset:22528
	ds_read_b128 v[218:221], v211 offset:23552
	global_load_lds_dwordx4 v[206:207], off
	s_add_i32 m0, s79, 0x2000
	s_add_u32 s80, s8, 0x40000
	v_lshl_add_u64 v[222:223], s[8:9], 0, v[166:167]
	s_addc_u32 s81, s9, 0
	s_add_i32 s79, s74, s61
	global_load_lds_dwordx4 v[222:223], off
	v_lshl_add_u64 v[224:225], s[80:81], 0, v[162:163]
	s_mov_b32 m0, s79
	v_lshl_add_u64 v[226:227], s[50:51], 0, v[164:165]
	global_load_lds_dwordx4 v[224:225], off
	s_add_i32 m0, s79, 0x2000
	v_lshl_add_u64 v[224:225], s[80:81], 0, v[166:167]
	global_load_lds_dwordx4 v[224:225], off
	s_mov_b32 m0, s17
	v_lshl_add_u64 v[224:225], s[50:51], 0, v[160:161]
	global_load_lds_dwordx4 v[224:225], off
	s_mov_b32 m0, s62
	s_nop 0
	global_load_lds_dwordx4 v[226:227], off
	s_waitcnt vmcnt(8) lgkmcnt(0)
	s_barrier
	s_setprio 1
	v_mfma_f32_16x16x32_bf16 v[60:63], v[96:99], v[178:181], 0
	v_mfma_f32_16x16x32_bf16 v[60:63], v[100:103], v[182:185], v[60:63]
	v_mfma_f32_16x16x32_bf16 v[44:47], v[100:103], v[190:193], 0
	v_mfma_f32_16x16x32_bf16 v[44:47], v[96:99], v[186:189], v[44:47]
	v_mfma_f32_16x16x32_bf16 v[28:31], v[96:99], v[194:197], 0
	v_mfma_f32_16x16x32_bf16 v[28:31], v[100:103], v[198:201], v[28:31]
	v_mfma_f32_16x16x32_bf16 v[12:15], v[100:103], v[218:221], 0
	v_mfma_f32_16x16x32_bf16 v[12:15], v[96:99], v[202:205], v[12:15]
	v_mfma_f32_16x16x32_bf16 v[8:11], v[120:123], v[202:205], 0
	v_mfma_f32_16x16x32_bf16 v[8:11], v[124:127], v[218:221], v[8:11]
	v_mfma_f32_16x16x32_bf16 v[24:27], v[124:127], v[198:201], 0
	v_mfma_f32_16x16x32_bf16 v[24:27], v[120:123], v[194:197], v[24:27]
	v_mfma_f32_16x16x32_bf16 v[40:43], v[120:123], v[186:189], 0
	v_mfma_f32_16x16x32_bf16 v[40:43], v[124:127], v[190:193], v[40:43]
	v_mfma_f32_16x16x32_bf16 v[56:59], v[124:127], v[182:185], 0
	v_mfma_f32_16x16x32_bf16 v[56:59], v[120:123], v[178:181], v[56:59]
	v_mfma_f32_16x16x32_bf16 v[52:55], v[144:147], v[178:181], 0
	v_mfma_f32_16x16x32_bf16 v[52:55], v[148:151], v[182:185], v[52:55]
	v_mfma_f32_16x16x32_bf16 v[36:39], v[148:151], v[190:193], 0
	v_mfma_f32_16x16x32_bf16 v[36:39], v[144:147], v[186:189], v[36:39]
	v_mfma_f32_16x16x32_bf16 v[20:23], v[144:147], v[194:197], 0
	v_mfma_f32_16x16x32_bf16 v[20:23], v[148:151], v[198:201], v[20:23]
	v_mfma_f32_16x16x32_bf16 v[4:7], v[148:151], v[218:221], 0
	v_mfma_f32_16x16x32_bf16 v[4:7], v[144:147], v[202:205], v[4:7]
	v_mfma_f32_16x16x32_bf16 v[0:3], v[152:155], v[202:205], 0
	v_mfma_f32_16x16x32_bf16 v[0:3], v[156:159], v[218:221], v[0:3]
	v_mfma_f32_16x16x32_bf16 v[16:19], v[156:159], v[198:201], 0
	v_mfma_f32_16x16x32_bf16 v[16:19], v[152:155], v[194:197], v[16:19]
	s_setprio 2
	s_barrier
	v_mfma_f32_16x16x32_bf16 v[32:35], v[152:155], v[186:189], 0
	v_mfma_f32_16x16x32_bf16 v[32:35], v[156:159], v[190:193], v[32:35]
	v_mfma_f32_16x16x32_bf16 v[48:51], v[156:159], v[182:185], 0
	v_mfma_f32_16x16x32_bf16 v[48:51], v[152:155], v[178:181], v[48:51]
	s_setprio 0
	s_add_i32 s79, 0, 0x18000
	s_add_i32 s80, 0, 0x1c000
	v_add_u32_e32 v124, s79, v208
	v_add_u32_e32 v156, s80, v208
	ds_read_b128 v[96:99], v124
	ds_read_b128 v[100:103], v124 offset:1024
	ds_read_b128 v[120:123], v124 offset:2048
	ds_read_b128 v[124:127], v124 offset:3072
	ds_read_b128 v[144:147], v156
	ds_read_b128 v[148:151], v156 offset:1024
	ds_read_b128 v[152:155], v156 offset:2048
	ds_read_b128 v[156:159], v156 offset:3072
	s_add_u32 s50, s50, 0x40000
	s_addc_u32 s51, s51, 0
	s_mov_b32 m0, s63
	v_lshl_add_u64 v[228:229], s[50:51], 0, v[160:161]
	ds_read_b128 v[178:181], v211 offset:32768
	ds_read_b128 v[182:185], v211 offset:33792
	ds_read_b128 v[186:189], v211 offset:34816
	ds_read_b128 v[190:193], v211 offset:35840
	ds_read_b128 v[194:197], v211 offset:36864
	ds_read_b128 v[198:201], v211 offset:37888
	ds_read_b128 v[202:205], v211 offset:38912
	ds_read_b128 v[218:221], v211 offset:39936
	global_load_lds_dwordx4 v[228:229], off
	s_mov_b32 m0, s64
	v_lshl_add_u64 v[228:229], s[50:51], 0, v[164:165]
	global_load_lds_dwordx4 v[228:229], off
	s_waitcnt vmcnt(8) lgkmcnt(0)
	s_barrier
	s_setprio 1
	v_mfma_f32_16x16x32_bf16 v[140:143], v[96:99], v[178:181], v[140:143]
	v_mfma_f32_16x16x32_bf16 v[140:143], v[100:103], v[182:185], v[140:143]
	v_mfma_f32_16x16x32_bf16 v[116:119], v[100:103], v[190:193], v[116:119]
	v_mfma_f32_16x16x32_bf16 v[116:119], v[96:99], v[186:189], v[116:119]
	v_mfma_f32_16x16x32_bf16 v[92:95], v[96:99], v[194:197], v[92:95]
	v_mfma_f32_16x16x32_bf16 v[92:95], v[100:103], v[198:201], v[92:95]
	v_mfma_f32_16x16x32_bf16 v[76:79], v[100:103], v[218:221], v[76:79]
	v_mfma_f32_16x16x32_bf16 v[76:79], v[96:99], v[202:205], v[76:79]
	v_mfma_f32_16x16x32_bf16 v[72:75], v[120:123], v[202:205], v[72:75]
	v_mfma_f32_16x16x32_bf16 v[72:75], v[124:127], v[218:221], v[72:75]
	v_mfma_f32_16x16x32_bf16 v[88:91], v[124:127], v[198:201], v[88:91]
	v_mfma_f32_16x16x32_bf16 v[88:91], v[120:123], v[194:197], v[88:91]
	v_mfma_f32_16x16x32_bf16 v[112:115], v[120:123], v[186:189], v[112:115]
	v_mfma_f32_16x16x32_bf16 v[112:115], v[124:127], v[190:193], v[112:115]
	v_mfma_f32_16x16x32_bf16 v[136:139], v[124:127], v[182:185], v[136:139]
	v_mfma_f32_16x16x32_bf16 v[136:139], v[120:123], v[178:181], v[136:139]
	v_mfma_f32_16x16x32_bf16 v[132:135], v[144:147], v[178:181], v[132:135]
	v_mfma_f32_16x16x32_bf16 v[132:135], v[148:151], v[182:185], v[132:135]
	v_mfma_f32_16x16x32_bf16 v[108:111], v[148:151], v[190:193], v[108:111]
	v_mfma_f32_16x16x32_bf16 v[108:111], v[144:147], v[186:189], v[108:111]
	v_mfma_f32_16x16x32_bf16 v[84:87], v[144:147], v[194:197], v[84:87]
	v_mfma_f32_16x16x32_bf16 v[84:87], v[148:151], v[198:201], v[84:87]
	v_mfma_f32_16x16x32_bf16 v[68:71], v[148:151], v[218:221], v[68:71]
	v_mfma_f32_16x16x32_bf16 v[68:71], v[144:147], v[202:205], v[68:71]
	v_mfma_f32_16x16x32_bf16 v[64:67], v[152:155], v[202:205], v[64:67]
	v_mfma_f32_16x16x32_bf16 v[64:67], v[156:159], v[218:221], v[64:67]
	v_mfma_f32_16x16x32_bf16 v[80:83], v[156:159], v[198:201], v[80:83]
	v_mfma_f32_16x16x32_bf16 v[80:83], v[152:155], v[194:197], v[80:83]
	s_setprio 2
	s_barrier
	v_mfma_f32_16x16x32_bf16 v[104:107], v[152:155], v[186:189], v[104:107]
	v_mfma_f32_16x16x32_bf16 v[104:107], v[156:159], v[190:193], v[104:107]
	v_mfma_f32_16x16x32_bf16 v[128:131], v[156:159], v[182:185], v[128:131]
	v_mfma_f32_16x16x32_bf16 v[128:131], v[152:155], v[178:181], v[128:131]
	s_setprio 2
	s_add_i32 s50, s79, s61
	v_lshl_add_u64 v[206:207], v[206:207], 0, s[36:37]
	s_mov_b32 m0, s50
	ds_read_b128 v[178:181], v211 offset:49152
	ds_read_b128 v[182:185], v211 offset:50176
	ds_read_b128 v[186:189], v211 offset:51200
	ds_read_b128 v[190:193], v211 offset:52224
	ds_read_b128 v[194:197], v211 offset:53248
	ds_read_b128 v[198:201], v211 offset:54272
	ds_read_b128 v[202:205], v211 offset:55296
	ds_read_b128 v[218:221], v211 offset:56320
	global_load_lds_dwordx4 v[206:207], off
	s_add_i32 m0, s50, 0x2000
	s_add_u32 s8, s8, 0x40080
	v_lshl_add_u64 v[206:207], v[222:223], 0, s[36:37]
	s_addc_u32 s9, s9, 0
	s_add_i32 s50, s80, s61
	global_load_lds_dwordx4 v[206:207], off
	s_mov_b32 m0, s50
	v_lshl_add_u64 v[206:207], s[8:9], 0, v[162:163]
	global_load_lds_dwordx4 v[206:207], off
	s_add_i32 m0, s50, 0x2000
	v_lshl_add_u64 v[206:207], s[8:9], 0, v[166:167]
	global_load_lds_dwordx4 v[206:207], off
	s_mov_b32 m0, s68
	v_lshl_add_u64 v[206:207], v[224:225], 0, s[36:37]
	global_load_lds_dwordx4 v[206:207], off
	s_mov_b32 m0, s69
	v_lshl_add_u64 v[206:207], v[226:227], 0, s[36:37]
	global_load_lds_dwordx4 v[206:207], off
	s_waitcnt vmcnt(8) lgkmcnt(0)
	s_barrier
	s_setprio 1
	v_mfma_f32_16x16x32_bf16 v[60:63], v[96:99], v[178:181], v[60:63]
	v_mfma_f32_16x16x32_bf16 v[60:63], v[100:103], v[182:185], v[60:63]
	v_mfma_f32_16x16x32_bf16 v[44:47], v[100:103], v[190:193], v[44:47]
	v_mfma_f32_16x16x32_bf16 v[44:47], v[96:99], v[186:189], v[44:47]
	v_mfma_f32_16x16x32_bf16 v[28:31], v[96:99], v[194:197], v[28:31]
	v_mfma_f32_16x16x32_bf16 v[28:31], v[100:103], v[198:201], v[28:31]
	v_mfma_f32_16x16x32_bf16 v[12:15], v[100:103], v[218:221], v[12:15]
	v_mfma_f32_16x16x32_bf16 v[12:15], v[96:99], v[202:205], v[12:15]
	v_mfma_f32_16x16x32_bf16 v[8:11], v[120:123], v[202:205], v[8:11]
	v_mfma_f32_16x16x32_bf16 v[8:11], v[124:127], v[218:221], v[8:11]
	v_mfma_f32_16x16x32_bf16 v[24:27], v[124:127], v[198:201], v[24:27]
	v_mfma_f32_16x16x32_bf16 v[24:27], v[120:123], v[194:197], v[24:27]
	v_mfma_f32_16x16x32_bf16 v[40:43], v[120:123], v[186:189], v[40:43]
	v_mfma_f32_16x16x32_bf16 v[40:43], v[124:127], v[190:193], v[40:43]
	v_mfma_f32_16x16x32_bf16 v[56:59], v[124:127], v[182:185], v[56:59]
	v_mfma_f32_16x16x32_bf16 v[56:59], v[120:123], v[178:181], v[56:59]
	v_mfma_f32_16x16x32_bf16 v[52:55], v[144:147], v[178:181], v[52:55]
	v_mfma_f32_16x16x32_bf16 v[52:55], v[148:151], v[182:185], v[52:55]
	v_mfma_f32_16x16x32_bf16 v[36:39], v[148:151], v[190:193], v[36:39]
	v_mfma_f32_16x16x32_bf16 v[36:39], v[144:147], v[186:189], v[36:39]
	v_mfma_f32_16x16x32_bf16 v[20:23], v[144:147], v[194:197], v[20:23]
	v_mfma_f32_16x16x32_bf16 v[20:23], v[148:151], v[198:201], v[20:23]
	v_mfma_f32_16x16x32_bf16 v[4:7], v[148:151], v[218:221], v[4:7]
	v_mfma_f32_16x16x32_bf16 v[4:7], v[144:147], v[202:205], v[4:7]
	v_mfma_f32_16x16x32_bf16 v[0:3], v[152:155], v[202:205], v[0:3]
	v_mfma_f32_16x16x32_bf16 v[0:3], v[156:159], v[218:221], v[0:3]
	v_mfma_f32_16x16x32_bf16 v[16:19], v[156:159], v[198:201], v[16:19]
	v_mfma_f32_16x16x32_bf16 v[16:19], v[152:155], v[194:197], v[16:19]
	s_setprio 2
	s_barrier
	v_mfma_f32_16x16x32_bf16 v[32:35], v[152:155], v[186:189], v[32:35]
	v_mfma_f32_16x16x32_bf16 v[32:35], v[156:159], v[190:193], v[32:35]
	v_mfma_f32_16x16x32_bf16 v[48:51], v[156:159], v[182:185], v[48:51]
	v_mfma_f32_16x16x32_bf16 v[48:51], v[152:155], v[178:181], v[48:51]
	s_setprio 0
	s_add_i32 s78, s78, 2
	s_add_u32 s6, s6, 0x100
	s_addc_u32 s7, s7, 0
	s_add_u32 s56, s56, 0x100
	s_addc_u32 s57, s57, 0
	s_cmp_gt_u32 s78, 13
.LBB0_323:
	ds_read_b128 v[96:99], v209
	ds_read_b128 v[100:103], v209 offset:1024
	ds_read_b128 v[120:123], v209 offset:2048
	ds_read_b128 v[124:127], v209 offset:3072
	ds_read_b128 v[144:147], v210
	ds_read_b128 v[148:151], v210 offset:1024
	ds_read_b128 v[152:155], v210 offset:2048
	ds_read_b128 v[156:159], v210 offset:3072
	s_add_u32 s8, s6, 0xfffc0080
	s_addc_u32 s9, s7, -1
	s_cmp_eq_u32 s78, 12
	s_cselect_b32 s51, s18, s9
	s_cselect_b32 s50, s43, s8
	s_cselect_b32 s9, s45, s57
	s_cselect_b32 s8, s55, s56
	v_lshl_add_u64 v[206:207], s[6:7], 0, v[170:171]
	s_add_i32 m0, s17, 0xc000
	ds_read_b128 v[178:181], v211
	ds_read_b128 v[182:185], v211 offset:1024
	ds_read_b128 v[186:189], v211 offset:2048
	ds_read_b128 v[190:193], v211 offset:3072
	ds_read_b128 v[194:197], v211 offset:4096
	ds_read_b128 v[198:201], v211 offset:5120
	ds_read_b128 v[202:205], v211 offset:6144
	ds_read_b128 v[218:221], v211 offset:7168
	global_load_lds_dwordx4 v[206:207], off
	s_add_i32 m0, s17, 0xe000
	v_lshl_add_u64 v[206:207], s[6:7], 0, v[172:173]
	global_load_lds_dwordx4 v[206:207], off
	s_waitcnt vmcnt(8) lgkmcnt(0)
	s_barrier
	s_setprio 1
	v_mfma_f32_16x16x32_bf16 v[140:143], v[96:99], v[178:181], v[140:143]
	v_mfma_f32_16x16x32_bf16 v[140:143], v[100:103], v[182:185], v[140:143]
	v_mfma_f32_16x16x32_bf16 v[116:119], v[100:103], v[190:193], v[116:119]
	v_mfma_f32_16x16x32_bf16 v[116:119], v[96:99], v[186:189], v[116:119]
	v_mfma_f32_16x16x32_bf16 v[92:95], v[96:99], v[194:197], v[92:95]
	v_mfma_f32_16x16x32_bf16 v[92:95], v[100:103], v[198:201], v[92:95]
	v_mfma_f32_16x16x32_bf16 v[76:79], v[100:103], v[218:221], v[76:79]
	v_mfma_f32_16x16x32_bf16 v[76:79], v[96:99], v[202:205], v[76:79]
	v_mfma_f32_16x16x32_bf16 v[72:75], v[120:123], v[202:205], v[72:75]
	v_mfma_f32_16x16x32_bf16 v[72:75], v[124:127], v[218:221], v[72:75]
	v_mfma_f32_16x16x32_bf16 v[88:91], v[124:127], v[198:201], v[88:91]
	v_mfma_f32_16x16x32_bf16 v[88:91], v[120:123], v[194:197], v[88:91]
	v_mfma_f32_16x16x32_bf16 v[112:115], v[120:123], v[186:189], v[112:115]
	v_mfma_f32_16x16x32_bf16 v[112:115], v[124:127], v[190:193], v[112:115]
	v_mfma_f32_16x16x32_bf16 v[136:139], v[124:127], v[182:185], v[136:139]
	v_mfma_f32_16x16x32_bf16 v[136:139], v[120:123], v[178:181], v[136:139]
	v_mfma_f32_16x16x32_bf16 v[132:135], v[144:147], v[178:181], v[132:135]
	v_mfma_f32_16x16x32_bf16 v[132:135], v[148:151], v[182:185], v[132:135]
	v_mfma_f32_16x16x32_bf16 v[108:111], v[148:151], v[190:193], v[108:111]
	v_mfma_f32_16x16x32_bf16 v[108:111], v[144:147], v[186:189], v[108:111]
	v_mfma_f32_16x16x32_bf16 v[84:87], v[144:147], v[194:197], v[84:87]
	v_mfma_f32_16x16x32_bf16 v[84:87], v[148:151], v[198:201], v[84:87]
	v_mfma_f32_16x16x32_bf16 v[68:71], v[148:151], v[218:221], v[68:71]
	v_mfma_f32_16x16x32_bf16 v[68:71], v[144:147], v[202:205], v[68:71]
	v_mfma_f32_16x16x32_bf16 v[64:67], v[152:155], v[202:205], v[64:67]
	v_mfma_f32_16x16x32_bf16 v[64:67], v[156:159], v[218:221], v[64:67]
	v_mfma_f32_16x16x32_bf16 v[80:83], v[156:159], v[198:201], v[80:83]
	v_mfma_f32_16x16x32_bf16 v[80:83], v[152:155], v[194:197], v[80:83]
	s_setprio 2
	s_barrier
	v_mfma_f32_16x16x32_bf16 v[104:107], v[152:155], v[186:189], v[104:107]
	v_mfma_f32_16x16x32_bf16 v[104:107], v[156:159], v[190:193], v[104:107]
	v_mfma_f32_16x16x32_bf16 v[128:131], v[156:159], v[182:185], v[128:131]
	v_mfma_f32_16x16x32_bf16 v[128:131], v[152:155], v[178:181], v[128:131]
	s_setprio 2
	s_add_i32 s79, s73, s61
	v_lshl_add_u64 v[206:207], s[8:9], 0, v[162:163]
	s_mov_b32 m0, s79
	ds_read_b128 v[178:181], v211 offset:16384
	ds_read_b128 v[182:185], v211 offset:17408
	ds_read_b128 v[186:189], v211 offset:18432
	ds_read_b128 v[190:193], v211 offset:19456
	ds_read_b128 v[194:197], v211 offset:20480
	ds_read_b128 v[198:201], v211 offset:21504
	ds_read_b128 v[202:205], v211 offset:22528
	ds_read_b128 v[218:221], v211 offset:23552
	global_load_lds_dwordx4 v[206:207], off
	s_add_i32 m0, s79, 0x2000
	s_add_u32 s80, s8, 0x40000
	v_lshl_add_u64 v[222:223], s[8:9], 0, v[166:167]
	s_addc_u32 s81, s9, 0
	s_add_i32 s79, s74, s61
	global_load_lds_dwordx4 v[222:223], off
	v_lshl_add_u64 v[224:225], s[80:81], 0, v[162:163]
	s_mov_b32 m0, s79
	v_lshl_add_u64 v[226:227], s[50:51], 0, v[164:165]
	global_load_lds_dwordx4 v[224:225], off
	s_add_i32 m0, s79, 0x2000
	v_lshl_add_u64 v[224:225], s[80:81], 0, v[166:167]
	global_load_lds_dwordx4 v[224:225], off
	s_mov_b32 m0, s17
	v_lshl_add_u64 v[224:225], s[50:51], 0, v[160:161]
	global_load_lds_dwordx4 v[224:225], off
	s_mov_b32 m0, s62
	s_nop 0
	global_load_lds_dwordx4 v[226:227], off
	s_waitcnt vmcnt(8) lgkmcnt(0)
	s_barrier
	s_setprio 1
	v_mfma_f32_16x16x32_bf16 v[60:63], v[96:99], v[178:181], v[60:63]
	v_mfma_f32_16x16x32_bf16 v[60:63], v[100:103], v[182:185], v[60:63]
	v_mfma_f32_16x16x32_bf16 v[44:47], v[100:103], v[190:193], v[44:47]
	v_mfma_f32_16x16x32_bf16 v[44:47], v[96:99], v[186:189], v[44:47]
	v_mfma_f32_16x16x32_bf16 v[28:31], v[96:99], v[194:197], v[28:31]
	v_mfma_f32_16x16x32_bf16 v[28:31], v[100:103], v[198:201], v[28:31]
	v_mfma_f32_16x16x32_bf16 v[12:15], v[100:103], v[218:221], v[12:15]
	v_mfma_f32_16x16x32_bf16 v[12:15], v[96:99], v[202:205], v[12:15]
	v_mfma_f32_16x16x32_bf16 v[8:11], v[120:123], v[202:205], v[8:11]
	v_mfma_f32_16x16x32_bf16 v[8:11], v[124:127], v[218:221], v[8:11]
	v_mfma_f32_16x16x32_bf16 v[24:27], v[124:127], v[198:201], v[24:27]
	v_mfma_f32_16x16x32_bf16 v[24:27], v[120:123], v[194:197], v[24:27]
	v_mfma_f32_16x16x32_bf16 v[40:43], v[120:123], v[186:189], v[40:43]
	v_mfma_f32_16x16x32_bf16 v[40:43], v[124:127], v[190:193], v[40:43]
	v_mfma_f32_16x16x32_bf16 v[56:59], v[124:127], v[182:185], v[56:59]
	v_mfma_f32_16x16x32_bf16 v[56:59], v[120:123], v[178:181], v[56:59]
	v_mfma_f32_16x16x32_bf16 v[52:55], v[144:147], v[178:181], v[52:55]
	v_mfma_f32_16x16x32_bf16 v[52:55], v[148:151], v[182:185], v[52:55]
	v_mfma_f32_16x16x32_bf16 v[36:39], v[148:151], v[190:193], v[36:39]
	v_mfma_f32_16x16x32_bf16 v[36:39], v[144:147], v[186:189], v[36:39]
	v_mfma_f32_16x16x32_bf16 v[20:23], v[144:147], v[194:197], v[20:23]
	v_mfma_f32_16x16x32_bf16 v[20:23], v[148:151], v[198:201], v[20:23]
	v_mfma_f32_16x16x32_bf16 v[4:7], v[148:151], v[218:221], v[4:7]
	v_mfma_f32_16x16x32_bf16 v[4:7], v[144:147], v[202:205], v[4:7]
	v_mfma_f32_16x16x32_bf16 v[0:3], v[152:155], v[202:205], v[0:3]
	v_mfma_f32_16x16x32_bf16 v[0:3], v[156:159], v[218:221], v[0:3]
	v_mfma_f32_16x16x32_bf16 v[16:19], v[156:159], v[198:201], v[16:19]
	v_mfma_f32_16x16x32_bf16 v[16:19], v[152:155], v[194:197], v[16:19]
	s_setprio 2
	s_barrier
	v_mfma_f32_16x16x32_bf16 v[32:35], v[152:155], v[186:189], v[32:35]
	v_mfma_f32_16x16x32_bf16 v[32:35], v[156:159], v[190:193], v[32:35]
	v_mfma_f32_16x16x32_bf16 v[48:51], v[156:159], v[182:185], v[48:51]
	v_mfma_f32_16x16x32_bf16 v[48:51], v[152:155], v[178:181], v[48:51]
	s_setprio 0
	s_add_i32 s79, 0, 0x18000
	s_add_i32 s80, 0, 0x1c000
	v_add_u32_e32 v124, s79, v208
	v_add_u32_e32 v156, s80, v208
	ds_read_b128 v[96:99], v124
	ds_read_b128 v[100:103], v124 offset:1024
	ds_read_b128 v[120:123], v124 offset:2048
	ds_read_b128 v[124:127], v124 offset:3072
	ds_read_b128 v[144:147], v156
	ds_read_b128 v[148:151], v156 offset:1024
	ds_read_b128 v[152:155], v156 offset:2048
	ds_read_b128 v[156:159], v156 offset:3072
	s_add_u32 s50, s50, 0x40000
	s_addc_u32 s51, s51, 0
	s_mov_b32 m0, s63
	v_lshl_add_u64 v[228:229], s[50:51], 0, v[160:161]
	ds_read_b128 v[178:181], v211 offset:32768
	ds_read_b128 v[182:185], v211 offset:33792
	ds_read_b128 v[186:189], v211 offset:34816
	ds_read_b128 v[190:193], v211 offset:35840
	ds_read_b128 v[194:197], v211 offset:36864
	ds_read_b128 v[198:201], v211 offset:37888
	ds_read_b128 v[202:205], v211 offset:38912
	ds_read_b128 v[218:221], v211 offset:39936
	global_load_lds_dwordx4 v[228:229], off
	s_mov_b32 m0, s64
	v_lshl_add_u64 v[228:229], s[50:51], 0, v[164:165]
	global_load_lds_dwordx4 v[228:229], off
	s_waitcnt vmcnt(8) lgkmcnt(0)
	s_barrier
	s_setprio 1
	v_mfma_f32_16x16x32_bf16 v[140:143], v[96:99], v[178:181], v[140:143]
	v_mfma_f32_16x16x32_bf16 v[140:143], v[100:103], v[182:185], v[140:143]
	v_mfma_f32_16x16x32_bf16 v[116:119], v[100:103], v[190:193], v[116:119]
	v_mfma_f32_16x16x32_bf16 v[116:119], v[96:99], v[186:189], v[116:119]
	v_mfma_f32_16x16x32_bf16 v[92:95], v[96:99], v[194:197], v[92:95]
	v_mfma_f32_16x16x32_bf16 v[92:95], v[100:103], v[198:201], v[92:95]
	v_mfma_f32_16x16x32_bf16 v[76:79], v[100:103], v[218:221], v[76:79]
	v_mfma_f32_16x16x32_bf16 v[76:79], v[96:99], v[202:205], v[76:79]
	v_mfma_f32_16x16x32_bf16 v[72:75], v[120:123], v[202:205], v[72:75]
	v_mfma_f32_16x16x32_bf16 v[72:75], v[124:127], v[218:221], v[72:75]
	v_mfma_f32_16x16x32_bf16 v[88:91], v[124:127], v[198:201], v[88:91]
	v_mfma_f32_16x16x32_bf16 v[88:91], v[120:123], v[194:197], v[88:91]
	v_mfma_f32_16x16x32_bf16 v[112:115], v[120:123], v[186:189], v[112:115]
	v_mfma_f32_16x16x32_bf16 v[112:115], v[124:127], v[190:193], v[112:115]
	v_mfma_f32_16x16x32_bf16 v[136:139], v[124:127], v[182:185], v[136:139]
	v_mfma_f32_16x16x32_bf16 v[136:139], v[120:123], v[178:181], v[136:139]
	v_mfma_f32_16x16x32_bf16 v[132:135], v[144:147], v[178:181], v[132:135]
	v_mfma_f32_16x16x32_bf16 v[132:135], v[148:151], v[182:185], v[132:135]
	v_mfma_f32_16x16x32_bf16 v[108:111], v[148:151], v[190:193], v[108:111]
	v_mfma_f32_16x16x32_bf16 v[108:111], v[144:147], v[186:189], v[108:111]
	v_mfma_f32_16x16x32_bf16 v[84:87], v[144:147], v[194:197], v[84:87]
	v_mfma_f32_16x16x32_bf16 v[84:87], v[148:151], v[198:201], v[84:87]
	v_mfma_f32_16x16x32_bf16 v[68:71], v[148:151], v[218:221], v[68:71]
	v_mfma_f32_16x16x32_bf16 v[68:71], v[144:147], v[202:205], v[68:71]
	v_mfma_f32_16x16x32_bf16 v[64:67], v[152:155], v[202:205], v[64:67]
	v_mfma_f32_16x16x32_bf16 v[64:67], v[156:159], v[218:221], v[64:67]
	v_mfma_f32_16x16x32_bf16 v[80:83], v[156:159], v[198:201], v[80:83]
	v_mfma_f32_16x16x32_bf16 v[80:83], v[152:155], v[194:197], v[80:83]
	s_setprio 2
	s_barrier
	v_mfma_f32_16x16x32_bf16 v[104:107], v[152:155], v[186:189], v[104:107]
	v_mfma_f32_16x16x32_bf16 v[104:107], v[156:159], v[190:193], v[104:107]
	v_mfma_f32_16x16x32_bf16 v[128:131], v[156:159], v[182:185], v[128:131]
	v_mfma_f32_16x16x32_bf16 v[128:131], v[152:155], v[178:181], v[128:131]
	s_setprio 2
	s_add_i32 s50, s79, s61
	v_lshl_add_u64 v[206:207], v[206:207], 0, s[36:37]
	s_mov_b32 m0, s50
	ds_read_b128 v[178:181], v211 offset:49152
	ds_read_b128 v[182:185], v211 offset:50176
	ds_read_b128 v[186:189], v211 offset:51200
	ds_read_b128 v[190:193], v211 offset:52224
	ds_read_b128 v[194:197], v211 offset:53248
	ds_read_b128 v[198:201], v211 offset:54272
	ds_read_b128 v[202:205], v211 offset:55296
	ds_read_b128 v[218:221], v211 offset:56320
	global_load_lds_dwordx4 v[206:207], off
	s_add_i32 m0, s50, 0x2000
	s_add_u32 s8, s8, 0x40080
	v_lshl_add_u64 v[206:207], v[222:223], 0, s[36:37]
	s_addc_u32 s9, s9, 0
	s_add_i32 s50, s80, s61
	global_load_lds_dwordx4 v[206:207], off
	s_mov_b32 m0, s50
	v_lshl_add_u64 v[206:207], s[8:9], 0, v[162:163]
	global_load_lds_dwordx4 v[206:207], off
	s_add_i32 m0, s50, 0x2000
	v_lshl_add_u64 v[206:207], s[8:9], 0, v[166:167]
	global_load_lds_dwordx4 v[206:207], off
	s_mov_b32 m0, s68
	v_lshl_add_u64 v[206:207], v[224:225], 0, s[36:37]
	global_load_lds_dwordx4 v[206:207], off
	s_mov_b32 m0, s69
	v_lshl_add_u64 v[206:207], v[226:227], 0, s[36:37]
	global_load_lds_dwordx4 v[206:207], off
	s_waitcnt vmcnt(8) lgkmcnt(0)
	s_barrier
	s_setprio 1
	v_mfma_f32_16x16x32_bf16 v[60:63], v[96:99], v[178:181], v[60:63]
	v_mfma_f32_16x16x32_bf16 v[60:63], v[100:103], v[182:185], v[60:63]
	v_mfma_f32_16x16x32_bf16 v[44:47], v[100:103], v[190:193], v[44:47]
	v_mfma_f32_16x16x32_bf16 v[44:47], v[96:99], v[186:189], v[44:47]
	v_mfma_f32_16x16x32_bf16 v[28:31], v[96:99], v[194:197], v[28:31]
	v_mfma_f32_16x16x32_bf16 v[28:31], v[100:103], v[198:201], v[28:31]
	v_mfma_f32_16x16x32_bf16 v[12:15], v[100:103], v[218:221], v[12:15]
	v_mfma_f32_16x16x32_bf16 v[12:15], v[96:99], v[202:205], v[12:15]
	v_mfma_f32_16x16x32_bf16 v[8:11], v[120:123], v[202:205], v[8:11]
	v_mfma_f32_16x16x32_bf16 v[8:11], v[124:127], v[218:221], v[8:11]
	v_mfma_f32_16x16x32_bf16 v[24:27], v[124:127], v[198:201], v[24:27]
	v_mfma_f32_16x16x32_bf16 v[24:27], v[120:123], v[194:197], v[24:27]
	v_mfma_f32_16x16x32_bf16 v[40:43], v[120:123], v[186:189], v[40:43]
	v_mfma_f32_16x16x32_bf16 v[40:43], v[124:127], v[190:193], v[40:43]
	v_mfma_f32_16x16x32_bf16 v[56:59], v[124:127], v[182:185], v[56:59]
	v_mfma_f32_16x16x32_bf16 v[56:59], v[120:123], v[178:181], v[56:59]
	v_mfma_f32_16x16x32_bf16 v[52:55], v[144:147], v[178:181], v[52:55]
	v_mfma_f32_16x16x32_bf16 v[52:55], v[148:151], v[182:185], v[52:55]
	v_mfma_f32_16x16x32_bf16 v[36:39], v[148:151], v[190:193], v[36:39]
	v_mfma_f32_16x16x32_bf16 v[36:39], v[144:147], v[186:189], v[36:39]
	v_mfma_f32_16x16x32_bf16 v[20:23], v[144:147], v[194:197], v[20:23]
	v_mfma_f32_16x16x32_bf16 v[20:23], v[148:151], v[198:201], v[20:23]
	v_mfma_f32_16x16x32_bf16 v[4:7], v[148:151], v[218:221], v[4:7]
	v_mfma_f32_16x16x32_bf16 v[4:7], v[144:147], v[202:205], v[4:7]
	v_mfma_f32_16x16x32_bf16 v[0:3], v[152:155], v[202:205], v[0:3]
	v_mfma_f32_16x16x32_bf16 v[0:3], v[156:159], v[218:221], v[0:3]
	v_mfma_f32_16x16x32_bf16 v[16:19], v[156:159], v[198:201], v[16:19]
	v_mfma_f32_16x16x32_bf16 v[16:19], v[152:155], v[194:197], v[16:19]
	s_setprio 2
	s_barrier
	v_mfma_f32_16x16x32_bf16 v[32:35], v[152:155], v[186:189], v[32:35]
	v_mfma_f32_16x16x32_bf16 v[32:35], v[156:159], v[190:193], v[32:35]
	v_mfma_f32_16x16x32_bf16 v[48:51], v[156:159], v[182:185], v[48:51]
	v_mfma_f32_16x16x32_bf16 v[48:51], v[152:155], v[178:181], v[48:51]
	s_setprio 0
	s_add_i32 s78, s78, 2
	s_add_u32 s6, s6, 0x100
	s_addc_u32 s7, s7, 0
	s_add_u32 s56, s56, 0x100
	s_addc_u32 s57, s57, 0
	s_cmp_gt_u32 s78, 13
	s_cbranch_scc0 .LBB0_323

.LBB0_700:
	ds_read_b128 v[130:133], v203
	ds_read_b128 v[134:137], v203 offset:1024
	ds_read_b128 v[138:141], v203 offset:2048
	ds_read_b128 v[142:145], v203 offset:3072
	ds_read_b128 v[146:149], v195
	ds_read_b128 v[150:153], v195 offset:1024
	ds_read_b128 v[154:157], v195 offset:2048
	ds_read_b128 v[158:161], v195 offset:3072
	s_add_u32 s47, s44, 0xfff80080
	s_addc_u32 s48, s45, -1
	s_cmp_eq_u32 s46, 28
	s_cselect_b32 s49, s29, s48
	s_cselect_b32 s48, s71, s47
	s_cselect_b32 s47, s31, s84
	s_cselect_b32 s46, s72, s83
	s_mov_b32 m0, s73
	v_lshl_add_u64 v[174:175], s[44:45], 0, v[180:181]
	ds_read_b128 v[162:165], v211
	ds_read_b128 v[166:169], v211 offset:1024
	ds_read_b128 v[170:173], v211 offset:2048
	ds_read_b128 v[184:187], v211 offset:3072
	ds_read_b128 v[190:193], v211 offset:4096
	ds_read_b128 v[196:199], v211 offset:5120
	ds_read_b128 v[204:207], v211 offset:6144
	ds_read_b128 v[212:215], v211 offset:7168
	global_load_lds_dwordx4 v[174:175], off
	s_mov_b32 m0, s74
	v_lshl_add_u64 v[174:175], s[44:45], 0, v[182:183]
	global_load_lds_dwordx4 v[174:175], off
	s_waitcnt vmcnt(8) lgkmcnt(0)
	s_barrier
	s_setprio 1
	v_mfma_f32_16x16x32_bf16 v[124:127], v[130:133], v[162:165], v[124:127]
	v_mfma_f32_16x16x32_bf16 v[124:127], v[134:137], v[166:169], v[124:127]
	v_mfma_f32_16x16x32_bf16 v[108:111], v[134:137], v[184:187], v[108:111]
	v_mfma_f32_16x16x32_bf16 v[108:111], v[130:133], v[170:173], v[108:111]
	v_mfma_f32_16x16x32_bf16 v[92:95], v[130:133], v[190:193], v[92:95]
	v_mfma_f32_16x16x32_bf16 v[92:95], v[134:137], v[196:199], v[92:95]
	v_mfma_f32_16x16x32_bf16 v[76:79], v[134:137], v[212:215], v[76:79]
	v_mfma_f32_16x16x32_bf16 v[76:79], v[130:133], v[204:207], v[76:79]
	v_mfma_f32_16x16x32_bf16 v[72:75], v[138:141], v[204:207], v[72:75]
	v_mfma_f32_16x16x32_bf16 v[72:75], v[142:145], v[212:215], v[72:75]
	v_mfma_f32_16x16x32_bf16 v[88:91], v[142:145], v[196:199], v[88:91]
	v_mfma_f32_16x16x32_bf16 v[88:91], v[138:141], v[190:193], v[88:91]
	v_mfma_f32_16x16x32_bf16 v[104:107], v[138:141], v[170:173], v[104:107]
	v_mfma_f32_16x16x32_bf16 v[104:107], v[142:145], v[184:187], v[104:107]
	v_mfma_f32_16x16x32_bf16 v[120:123], v[142:145], v[166:169], v[120:123]
	v_mfma_f32_16x16x32_bf16 v[120:123], v[138:141], v[162:165], v[120:123]
	v_mfma_f32_16x16x32_bf16 v[116:119], v[146:149], v[162:165], v[116:119]
	v_mfma_f32_16x16x32_bf16 v[116:119], v[150:153], v[166:169], v[116:119]
	v_mfma_f32_16x16x32_bf16 v[100:103], v[150:153], v[184:187], v[100:103]
	v_mfma_f32_16x16x32_bf16 v[100:103], v[146:149], v[170:173], v[100:103]
	v_mfma_f32_16x16x32_bf16 v[84:87], v[146:149], v[190:193], v[84:87]
	v_mfma_f32_16x16x32_bf16 v[84:87], v[150:153], v[196:199], v[84:87]
	v_mfma_f32_16x16x32_bf16 v[68:71], v[150:153], v[212:215], v[68:71]
	v_mfma_f32_16x16x32_bf16 v[68:71], v[146:149], v[204:207], v[68:71]
	v_mfma_f32_16x16x32_bf16 v[64:67], v[154:157], v[204:207], v[64:67]
	v_mfma_f32_16x16x32_bf16 v[64:67], v[158:161], v[212:215], v[64:67]
	v_mfma_f32_16x16x32_bf16 v[80:83], v[158:161], v[196:199], v[80:83]
	v_mfma_f32_16x16x32_bf16 v[80:83], v[154:157], v[190:193], v[80:83]
	s_setprio 2
	s_barrier
	v_mfma_f32_16x16x32_bf16 v[96:99], v[154:157], v[170:173], v[96:99]
	v_mfma_f32_16x16x32_bf16 v[96:99], v[158:161], v[184:187], v[96:99]
	v_mfma_f32_16x16x32_bf16 v[112:115], v[158:161], v[166:169], v[112:115]
	v_mfma_f32_16x16x32_bf16 v[112:115], v[154:157], v[162:165], v[112:115]
	s_setprio 2
	s_mov_b32 m0, s75
	v_lshl_add_u64 v[174:175], s[46:47], 0, v[176:177]
	s_add_u32 s86, s46, 0x80000
	ds_read_b128 v[162:165], v211 offset:16384
	ds_read_b128 v[166:169], v211 offset:17408
	ds_read_b128 v[170:173], v211 offset:18432
	ds_read_b128 v[184:187], v211 offset:19456
	ds_read_b128 v[190:193], v211 offset:20480
	ds_read_b128 v[196:199], v211 offset:21504
	ds_read_b128 v[204:207], v211 offset:22528
	ds_read_b128 v[212:215], v211 offset:23552
	global_load_lds_dwordx4 v[174:175], off
	v_lshl_add_u64 v[200:201], s[46:47], 0, v[178:179]
	s_mov_b32 m0, s76
	s_addc_u32 s87, s47, 0
	global_load_lds_dwordx4 v[200:201], off
	v_lshl_add_u64 v[208:209], s[86:87], 0, v[176:177]
	s_mov_b32 m0, s77
	v_lshl_add_u64 v[216:217], s[48:49], 0, v[178:179]
	global_load_lds_dwordx4 v[208:209], off
	s_mov_b32 m0, s78
	v_lshl_add_u64 v[208:209], s[86:87], 0, v[178:179]
	global_load_lds_dwordx4 v[208:209], off
	s_mov_b32 m0, s56
	v_lshl_add_u64 v[208:209], s[48:49], 0, v[176:177]
	global_load_lds_dwordx4 v[208:209], off
	s_mov_b32 m0, s57
	s_nop 0
	global_load_lds_dwordx4 v[216:217], off
	s_waitcnt vmcnt(8) lgkmcnt(0)
	s_barrier
	s_setprio 1
	v_mfma_f32_16x16x32_bf16 v[60:63], v[130:133], v[162:165], v[60:63]
	v_mfma_f32_16x16x32_bf16 v[60:63], v[134:137], v[166:169], v[60:63]
	v_mfma_f32_16x16x32_bf16 v[44:47], v[134:137], v[184:187], v[44:47]
	v_mfma_f32_16x16x32_bf16 v[44:47], v[130:133], v[170:173], v[44:47]
	v_mfma_f32_16x16x32_bf16 v[28:31], v[130:133], v[190:193], v[28:31]
	v_mfma_f32_16x16x32_bf16 v[28:31], v[134:137], v[196:199], v[28:31]
	v_mfma_f32_16x16x32_bf16 v[12:15], v[134:137], v[212:215], v[12:15]
	v_mfma_f32_16x16x32_bf16 v[12:15], v[130:133], v[204:207], v[12:15]
	v_mfma_f32_16x16x32_bf16 v[8:11], v[138:141], v[204:207], v[8:11]
	v_mfma_f32_16x16x32_bf16 v[8:11], v[142:145], v[212:215], v[8:11]
	v_mfma_f32_16x16x32_bf16 v[24:27], v[142:145], v[196:199], v[24:27]
	v_mfma_f32_16x16x32_bf16 v[24:27], v[138:141], v[190:193], v[24:27]
	v_mfma_f32_16x16x32_bf16 v[40:43], v[138:141], v[170:173], v[40:43]
	v_mfma_f32_16x16x32_bf16 v[40:43], v[142:145], v[184:187], v[40:43]
	v_mfma_f32_16x16x32_bf16 v[56:59], v[142:145], v[166:169], v[56:59]
	v_mfma_f32_16x16x32_bf16 v[56:59], v[138:141], v[162:165], v[56:59]
	v_mfma_f32_16x16x32_bf16 v[52:55], v[146:149], v[162:165], v[52:55]
	v_mfma_f32_16x16x32_bf16 v[52:55], v[150:153], v[166:169], v[52:55]
	v_mfma_f32_16x16x32_bf16 v[36:39], v[150:153], v[184:187], v[36:39]
	v_mfma_f32_16x16x32_bf16 v[36:39], v[146:149], v[170:173], v[36:39]
	v_mfma_f32_16x16x32_bf16 v[20:23], v[146:149], v[190:193], v[20:23]
	v_mfma_f32_16x16x32_bf16 v[20:23], v[150:153], v[196:199], v[20:23]
	v_mfma_f32_16x16x32_bf16 v[4:7], v[150:153], v[212:215], v[4:7]
	v_mfma_f32_16x16x32_bf16 v[4:7], v[146:149], v[204:207], v[4:7]
	v_mfma_f32_16x16x32_bf16 v[0:3], v[154:157], v[204:207], v[0:3]
	v_mfma_f32_16x16x32_bf16 v[0:3], v[158:161], v[212:215], v[0:3]
	v_mfma_f32_16x16x32_bf16 v[16:19], v[158:161], v[196:199], v[16:19]
	v_mfma_f32_16x16x32_bf16 v[16:19], v[154:157], v[190:193], v[16:19]
	s_setprio 2
	s_barrier
	v_mfma_f32_16x16x32_bf16 v[32:35], v[154:157], v[170:173], v[32:35]
	v_mfma_f32_16x16x32_bf16 v[32:35], v[158:161], v[184:187], v[32:35]
	v_mfma_f32_16x16x32_bf16 v[48:51], v[158:161], v[166:169], v[48:51]
	v_mfma_f32_16x16x32_bf16 v[48:51], v[154:157], v[162:165], v[48:51]
	s_setprio 0
	ds_read_b128 v[130:133], v128
	ds_read_b128 v[134:137], v128 offset:1024
	ds_read_b128 v[138:141], v128 offset:2048
	ds_read_b128 v[142:145], v128 offset:3072
	ds_read_b128 v[146:149], v129
	ds_read_b128 v[150:153], v129 offset:1024
	ds_read_b128 v[154:157], v129 offset:2048
	ds_read_b128 v[158:161], v129 offset:3072
	s_add_u32 s48, s48, 0x80000
	s_addc_u32 s49, s49, 0
	s_mov_b32 m0, s58
	v_lshl_add_u64 v[218:219], s[48:49], 0, v[176:177]
	ds_read_b128 v[162:165], v211 offset:32768
	ds_read_b128 v[166:169], v211 offset:33792
	ds_read_b128 v[170:173], v211 offset:34816
	ds_read_b128 v[184:187], v211 offset:35840
	ds_read_b128 v[190:193], v211 offset:36864
	ds_read_b128 v[196:199], v211 offset:37888
	ds_read_b128 v[204:207], v211 offset:38912
	ds_read_b128 v[212:215], v211 offset:39936
	global_load_lds_dwordx4 v[218:219], off
	s_mov_b32 m0, s59
	v_lshl_add_u64 v[218:219], s[48:49], 0, v[178:179]
	global_load_lds_dwordx4 v[218:219], off
	s_waitcnt vmcnt(8) lgkmcnt(0)
	s_barrier
	s_setprio 1
	v_mfma_f32_16x16x32_bf16 v[124:127], v[130:133], v[162:165], v[124:127]
	v_mfma_f32_16x16x32_bf16 v[124:127], v[134:137], v[166:169], v[124:127]
	v_mfma_f32_16x16x32_bf16 v[108:111], v[134:137], v[184:187], v[108:111]
	v_mfma_f32_16x16x32_bf16 v[108:111], v[130:133], v[170:173], v[108:111]
	v_mfma_f32_16x16x32_bf16 v[92:95], v[130:133], v[190:193], v[92:95]
	v_mfma_f32_16x16x32_bf16 v[92:95], v[134:137], v[196:199], v[92:95]
	v_mfma_f32_16x16x32_bf16 v[76:79], v[134:137], v[212:215], v[76:79]
	v_mfma_f32_16x16x32_bf16 v[76:79], v[130:133], v[204:207], v[76:79]
	v_mfma_f32_16x16x32_bf16 v[72:75], v[138:141], v[204:207], v[72:75]
	v_mfma_f32_16x16x32_bf16 v[72:75], v[142:145], v[212:215], v[72:75]
	v_mfma_f32_16x16x32_bf16 v[88:91], v[142:145], v[196:199], v[88:91]
	v_mfma_f32_16x16x32_bf16 v[88:91], v[138:141], v[190:193], v[88:91]
	v_mfma_f32_16x16x32_bf16 v[104:107], v[138:141], v[170:173], v[104:107]
	v_mfma_f32_16x16x32_bf16 v[104:107], v[142:145], v[184:187], v[104:107]
	v_mfma_f32_16x16x32_bf16 v[120:123], v[142:145], v[166:169], v[120:123]
	v_mfma_f32_16x16x32_bf16 v[120:123], v[138:141], v[162:165], v[120:123]
	v_mfma_f32_16x16x32_bf16 v[116:119], v[146:149], v[162:165], v[116:119]
	v_mfma_f32_16x16x32_bf16 v[116:119], v[150:153], v[166:169], v[116:119]
	v_mfma_f32_16x16x32_bf16 v[100:103], v[150:153], v[184:187], v[100:103]
	v_mfma_f32_16x16x32_bf16 v[100:103], v[146:149], v[170:173], v[100:103]
	v_mfma_f32_16x16x32_bf16 v[84:87], v[146:149], v[190:193], v[84:87]
	v_mfma_f32_16x16x32_bf16 v[84:87], v[150:153], v[196:199], v[84:87]
	v_mfma_f32_16x16x32_bf16 v[68:71], v[150:153], v[212:215], v[68:71]
	v_mfma_f32_16x16x32_bf16 v[68:71], v[146:149], v[204:207], v[68:71]
	v_mfma_f32_16x16x32_bf16 v[64:67], v[154:157], v[204:207], v[64:67]
	v_mfma_f32_16x16x32_bf16 v[64:67], v[158:161], v[212:215], v[64:67]
	v_mfma_f32_16x16x32_bf16 v[80:83], v[158:161], v[196:199], v[80:83]
	v_mfma_f32_16x16x32_bf16 v[80:83], v[154:157], v[190:193], v[80:83]
	s_setprio 2
	s_barrier
	v_mfma_f32_16x16x32_bf16 v[96:99], v[154:157], v[170:173], v[96:99]
	v_mfma_f32_16x16x32_bf16 v[96:99], v[158:161], v[184:187], v[96:99]
	v_mfma_f32_16x16x32_bf16 v[112:115], v[158:161], v[166:169], v[112:115]
	v_mfma_f32_16x16x32_bf16 v[112:115], v[154:157], v[162:165], v[112:115]
	s_setprio 2
	s_mov_b32 m0, s79
	v_lshl_add_u64 v[174:175], v[174:175], 0, s[20:21]
	s_add_u32 s46, s46, 0x80080
	ds_read_b128 v[162:165], v211 offset:49152
	ds_read_b128 v[166:169], v211 offset:50176
	ds_read_b128 v[170:173], v211 offset:51200
	ds_read_b128 v[184:187], v211 offset:52224
	ds_read_b128 v[190:193], v211 offset:53248
	ds_read_b128 v[196:199], v211 offset:54272
	ds_read_b128 v[204:207], v211 offset:55296
	ds_read_b128 v[212:215], v211 offset:56320
	global_load_lds_dwordx4 v[174:175], off
	v_lshl_add_u64 v[174:175], v[200:201], 0, s[20:21]
	s_mov_b32 m0, s80
	s_addc_u32 s47, s47, 0
	global_load_lds_dwordx4 v[174:175], off
	s_mov_b32 m0, s81
	v_lshl_add_u64 v[174:175], s[46:47], 0, v[176:177]
	global_load_lds_dwordx4 v[174:175], off
	s_mov_b32 m0, s82
	v_lshl_add_u64 v[174:175], s[46:47], 0, v[178:179]
	global_load_lds_dwordx4 v[174:175], off
	s_mov_b32 m0, s61
	v_lshl_add_u64 v[174:175], v[208:209], 0, s[20:21]
	global_load_lds_dwordx4 v[174:175], off
	s_mov_b32 m0, s62
	v_lshl_add_u64 v[174:175], v[216:217], 0, s[20:21]
	global_load_lds_dwordx4 v[174:175], off
	s_waitcnt vmcnt(8) lgkmcnt(0)
	s_barrier
	s_setprio 1
	v_mfma_f32_16x16x32_bf16 v[60:63], v[130:133], v[162:165], v[60:63]
	v_mfma_f32_16x16x32_bf16 v[60:63], v[134:137], v[166:169], v[60:63]
	v_mfma_f32_16x16x32_bf16 v[44:47], v[134:137], v[184:187], v[44:47]
	v_mfma_f32_16x16x32_bf16 v[44:47], v[130:133], v[170:173], v[44:47]
	v_mfma_f32_16x16x32_bf16 v[28:31], v[130:133], v[190:193], v[28:31]
	v_mfma_f32_16x16x32_bf16 v[28:31], v[134:137], v[196:199], v[28:31]
	v_mfma_f32_16x16x32_bf16 v[12:15], v[134:137], v[212:215], v[12:15]
	v_mfma_f32_16x16x32_bf16 v[12:15], v[130:133], v[204:207], v[12:15]
	v_mfma_f32_16x16x32_bf16 v[8:11], v[138:141], v[204:207], v[8:11]
	v_mfma_f32_16x16x32_bf16 v[8:11], v[142:145], v[212:215], v[8:11]
	v_mfma_f32_16x16x32_bf16 v[24:27], v[142:145], v[196:199], v[24:27]
	v_mfma_f32_16x16x32_bf16 v[24:27], v[138:141], v[190:193], v[24:27]
	v_mfma_f32_16x16x32_bf16 v[40:43], v[138:141], v[170:173], v[40:43]
	v_mfma_f32_16x16x32_bf16 v[40:43], v[142:145], v[184:187], v[40:43]
	v_mfma_f32_16x16x32_bf16 v[56:59], v[142:145], v[166:169], v[56:59]
	v_mfma_f32_16x16x32_bf16 v[56:59], v[138:141], v[162:165], v[56:59]
	v_mfma_f32_16x16x32_bf16 v[52:55], v[146:149], v[162:165], v[52:55]
	v_mfma_f32_16x16x32_bf16 v[52:55], v[150:153], v[166:169], v[52:55]
	v_mfma_f32_16x16x32_bf16 v[36:39], v[150:153], v[184:187], v[36:39]
	v_mfma_f32_16x16x32_bf16 v[36:39], v[146:149], v[170:173], v[36:39]
	v_mfma_f32_16x16x32_bf16 v[20:23], v[146:149], v[190:193], v[20:23]
	v_mfma_f32_16x16x32_bf16 v[20:23], v[150:153], v[196:199], v[20:23]
	v_mfma_f32_16x16x32_bf16 v[4:7], v[150:153], v[212:215], v[4:7]
	v_mfma_f32_16x16x32_bf16 v[4:7], v[146:149], v[204:207], v[4:7]
	v_mfma_f32_16x16x32_bf16 v[0:3], v[154:157], v[204:207], v[0:3]
	v_mfma_f32_16x16x32_bf16 v[0:3], v[158:161], v[212:215], v[0:3]
	v_mfma_f32_16x16x32_bf16 v[16:19], v[158:161], v[196:199], v[16:19]
	v_mfma_f32_16x16x32_bf16 v[16:19], v[154:157], v[190:193], v[16:19]
	s_setprio 2
	s_barrier
	v_mfma_f32_16x16x32_bf16 v[32:35], v[154:157], v[170:173], v[32:35]
	v_mfma_f32_16x16x32_bf16 v[32:35], v[158:161], v[184:187], v[32:35]
	v_mfma_f32_16x16x32_bf16 v[48:51], v[158:161], v[166:169], v[48:51]
	v_mfma_f32_16x16x32_bf16 v[48:51], v[154:157], v[162:165], v[48:51]
	s_setprio 0
	s_add_i32 s70, s70, 1
	s_add_u32 s44, s44, 0x100
	s_addc_u32 s45, s45, 0
	s_add_u32 s83, s83, 0x100
	s_addc_u32 s84, s84, 0
	s_cmp_gt_u32 s85, 29
	s_cbranch_scc0 .LBB0_698
	s_lshl_b32 s29, s41, 12
	s_and_b32 s29, s29, 0x1000
	s_add_i32 s29, s29, 0
	v_mbcnt_lo_u32_b32 v128, -1, 0
	v_mbcnt_hi_u32_b32 v128, -1, v128
	s_add_i32 s29, s29, s63
	v_lshlrev_b32_e32 v128, 4, v128
	s_add_i32 s29, s29, 0x20400
	v_and_b32_e32 v128, 0xf0, v128
	v_add_u32_e32 v128, s29, v128
	ds_read2_b32 v[214:215], v128 offset0:3 offset1:67
	ds_read2_b32 v[206:207], v128 offset0:131 offset1:195
	v_add_u32_e32 v128, 12, v128
	ds_read2st64_b32 v[196:197], v128 offset0:8 offset1:9
	ds_read2st64_b32 v[190:191], v128 offset0:10 offset1:11
	s_and_b64 vcc, exec, s[22:23]
	s_waitcnt lgkmcnt(0)
	v_mov_b32_e32 v210, v215
	v_mov_b32_e32 v202, v207
	v_mov_b32_e32 v194, v197
	v_mov_b32_e32 v188, v191
	s_cbranch_vccz .LBB0_703
	s_barrier

.LBB0_783:
	s_ashr_i32 s23, s22, 31
	s_lshl_b64 s[26:27], s[22:23], 19
	s_add_u32 s26, s43, s26
	s_addc_u32 s27, s44, s27
	s_and_b64 s[28:29], s[4:5], exec
	s_cselect_b32 s23, s27, s37
	s_cselect_b32 s31, s26, s36
	s_ashr_i32 s25, s24, 31
	s_lshl_b64 s[28:29], s[24:25], 19
	s_add_u32 s28, s45, s28
	s_addc_u32 s29, s46, s29
	s_and_b64 s[40:41], s[4:5], exec
	s_cselect_b32 s25, s29, s39
	s_cselect_b32 s62, s28, s38
	s_add_u32 s36, s36, 0x40080
	s_addc_u32 s37, s37, 0
	s_add_u32 s63, s38, 0x100
	s_addc_u32 s64, s39, 0
	s_mov_b32 s65, -2
	ds_read_b128 v[144:147], v163
	ds_read_b128 v[148:151], v163 offset:1024
	ds_read_b128 v[152:155], v163 offset:2048
	ds_read_b128 v[156:159], v163 offset:3072
	ds_read_b128 v[168:171], v164
	ds_read_b128 v[172:175], v164 offset:1024
	ds_read_b128 v[176:179], v164 offset:2048
	ds_read_b128 v[180:183], v164 offset:3072
	s_add_u32 s38, s36, 0xfffc0080
	s_addc_u32 s39, s37, -1
	s_cmp_eq_u32 s65, 12
	s_cselect_b32 s41, s23, s39
	s_cselect_b32 s40, s31, s38
	s_cselect_b32 s39, s25, s64
	s_cselect_b32 s38, s62, s63
	v_lshl_add_u64 v[160:161], s[36:37], 0, v[136:137]
	s_add_i32 m0, s50, 0xc000
	ds_read_b128 v[184:187], v165
	ds_read_b128 v[188:191], v165 offset:1024
	ds_read_b128 v[192:195], v165 offset:2048
	ds_read_b128 v[196:199], v165 offset:3072
	ds_read_b128 v[200:203], v165 offset:4096
	ds_read_b128 v[204:207], v165 offset:5120
	ds_read_b128 v[208:211], v165 offset:6144
	ds_read_b128 v[212:215], v165 offset:7168
	global_load_lds_dwordx4 v[160:161], off
	s_add_i32 m0, s50, 0xe000
	v_lshl_add_u64 v[160:161], s[36:37], 0, v[138:139]
	global_load_lds_dwordx4 v[160:161], off
	s_waitcnt vmcnt(8) lgkmcnt(0)
	s_barrier
	s_setprio 1
	v_mfma_f32_16x16x32_bf16 v[124:127], v[144:147], v[184:187], 0
	v_mfma_f32_16x16x32_bf16 v[124:127], v[148:151], v[188:191], v[124:127]
	v_mfma_f32_16x16x32_bf16 v[108:111], v[148:151], v[196:199], 0
	v_mfma_f32_16x16x32_bf16 v[108:111], v[144:147], v[192:195], v[108:111]
	v_mfma_f32_16x16x32_bf16 v[92:95], v[144:147], v[200:203], 0
	v_mfma_f32_16x16x32_bf16 v[92:95], v[148:151], v[204:207], v[92:95]
	v_mfma_f32_16x16x32_bf16 v[76:79], v[148:151], v[212:215], 0
	v_mfma_f32_16x16x32_bf16 v[76:79], v[144:147], v[208:211], v[76:79]
	v_mfma_f32_16x16x32_bf16 v[72:75], v[152:155], v[208:211], 0
	v_mfma_f32_16x16x32_bf16 v[72:75], v[156:159], v[212:215], v[72:75]
	v_mfma_f32_16x16x32_bf16 v[88:91], v[156:159], v[204:207], 0
	v_mfma_f32_16x16x32_bf16 v[88:91], v[152:155], v[200:203], v[88:91]
	v_mfma_f32_16x16x32_bf16 v[104:107], v[152:155], v[192:195], 0
	v_mfma_f32_16x16x32_bf16 v[104:107], v[156:159], v[196:199], v[104:107]
	v_mfma_f32_16x16x32_bf16 v[120:123], v[156:159], v[188:191], 0
	v_mfma_f32_16x16x32_bf16 v[120:123], v[152:155], v[184:187], v[120:123]
	v_mfma_f32_16x16x32_bf16 v[116:119], v[168:171], v[184:187], 0
	v_mfma_f32_16x16x32_bf16 v[116:119], v[172:175], v[188:191], v[116:119]
	v_mfma_f32_16x16x32_bf16 v[100:103], v[172:175], v[196:199], 0
	v_mfma_f32_16x16x32_bf16 v[100:103], v[168:171], v[192:195], v[100:103]
	v_mfma_f32_16x16x32_bf16 v[84:87], v[168:171], v[200:203], 0
	v_mfma_f32_16x16x32_bf16 v[84:87], v[172:175], v[204:207], v[84:87]
	v_mfma_f32_16x16x32_bf16 v[68:71], v[172:175], v[212:215], 0
	v_mfma_f32_16x16x32_bf16 v[68:71], v[168:171], v[208:211], v[68:71]
	v_mfma_f32_16x16x32_bf16 v[64:67], v[176:179], v[208:211], 0
	v_mfma_f32_16x16x32_bf16 v[64:67], v[180:183], v[212:215], v[64:67]
	v_mfma_f32_16x16x32_bf16 v[80:83], v[180:183], v[204:207], 0
	v_mfma_f32_16x16x32_bf16 v[80:83], v[176:179], v[200:203], v[80:83]
	s_setprio 2
	s_barrier
	v_mfma_f32_16x16x32_bf16 v[96:99], v[176:179], v[192:195], 0
	v_mfma_f32_16x16x32_bf16 v[96:99], v[180:183], v[196:199], v[96:99]
	v_mfma_f32_16x16x32_bf16 v[112:115], v[180:183], v[188:191], 0
	v_mfma_f32_16x16x32_bf16 v[112:115], v[176:179], v[184:187], v[112:115]
	s_setprio 2
	s_add_i32 s66, s59, s47
	v_lshl_add_u64 v[160:161], s[38:39], 0, v[132:133]
	s_mov_b32 m0, s66
	ds_read_b128 v[184:187], v165 offset:16384
	ds_read_b128 v[188:191], v165 offset:17408
	ds_read_b128 v[192:195], v165 offset:18432
	ds_read_b128 v[196:199], v165 offset:19456
	ds_read_b128 v[200:203], v165 offset:20480
	ds_read_b128 v[204:207], v165 offset:21504
	ds_read_b128 v[208:211], v165 offset:22528
	ds_read_b128 v[212:215], v165 offset:23552
	global_load_lds_dwordx4 v[160:161], off
	s_add_i32 m0, s66, 0x2000
	s_add_u32 s66, s38, 0x40000
	v_lshl_add_u64 v[216:217], s[38:39], 0, v[128:129]
	s_addc_u32 s67, s39, 0
	s_add_i32 s68, s60, s47
	global_load_lds_dwordx4 v[216:217], off
	v_lshl_add_u64 v[218:219], s[66:67], 0, v[132:133]
	s_mov_b32 m0, s68
	v_lshl_add_u64 v[220:221], s[40:41], 0, v[130:131]
	global_load_lds_dwordx4 v[218:219], off
	s_add_i32 m0, s68, 0x2000
	v_lshl_add_u64 v[218:219], s[66:67], 0, v[128:129]
	global_load_lds_dwordx4 v[218:219], off
	s_mov_b32 m0, s50
	v_lshl_add_u64 v[218:219], s[40:41], 0, v[134:135]
	global_load_lds_dwordx4 v[218:219], off
	s_mov_b32 m0, s51
	s_nop 0
	global_load_lds_dwordx4 v[220:221], off
	s_waitcnt vmcnt(8) lgkmcnt(0)
	s_barrier
	s_setprio 1
	v_mfma_f32_16x16x32_bf16 v[60:63], v[144:147], v[184:187], 0
	v_mfma_f32_16x16x32_bf16 v[60:63], v[148:151], v[188:191], v[60:63]
	v_mfma_f32_16x16x32_bf16 v[44:47], v[148:151], v[196:199], 0
	v_mfma_f32_16x16x32_bf16 v[44:47], v[144:147], v[192:195], v[44:47]
	v_mfma_f32_16x16x32_bf16 v[28:31], v[144:147], v[200:203], 0
	v_mfma_f32_16x16x32_bf16 v[28:31], v[148:151], v[204:207], v[28:31]
	v_mfma_f32_16x16x32_bf16 v[12:15], v[148:151], v[212:215], 0
	v_mfma_f32_16x16x32_bf16 v[12:15], v[144:147], v[208:211], v[12:15]
	v_mfma_f32_16x16x32_bf16 v[8:11], v[152:155], v[208:211], 0
	v_mfma_f32_16x16x32_bf16 v[8:11], v[156:159], v[212:215], v[8:11]
	v_mfma_f32_16x16x32_bf16 v[24:27], v[156:159], v[204:207], 0
	v_mfma_f32_16x16x32_bf16 v[24:27], v[152:155], v[200:203], v[24:27]
	v_mfma_f32_16x16x32_bf16 v[40:43], v[152:155], v[192:195], 0
	v_mfma_f32_16x16x32_bf16 v[40:43], v[156:159], v[196:199], v[40:43]
	v_mfma_f32_16x16x32_bf16 v[56:59], v[156:159], v[188:191], 0
	v_mfma_f32_16x16x32_bf16 v[56:59], v[152:155], v[184:187], v[56:59]
	v_mfma_f32_16x16x32_bf16 v[52:55], v[168:171], v[184:187], 0
	v_mfma_f32_16x16x32_bf16 v[52:55], v[172:175], v[188:191], v[52:55]
	v_mfma_f32_16x16x32_bf16 v[36:39], v[172:175], v[196:199], 0
	v_mfma_f32_16x16x32_bf16 v[36:39], v[168:171], v[192:195], v[36:39]
	v_mfma_f32_16x16x32_bf16 v[20:23], v[168:171], v[200:203], 0
	v_mfma_f32_16x16x32_bf16 v[20:23], v[172:175], v[204:207], v[20:23]
	v_mfma_f32_16x16x32_bf16 v[4:7], v[172:175], v[212:215], 0
	v_mfma_f32_16x16x32_bf16 v[4:7], v[168:171], v[208:211], v[4:7]
	v_mfma_f32_16x16x32_bf16 v[0:3], v[176:179], v[208:211], 0
	v_mfma_f32_16x16x32_bf16 v[0:3], v[180:183], v[212:215], v[0:3]
	v_mfma_f32_16x16x32_bf16 v[16:19], v[180:183], v[204:207], 0
	v_mfma_f32_16x16x32_bf16 v[16:19], v[176:179], v[200:203], v[16:19]
	s_setprio 2
	s_barrier
	v_mfma_f32_16x16x32_bf16 v[32:35], v[176:179], v[192:195], 0
	v_mfma_f32_16x16x32_bf16 v[32:35], v[180:183], v[196:199], v[32:35]
	v_mfma_f32_16x16x32_bf16 v[48:51], v[180:183], v[188:191], 0
	v_mfma_f32_16x16x32_bf16 v[48:51], v[176:179], v[184:187], v[48:51]
	s_setprio 0
	s_add_i32 s66, 0, 0x18000
	s_add_i32 s67, 0, 0x1c000
	v_add_u32_e32 v156, s66, v162
	v_add_u32_e32 v167, s67, v162
	ds_read_b128 v[144:147], v156
	ds_read_b128 v[148:151], v156 offset:1024
	ds_read_b128 v[152:155], v156 offset:2048
	ds_read_b128 v[156:159], v156 offset:3072
	ds_read_b128 v[168:171], v167
	ds_read_b128 v[172:175], v167 offset:1024
	ds_read_b128 v[176:179], v167 offset:2048
	ds_read_b128 v[180:183], v167 offset:3072
	s_add_u32 s40, s40, 0x40000
	s_addc_u32 s41, s41, 0
	s_mov_b32 m0, s54
	v_lshl_add_u64 v[222:223], s[40:41], 0, v[134:135]
	ds_read_b128 v[184:187], v165 offset:32768
	ds_read_b128 v[188:191], v165 offset:33792
	ds_read_b128 v[192:195], v165 offset:34816
	ds_read_b128 v[196:199], v165 offset:35840
	ds_read_b128 v[200:203], v165 offset:36864
	ds_read_b128 v[204:207], v165 offset:37888
	ds_read_b128 v[208:211], v165 offset:38912
	ds_read_b128 v[212:215], v165 offset:39936
	global_load_lds_dwordx4 v[222:223], off
	s_mov_b32 m0, s55
	v_lshl_add_u64 v[222:223], s[40:41], 0, v[130:131]
	global_load_lds_dwordx4 v[222:223], off
	s_waitcnt vmcnt(8) lgkmcnt(0)
	s_barrier
	s_setprio 1
	v_mfma_f32_16x16x32_bf16 v[124:127], v[144:147], v[184:187], v[124:127]
	v_mfma_f32_16x16x32_bf16 v[124:127], v[148:151], v[188:191], v[124:127]
	v_mfma_f32_16x16x32_bf16 v[108:111], v[148:151], v[196:199], v[108:111]
	v_mfma_f32_16x16x32_bf16 v[108:111], v[144:147], v[192:195], v[108:111]
	v_mfma_f32_16x16x32_bf16 v[92:95], v[144:147], v[200:203], v[92:95]
	v_mfma_f32_16x16x32_bf16 v[92:95], v[148:151], v[204:207], v[92:95]
	v_mfma_f32_16x16x32_bf16 v[76:79], v[148:151], v[212:215], v[76:79]
	v_mfma_f32_16x16x32_bf16 v[76:79], v[144:147], v[208:211], v[76:79]
	v_mfma_f32_16x16x32_bf16 v[72:75], v[152:155], v[208:211], v[72:75]
	v_mfma_f32_16x16x32_bf16 v[72:75], v[156:159], v[212:215], v[72:75]
	v_mfma_f32_16x16x32_bf16 v[88:91], v[156:159], v[204:207], v[88:91]
	v_mfma_f32_16x16x32_bf16 v[88:91], v[152:155], v[200:203], v[88:91]
	v_mfma_f32_16x16x32_bf16 v[104:107], v[152:155], v[192:195], v[104:107]
	v_mfma_f32_16x16x32_bf16 v[104:107], v[156:159], v[196:199], v[104:107]
	v_mfma_f32_16x16x32_bf16 v[120:123], v[156:159], v[188:191], v[120:123]
	v_mfma_f32_16x16x32_bf16 v[120:123], v[152:155], v[184:187], v[120:123]
	v_mfma_f32_16x16x32_bf16 v[116:119], v[168:171], v[184:187], v[116:119]
	v_mfma_f32_16x16x32_bf16 v[116:119], v[172:175], v[188:191], v[116:119]
	v_mfma_f32_16x16x32_bf16 v[100:103], v[172:175], v[196:199], v[100:103]
	v_mfma_f32_16x16x32_bf16 v[100:103], v[168:171], v[192:195], v[100:103]
	v_mfma_f32_16x16x32_bf16 v[84:87], v[168:171], v[200:203], v[84:87]
	v_mfma_f32_16x16x32_bf16 v[84:87], v[172:175], v[204:207], v[84:87]
	v_mfma_f32_16x16x32_bf16 v[68:71], v[172:175], v[212:215], v[68:71]
	v_mfma_f32_16x16x32_bf16 v[68:71], v[168:171], v[208:211], v[68:71]
	v_mfma_f32_16x16x32_bf16 v[64:67], v[176:179], v[208:211], v[64:67]
	v_mfma_f32_16x16x32_bf16 v[64:67], v[180:183], v[212:215], v[64:67]
	v_mfma_f32_16x16x32_bf16 v[80:83], v[180:183], v[204:207], v[80:83]
	v_mfma_f32_16x16x32_bf16 v[80:83], v[176:179], v[200:203], v[80:83]
	s_setprio 2
	s_barrier
	v_mfma_f32_16x16x32_bf16 v[96:99], v[176:179], v[192:195], v[96:99]
	v_mfma_f32_16x16x32_bf16 v[96:99], v[180:183], v[196:199], v[96:99]
	v_mfma_f32_16x16x32_bf16 v[112:115], v[180:183], v[188:191], v[112:115]
	v_mfma_f32_16x16x32_bf16 v[112:115], v[176:179], v[184:187], v[112:115]
	s_setprio 2
	s_add_i32 s40, s66, s47
	v_lshl_add_u64 v[160:161], v[160:161], 0, s[16:17]
	s_mov_b32 m0, s40
	ds_read_b128 v[184:187], v165 offset:49152
	ds_read_b128 v[188:191], v165 offset:50176
	ds_read_b128 v[192:195], v165 offset:51200
	ds_read_b128 v[196:199], v165 offset:52224
	ds_read_b128 v[200:203], v165 offset:53248
	ds_read_b128 v[204:207], v165 offset:54272
	ds_read_b128 v[208:211], v165 offset:55296
	ds_read_b128 v[212:215], v165 offset:56320
	global_load_lds_dwordx4 v[160:161], off
	s_add_i32 m0, s40, 0x2000
	s_add_u32 s38, s38, 0x40080
	v_lshl_add_u64 v[160:161], v[216:217], 0, s[16:17]
	s_addc_u32 s39, s39, 0
	s_add_i32 s40, s67, s47
	global_load_lds_dwordx4 v[160:161], off
	s_mov_b32 m0, s40
	v_lshl_add_u64 v[160:161], s[38:39], 0, v[132:133]
	global_load_lds_dwordx4 v[160:161], off
	s_add_i32 m0, s40, 0x2000
	v_lshl_add_u64 v[160:161], s[38:39], 0, v[128:129]
	global_load_lds_dwordx4 v[160:161], off
	s_mov_b32 m0, s57
	v_lshl_add_u64 v[160:161], v[218:219], 0, s[16:17]
	global_load_lds_dwordx4 v[160:161], off
	s_mov_b32 m0, s58
	v_lshl_add_u64 v[160:161], v[220:221], 0, s[16:17]
	global_load_lds_dwordx4 v[160:161], off
	s_waitcnt vmcnt(8) lgkmcnt(0)
	s_barrier
	s_setprio 1
	v_mfma_f32_16x16x32_bf16 v[60:63], v[144:147], v[184:187], v[60:63]
	v_mfma_f32_16x16x32_bf16 v[60:63], v[148:151], v[188:191], v[60:63]
	v_mfma_f32_16x16x32_bf16 v[44:47], v[148:151], v[196:199], v[44:47]
	v_mfma_f32_16x16x32_bf16 v[44:47], v[144:147], v[192:195], v[44:47]
	v_mfma_f32_16x16x32_bf16 v[28:31], v[144:147], v[200:203], v[28:31]
	v_mfma_f32_16x16x32_bf16 v[28:31], v[148:151], v[204:207], v[28:31]
	v_mfma_f32_16x16x32_bf16 v[12:15], v[148:151], v[212:215], v[12:15]
	v_mfma_f32_16x16x32_bf16 v[12:15], v[144:147], v[208:211], v[12:15]
	v_mfma_f32_16x16x32_bf16 v[8:11], v[152:155], v[208:211], v[8:11]
	v_mfma_f32_16x16x32_bf16 v[8:11], v[156:159], v[212:215], v[8:11]
	v_mfma_f32_16x16x32_bf16 v[24:27], v[156:159], v[204:207], v[24:27]
	v_mfma_f32_16x16x32_bf16 v[24:27], v[152:155], v[200:203], v[24:27]
	v_mfma_f32_16x16x32_bf16 v[40:43], v[152:155], v[192:195], v[40:43]
	v_mfma_f32_16x16x32_bf16 v[40:43], v[156:159], v[196:199], v[40:43]
	v_mfma_f32_16x16x32_bf16 v[56:59], v[156:159], v[188:191], v[56:59]
	v_mfma_f32_16x16x32_bf16 v[56:59], v[152:155], v[184:187], v[56:59]
	v_mfma_f32_16x16x32_bf16 v[52:55], v[168:171], v[184:187], v[52:55]
	v_mfma_f32_16x16x32_bf16 v[52:55], v[172:175], v[188:191], v[52:55]
	v_mfma_f32_16x16x32_bf16 v[36:39], v[172:175], v[196:199], v[36:39]
	v_mfma_f32_16x16x32_bf16 v[36:39], v[168:171], v[192:195], v[36:39]
	v_mfma_f32_16x16x32_bf16 v[20:23], v[168:171], v[200:203], v[20:23]
	v_mfma_f32_16x16x32_bf16 v[20:23], v[172:175], v[204:207], v[20:23]
	v_mfma_f32_16x16x32_bf16 v[4:7], v[172:175], v[212:215], v[4:7]
	v_mfma_f32_16x16x32_bf16 v[4:7], v[168:171], v[208:211], v[4:7]
	v_mfma_f32_16x16x32_bf16 v[0:3], v[176:179], v[208:211], v[0:3]
	v_mfma_f32_16x16x32_bf16 v[0:3], v[180:183], v[212:215], v[0:3]
	v_mfma_f32_16x16x32_bf16 v[16:19], v[180:183], v[204:207], v[16:19]
	v_mfma_f32_16x16x32_bf16 v[16:19], v[176:179], v[200:203], v[16:19]
	s_setprio 2
	s_barrier
	v_mfma_f32_16x16x32_bf16 v[32:35], v[176:179], v[192:195], v[32:35]
	v_mfma_f32_16x16x32_bf16 v[32:35], v[180:183], v[196:199], v[32:35]
	v_mfma_f32_16x16x32_bf16 v[48:51], v[180:183], v[188:191], v[48:51]
	v_mfma_f32_16x16x32_bf16 v[48:51], v[176:179], v[184:187], v[48:51]
	s_setprio 0
	s_add_i32 s65, s65, 2
	s_add_u32 s36, s36, 0x100
	s_addc_u32 s37, s37, 0
	s_add_u32 s63, s63, 0x100
	s_addc_u32 s64, s64, 0
	s_cmp_gt_u32 s65, 13
.LBB0_784:
	ds_read_b128 v[144:147], v163
	ds_read_b128 v[148:151], v163 offset:1024
	ds_read_b128 v[152:155], v163 offset:2048
	ds_read_b128 v[156:159], v163 offset:3072
	ds_read_b128 v[168:171], v164
	ds_read_b128 v[172:175], v164 offset:1024
	ds_read_b128 v[176:179], v164 offset:2048
	ds_read_b128 v[180:183], v164 offset:3072
	s_add_u32 s38, s36, 0xfffc0080
	s_addc_u32 s39, s37, -1
	s_cmp_eq_u32 s65, 12
	s_cselect_b32 s41, s23, s39
	s_cselect_b32 s40, s31, s38
	s_cselect_b32 s39, s25, s64
	s_cselect_b32 s38, s62, s63
	v_lshl_add_u64 v[160:161], s[36:37], 0, v[136:137]
	s_add_i32 m0, s50, 0xc000
	ds_read_b128 v[184:187], v165
	ds_read_b128 v[188:191], v165 offset:1024
	ds_read_b128 v[192:195], v165 offset:2048
	ds_read_b128 v[196:199], v165 offset:3072
	ds_read_b128 v[200:203], v165 offset:4096
	ds_read_b128 v[204:207], v165 offset:5120
	ds_read_b128 v[208:211], v165 offset:6144
	ds_read_b128 v[212:215], v165 offset:7168
	global_load_lds_dwordx4 v[160:161], off
	s_add_i32 m0, s50, 0xe000
	v_lshl_add_u64 v[160:161], s[36:37], 0, v[138:139]
	global_load_lds_dwordx4 v[160:161], off
	s_waitcnt vmcnt(8) lgkmcnt(0)
	s_barrier
	s_setprio 1
	v_mfma_f32_16x16x32_bf16 v[124:127], v[144:147], v[184:187], v[124:127]
	v_mfma_f32_16x16x32_bf16 v[124:127], v[148:151], v[188:191], v[124:127]
	v_mfma_f32_16x16x32_bf16 v[108:111], v[148:151], v[196:199], v[108:111]
	v_mfma_f32_16x16x32_bf16 v[108:111], v[144:147], v[192:195], v[108:111]
	v_mfma_f32_16x16x32_bf16 v[92:95], v[144:147], v[200:203], v[92:95]
	v_mfma_f32_16x16x32_bf16 v[92:95], v[148:151], v[204:207], v[92:95]
	v_mfma_f32_16x16x32_bf16 v[76:79], v[148:151], v[212:215], v[76:79]
	v_mfma_f32_16x16x32_bf16 v[76:79], v[144:147], v[208:211], v[76:79]
	v_mfma_f32_16x16x32_bf16 v[72:75], v[152:155], v[208:211], v[72:75]
	v_mfma_f32_16x16x32_bf16 v[72:75], v[156:159], v[212:215], v[72:75]
	v_mfma_f32_16x16x32_bf16 v[88:91], v[156:159], v[204:207], v[88:91]
	v_mfma_f32_16x16x32_bf16 v[88:91], v[152:155], v[200:203], v[88:91]
	v_mfma_f32_16x16x32_bf16 v[104:107], v[152:155], v[192:195], v[104:107]
	v_mfma_f32_16x16x32_bf16 v[104:107], v[156:159], v[196:199], v[104:107]
	v_mfma_f32_16x16x32_bf16 v[120:123], v[156:159], v[188:191], v[120:123]
	v_mfma_f32_16x16x32_bf16 v[120:123], v[152:155], v[184:187], v[120:123]
	v_mfma_f32_16x16x32_bf16 v[116:119], v[168:171], v[184:187], v[116:119]
	v_mfma_f32_16x16x32_bf16 v[116:119], v[172:175], v[188:191], v[116:119]
	v_mfma_f32_16x16x32_bf16 v[100:103], v[172:175], v[196:199], v[100:103]
	v_mfma_f32_16x16x32_bf16 v[100:103], v[168:171], v[192:195], v[100:103]
	v_mfma_f32_16x16x32_bf16 v[84:87], v[168:171], v[200:203], v[84:87]
	v_mfma_f32_16x16x32_bf16 v[84:87], v[172:175], v[204:207], v[84:87]
	v_mfma_f32_16x16x32_bf16 v[68:71], v[172:175], v[212:215], v[68:71]
	v_mfma_f32_16x16x32_bf16 v[68:71], v[168:171], v[208:211], v[68:71]
	v_mfma_f32_16x16x32_bf16 v[64:67], v[176:179], v[208:211], v[64:67]
	v_mfma_f32_16x16x32_bf16 v[64:67], v[180:183], v[212:215], v[64:67]
	v_mfma_f32_16x16x32_bf16 v[80:83], v[180:183], v[204:207], v[80:83]
	v_mfma_f32_16x16x32_bf16 v[80:83], v[176:179], v[200:203], v[80:83]
	s_setprio 2
	s_barrier
	v_mfma_f32_16x16x32_bf16 v[96:99], v[176:179], v[192:195], v[96:99]
	v_mfma_f32_16x16x32_bf16 v[96:99], v[180:183], v[196:199], v[96:99]
	v_mfma_f32_16x16x32_bf16 v[112:115], v[180:183], v[188:191], v[112:115]
	v_mfma_f32_16x16x32_bf16 v[112:115], v[176:179], v[184:187], v[112:115]
	s_setprio 2
	s_add_i32 s66, s59, s47
	v_lshl_add_u64 v[160:161], s[38:39], 0, v[132:133]
	s_mov_b32 m0, s66
	ds_read_b128 v[184:187], v165 offset:16384
	ds_read_b128 v[188:191], v165 offset:17408
	ds_read_b128 v[192:195], v165 offset:18432
	ds_read_b128 v[196:199], v165 offset:19456
	ds_read_b128 v[200:203], v165 offset:20480
	ds_read_b128 v[204:207], v165 offset:21504
	ds_read_b128 v[208:211], v165 offset:22528
	ds_read_b128 v[212:215], v165 offset:23552
	global_load_lds_dwordx4 v[160:161], off
	s_add_i32 m0, s66, 0x2000
	s_add_u32 s66, s38, 0x40000
	v_lshl_add_u64 v[216:217], s[38:39], 0, v[128:129]
	s_addc_u32 s67, s39, 0
	s_add_i32 s68, s60, s47
	global_load_lds_dwordx4 v[216:217], off
	v_lshl_add_u64 v[218:219], s[66:67], 0, v[132:133]
	s_mov_b32 m0, s68
	v_lshl_add_u64 v[220:221], s[40:41], 0, v[130:131]
	global_load_lds_dwordx4 v[218:219], off
	s_add_i32 m0, s68, 0x2000
	v_lshl_add_u64 v[218:219], s[66:67], 0, v[128:129]
	global_load_lds_dwordx4 v[218:219], off
	s_mov_b32 m0, s50
	v_lshl_add_u64 v[218:219], s[40:41], 0, v[134:135]
	global_load_lds_dwordx4 v[218:219], off
	s_mov_b32 m0, s51
	s_nop 0
	global_load_lds_dwordx4 v[220:221], off
	s_waitcnt vmcnt(8) lgkmcnt(0)
	s_barrier
	s_setprio 1
	v_mfma_f32_16x16x32_bf16 v[60:63], v[144:147], v[184:187], v[60:63]
	v_mfma_f32_16x16x32_bf16 v[60:63], v[148:151], v[188:191], v[60:63]
	v_mfma_f32_16x16x32_bf16 v[44:47], v[148:151], v[196:199], v[44:47]
	v_mfma_f32_16x16x32_bf16 v[44:47], v[144:147], v[192:195], v[44:47]
	v_mfma_f32_16x16x32_bf16 v[28:31], v[144:147], v[200:203], v[28:31]
	v_mfma_f32_16x16x32_bf16 v[28:31], v[148:151], v[204:207], v[28:31]
	v_mfma_f32_16x16x32_bf16 v[12:15], v[148:151], v[212:215], v[12:15]
	v_mfma_f32_16x16x32_bf16 v[12:15], v[144:147], v[208:211], v[12:15]
	v_mfma_f32_16x16x32_bf16 v[8:11], v[152:155], v[208:211], v[8:11]
	v_mfma_f32_16x16x32_bf16 v[8:11], v[156:159], v[212:215], v[8:11]
	v_mfma_f32_16x16x32_bf16 v[24:27], v[156:159], v[204:207], v[24:27]
	v_mfma_f32_16x16x32_bf16 v[24:27], v[152:155], v[200:203], v[24:27]
	v_mfma_f32_16x16x32_bf16 v[40:43], v[152:155], v[192:195], v[40:43]
	v_mfma_f32_16x16x32_bf16 v[40:43], v[156:159], v[196:199], v[40:43]
	v_mfma_f32_16x16x32_bf16 v[56:59], v[156:159], v[188:191], v[56:59]
	v_mfma_f32_16x16x32_bf16 v[56:59], v[152:155], v[184:187], v[56:59]
	v_mfma_f32_16x16x32_bf16 v[52:55], v[168:171], v[184:187], v[52:55]
	v_mfma_f32_16x16x32_bf16 v[52:55], v[172:175], v[188:191], v[52:55]
	v_mfma_f32_16x16x32_bf16 v[36:39], v[172:175], v[196:199], v[36:39]
	v_mfma_f32_16x16x32_bf16 v[36:39], v[168:171], v[192:195], v[36:39]
	v_mfma_f32_16x16x32_bf16 v[20:23], v[168:171], v[200:203], v[20:23]
	v_mfma_f32_16x16x32_bf16 v[20:23], v[172:175], v[204:207], v[20:23]
	v_mfma_f32_16x16x32_bf16 v[4:7], v[172:175], v[212:215], v[4:7]
	v_mfma_f32_16x16x32_bf16 v[4:7], v[168:171], v[208:211], v[4:7]
	v_mfma_f32_16x16x32_bf16 v[0:3], v[176:179], v[208:211], v[0:3]
	v_mfma_f32_16x16x32_bf16 v[0:3], v[180:183], v[212:215], v[0:3]
	v_mfma_f32_16x16x32_bf16 v[16:19], v[180:183], v[204:207], v[16:19]
	v_mfma_f32_16x16x32_bf16 v[16:19], v[176:179], v[200:203], v[16:19]
	s_setprio 2
	s_barrier
	v_mfma_f32_16x16x32_bf16 v[32:35], v[176:179], v[192:195], v[32:35]
	v_mfma_f32_16x16x32_bf16 v[32:35], v[180:183], v[196:199], v[32:35]
	v_mfma_f32_16x16x32_bf16 v[48:51], v[180:183], v[188:191], v[48:51]
	v_mfma_f32_16x16x32_bf16 v[48:51], v[176:179], v[184:187], v[48:51]
	s_setprio 0
	s_add_i32 s66, 0, 0x18000
	s_add_i32 s67, 0, 0x1c000
	v_add_u32_e32 v156, s66, v162
	v_add_u32_e32 v167, s67, v162
	ds_read_b128 v[144:147], v156
	ds_read_b128 v[148:151], v156 offset:1024
	ds_read_b128 v[152:155], v156 offset:2048
	ds_read_b128 v[156:159], v156 offset:3072
	ds_read_b128 v[168:171], v167
	ds_read_b128 v[172:175], v167 offset:1024
	ds_read_b128 v[176:179], v167 offset:2048
	ds_read_b128 v[180:183], v167 offset:3072
	s_add_u32 s40, s40, 0x40000
	s_addc_u32 s41, s41, 0
	s_mov_b32 m0, s54
	v_lshl_add_u64 v[222:223], s[40:41], 0, v[134:135]
	ds_read_b128 v[184:187], v165 offset:32768
	ds_read_b128 v[188:191], v165 offset:33792
	ds_read_b128 v[192:195], v165 offset:34816
	ds_read_b128 v[196:199], v165 offset:35840
	ds_read_b128 v[200:203], v165 offset:36864
	ds_read_b128 v[204:207], v165 offset:37888
	ds_read_b128 v[208:211], v165 offset:38912
	ds_read_b128 v[212:215], v165 offset:39936
	global_load_lds_dwordx4 v[222:223], off
	s_mov_b32 m0, s55
	v_lshl_add_u64 v[222:223], s[40:41], 0, v[130:131]
	global_load_lds_dwordx4 v[222:223], off
	s_waitcnt vmcnt(8) lgkmcnt(0)
	s_barrier
	s_setprio 1
	v_mfma_f32_16x16x32_bf16 v[124:127], v[144:147], v[184:187], v[124:127]
	v_mfma_f32_16x16x32_bf16 v[124:127], v[148:151], v[188:191], v[124:127]
	v_mfma_f32_16x16x32_bf16 v[108:111], v[148:151], v[196:199], v[108:111]
	v_mfma_f32_16x16x32_bf16 v[108:111], v[144:147], v[192:195], v[108:111]
	v_mfma_f32_16x16x32_bf16 v[92:95], v[144:147], v[200:203], v[92:95]
	v_mfma_f32_16x16x32_bf16 v[92:95], v[148:151], v[204:207], v[92:95]
	v_mfma_f32_16x16x32_bf16 v[76:79], v[148:151], v[212:215], v[76:79]
	v_mfma_f32_16x16x32_bf16 v[76:79], v[144:147], v[208:211], v[76:79]
	v_mfma_f32_16x16x32_bf16 v[72:75], v[152:155], v[208:211], v[72:75]
	v_mfma_f32_16x16x32_bf16 v[72:75], v[156:159], v[212:215], v[72:75]
	v_mfma_f32_16x16x32_bf16 v[88:91], v[156:159], v[204:207], v[88:91]
	v_mfma_f32_16x16x32_bf16 v[88:91], v[152:155], v[200:203], v[88:91]
	v_mfma_f32_16x16x32_bf16 v[104:107], v[152:155], v[192:195], v[104:107]
	v_mfma_f32_16x16x32_bf16 v[104:107], v[156:159], v[196:199], v[104:107]
	v_mfma_f32_16x16x32_bf16 v[120:123], v[156:159], v[188:191], v[120:123]
	v_mfma_f32_16x16x32_bf16 v[120:123], v[152:155], v[184:187], v[120:123]
	v_mfma_f32_16x16x32_bf16 v[116:119], v[168:171], v[184:187], v[116:119]
	v_mfma_f32_16x16x32_bf16 v[116:119], v[172:175], v[188:191], v[116:119]
	v_mfma_f32_16x16x32_bf16 v[100:103], v[172:175], v[196:199], v[100:103]
	v_mfma_f32_16x16x32_bf16 v[100:103], v[168:171], v[192:195], v[100:103]
	v_mfma_f32_16x16x32_bf16 v[84:87], v[168:171], v[200:203], v[84:87]
	v_mfma_f32_16x16x32_bf16 v[84:87], v[172:175], v[204:207], v[84:87]
	v_mfma_f32_16x16x32_bf16 v[68:71], v[172:175], v[212:215], v[68:71]
	v_mfma_f32_16x16x32_bf16 v[68:71], v[168:171], v[208:211], v[68:71]
	v_mfma_f32_16x16x32_bf16 v[64:67], v[176:179], v[208:211], v[64:67]
	v_mfma_f32_16x16x32_bf16 v[64:67], v[180:183], v[212:215], v[64:67]
	v_mfma_f32_16x16x32_bf16 v[80:83], v[180:183], v[204:207], v[80:83]
	v_mfma_f32_16x16x32_bf16 v[80:83], v[176:179], v[200:203], v[80:83]
	s_setprio 2
	s_barrier
	v_mfma_f32_16x16x32_bf16 v[96:99], v[176:179], v[192:195], v[96:99]
	v_mfma_f32_16x16x32_bf16 v[96:99], v[180:183], v[196:199], v[96:99]
	v_mfma_f32_16x16x32_bf16 v[112:115], v[180:183], v[188:191], v[112:115]
	v_mfma_f32_16x16x32_bf16 v[112:115], v[176:179], v[184:187], v[112:115]
	s_setprio 2
	s_add_i32 s40, s66, s47
	v_lshl_add_u64 v[160:161], v[160:161], 0, s[16:17]
	s_mov_b32 m0, s40
	ds_read_b128 v[184:187], v165 offset:49152
	ds_read_b128 v[188:191], v165 offset:50176
	ds_read_b128 v[192:195], v165 offset:51200
	ds_read_b128 v[196:199], v165 offset:52224
	ds_read_b128 v[200:203], v165 offset:53248
	ds_read_b128 v[204:207], v165 offset:54272
	ds_read_b128 v[208:211], v165 offset:55296
	ds_read_b128 v[212:215], v165 offset:56320
	global_load_lds_dwordx4 v[160:161], off
	s_add_i32 m0, s40, 0x2000
	s_add_u32 s38, s38, 0x40080
	v_lshl_add_u64 v[160:161], v[216:217], 0, s[16:17]
	s_addc_u32 s39, s39, 0
	s_add_i32 s40, s67, s47
	global_load_lds_dwordx4 v[160:161], off
	s_mov_b32 m0, s40
	v_lshl_add_u64 v[160:161], s[38:39], 0, v[132:133]
	global_load_lds_dwordx4 v[160:161], off
	s_add_i32 m0, s40, 0x2000
	v_lshl_add_u64 v[160:161], s[38:39], 0, v[128:129]
	global_load_lds_dwordx4 v[160:161], off
	s_mov_b32 m0, s57
	v_lshl_add_u64 v[160:161], v[218:219], 0, s[16:17]
	global_load_lds_dwordx4 v[160:161], off
	s_mov_b32 m0, s58
	v_lshl_add_u64 v[160:161], v[220:221], 0, s[16:17]
	global_load_lds_dwordx4 v[160:161], off
	s_waitcnt vmcnt(8) lgkmcnt(0)
	s_barrier
	s_setprio 1
	v_mfma_f32_16x16x32_bf16 v[60:63], v[144:147], v[184:187], v[60:63]
	v_mfma_f32_16x16x32_bf16 v[60:63], v[148:151], v[188:191], v[60:63]
	v_mfma_f32_16x16x32_bf16 v[44:47], v[148:151], v[196:199], v[44:47]
	v_mfma_f32_16x16x32_bf16 v[44:47], v[144:147], v[192:195], v[44:47]
	v_mfma_f32_16x16x32_bf16 v[28:31], v[144:147], v[200:203], v[28:31]
	v_mfma_f32_16x16x32_bf16 v[28:31], v[148:151], v[204:207], v[28:31]
	v_mfma_f32_16x16x32_bf16 v[12:15], v[148:151], v[212:215], v[12:15]
	v_mfma_f32_16x16x32_bf16 v[12:15], v[144:147], v[208:211], v[12:15]
	v_mfma_f32_16x16x32_bf16 v[8:11], v[152:155], v[208:211], v[8:11]
	v_mfma_f32_16x16x32_bf16 v[8:11], v[156:159], v[212:215], v[8:11]
	v_mfma_f32_16x16x32_bf16 v[24:27], v[156:159], v[204:207], v[24:27]
	v_mfma_f32_16x16x32_bf16 v[24:27], v[152:155], v[200:203], v[24:27]
	v_mfma_f32_16x16x32_bf16 v[40:43], v[152:155], v[192:195], v[40:43]
	v_mfma_f32_16x16x32_bf16 v[40:43], v[156:159], v[196:199], v[40:43]
	v_mfma_f32_16x16x32_bf16 v[56:59], v[156:159], v[188:191], v[56:59]
	v_mfma_f32_16x16x32_bf16 v[56:59], v[152:155], v[184:187], v[56:59]
	v_mfma_f32_16x16x32_bf16 v[52:55], v[168:171], v[184:187], v[52:55]
	v_mfma_f32_16x16x32_bf16 v[52:55], v[172:175], v[188:191], v[52:55]
	v_mfma_f32_16x16x32_bf16 v[36:39], v[172:175], v[196:199], v[36:39]
	v_mfma_f32_16x16x32_bf16 v[36:39], v[168:171], v[192:195], v[36:39]
	v_mfma_f32_16x16x32_bf16 v[20:23], v[168:171], v[200:203], v[20:23]
	v_mfma_f32_16x16x32_bf16 v[20:23], v[172:175], v[204:207], v[20:23]
	v_mfma_f32_16x16x32_bf16 v[4:7], v[172:175], v[212:215], v[4:7]
	v_mfma_f32_16x16x32_bf16 v[4:7], v[168:171], v[208:211], v[4:7]
	v_mfma_f32_16x16x32_bf16 v[0:3], v[176:179], v[208:211], v[0:3]
	v_mfma_f32_16x16x32_bf16 v[0:3], v[180:183], v[212:215], v[0:3]
	v_mfma_f32_16x16x32_bf16 v[16:19], v[180:183], v[204:207], v[16:19]
	v_mfma_f32_16x16x32_bf16 v[16:19], v[176:179], v[200:203], v[16:19]
	s_setprio 2
	s_barrier
	v_mfma_f32_16x16x32_bf16 v[32:35], v[176:179], v[192:195], v[32:35]
	v_mfma_f32_16x16x32_bf16 v[32:35], v[180:183], v[196:199], v[32:35]
	v_mfma_f32_16x16x32_bf16 v[48:51], v[180:183], v[188:191], v[48:51]
	v_mfma_f32_16x16x32_bf16 v[48:51], v[176:179], v[184:187], v[48:51]
	s_setprio 0
	s_add_i32 s65, s65, 2
	s_add_u32 s36, s36, 0x100
	s_addc_u32 s37, s37, 0
	s_add_u32 s63, s63, 0x100
	s_addc_u32 s64, s64, 0
	s_cmp_gt_u32 s65, 13
	s_cbranch_scc0 .LBB0_784

.LBB0_865:
	s_add_u32 s62, s28, 0x100
	s_addc_u32 s63, s29, 0
	s_mov_b32 s64, -2
	ds_read_b128 v[120:123], v233
	ds_read_b128 v[124:127], v233 offset:1024
	ds_read_b128 v[136:139], v233 offset:2048
	ds_read_b128 v[140:143], v233 offset:3072
	ds_read_b128 v[144:147], v234
	ds_read_b128 v[148:151], v234 offset:1024
	ds_read_b128 v[152:155], v234 offset:2048
	ds_read_b128 v[156:159], v234 offset:3072
	s_add_u32 s28, s26, 0x100
	s_addc_u32 s29, s27, 0
	s_cmp_eq_u32 s64, 40
	s_cselect_b32 s37, s7, s29
	s_cselect_b32 s36, s6, s28
	s_cselect_b32 s31, s25, s63
	s_cselect_b32 s30, s24, s62
	v_lshl_add_u64 v[208:209], s[26:27], 0, v[192:193]
	s_add_i32 m0, s44, 0xc000
	ds_read_b128 v[160:163], v235
	ds_read_b128 v[164:167], v235 offset:1024
	ds_read_b128 v[168:171], v235 offset:2048
	ds_read_b128 v[172:175], v235 offset:3072
	ds_read_b128 v[176:179], v235 offset:4096
	ds_read_b128 v[180:183], v235 offset:5120
	ds_read_b128 v[200:203], v235 offset:6144
	ds_read_b128 v[204:207], v235 offset:7168
	global_load_lds_dwordx4 v[208:209], off
	s_add_i32 m0, s44, 0xe000
	v_lshl_add_u64 v[208:209], s[26:27], 0, v[194:195]
	global_load_lds_dwordx4 v[208:209], off
	s_waitcnt vmcnt(8) lgkmcnt(0)
	s_barrier
	s_setprio 1
	v_mfma_f32_16x16x32_bf16 v[132:135], v[120:123], v[160:163], 0
	v_mfma_f32_16x16x32_bf16 v[132:135], v[124:127], v[164:167], v[132:135]
	v_mfma_f32_16x16x32_bf16 v[108:111], v[124:127], v[172:175], 0
	v_mfma_f32_16x16x32_bf16 v[108:111], v[120:123], v[168:171], v[108:111]
	v_mfma_f32_16x16x32_bf16 v[92:95], v[120:123], v[176:179], 0
	v_mfma_f32_16x16x32_bf16 v[92:95], v[124:127], v[180:183], v[92:95]
	v_mfma_f32_16x16x32_bf16 v[76:79], v[124:127], v[204:207], 0
	v_mfma_f32_16x16x32_bf16 v[76:79], v[120:123], v[200:203], v[76:79]
	v_mfma_f32_16x16x32_bf16 v[72:75], v[136:139], v[200:203], 0
	v_mfma_f32_16x16x32_bf16 v[72:75], v[140:143], v[204:207], v[72:75]
	v_mfma_f32_16x16x32_bf16 v[88:91], v[140:143], v[180:183], 0
	v_mfma_f32_16x16x32_bf16 v[88:91], v[136:139], v[176:179], v[88:91]
	v_mfma_f32_16x16x32_bf16 v[104:107], v[136:139], v[168:171], 0
	v_mfma_f32_16x16x32_bf16 v[104:107], v[140:143], v[172:175], v[104:107]
	v_mfma_f32_16x16x32_bf16 v[128:131], v[140:143], v[164:167], 0
	v_mfma_f32_16x16x32_bf16 v[128:131], v[136:139], v[160:163], v[128:131]
	v_mfma_f32_16x16x32_bf16 v[116:119], v[144:147], v[160:163], 0
	v_mfma_f32_16x16x32_bf16 v[116:119], v[148:151], v[164:167], v[116:119]
	v_mfma_f32_16x16x32_bf16 v[100:103], v[148:151], v[172:175], 0
	v_mfma_f32_16x16x32_bf16 v[100:103], v[144:147], v[168:171], v[100:103]
	v_mfma_f32_16x16x32_bf16 v[84:87], v[144:147], v[176:179], 0
	v_mfma_f32_16x16x32_bf16 v[84:87], v[148:151], v[180:183], v[84:87]
	v_mfma_f32_16x16x32_bf16 v[68:71], v[148:151], v[204:207], 0
	v_mfma_f32_16x16x32_bf16 v[68:71], v[144:147], v[200:203], v[68:71]
	v_mfma_f32_16x16x32_bf16 v[64:67], v[152:155], v[200:203], 0
	v_mfma_f32_16x16x32_bf16 v[64:67], v[156:159], v[204:207], v[64:67]
	v_mfma_f32_16x16x32_bf16 v[80:83], v[156:159], v[180:183], 0
	v_mfma_f32_16x16x32_bf16 v[80:83], v[152:155], v[176:179], v[80:83]
	s_setprio 2
	s_barrier
	v_mfma_f32_16x16x32_bf16 v[96:99], v[152:155], v[168:171], 0
	v_mfma_f32_16x16x32_bf16 v[96:99], v[156:159], v[172:175], v[96:99]
	v_mfma_f32_16x16x32_bf16 v[112:115], v[156:159], v[164:167], 0
	v_mfma_f32_16x16x32_bf16 v[112:115], v[152:155], v[160:163], v[112:115]
	s_setprio 2
	s_add_i32 s26, s56, s43
	v_lshl_add_u64 v[208:209], s[30:31], 0, v[186:187]
	s_mov_b32 m0, s26
	ds_read_b128 v[160:163], v235 offset:16384
	ds_read_b128 v[164:167], v235 offset:17408
	ds_read_b128 v[168:171], v235 offset:18432
	ds_read_b128 v[172:175], v235 offset:19456
	ds_read_b128 v[176:179], v235 offset:20480
	ds_read_b128 v[180:183], v235 offset:21504
	ds_read_b128 v[200:203], v235 offset:22528
	ds_read_b128 v[204:207], v235 offset:23552
	global_load_lds_dwordx4 v[208:209], off
	s_add_i32 m0, s26, 0x2000
	s_add_u32 s26, s30, 0xb0000
	v_lshl_add_u64 v[210:211], s[30:31], 0, v[190:191]
	s_addc_u32 s27, s31, 0
	s_add_i32 s65, s57, s43
	global_load_lds_dwordx4 v[210:211], off
	v_lshl_add_u64 v[212:213], s[26:27], 0, v[186:187]
	s_mov_b32 m0, s65
	v_lshl_add_u64 v[214:215], s[36:37], 0, v[188:189]
	global_load_lds_dwordx4 v[212:213], off
	s_add_i32 m0, s65, 0x2000
	v_lshl_add_u64 v[212:213], s[26:27], 0, v[190:191]
	global_load_lds_dwordx4 v[212:213], off
	s_mov_b32 m0, s44
	v_lshl_add_u64 v[212:213], s[36:37], 0, v[184:185]
	global_load_lds_dwordx4 v[212:213], off
	s_mov_b32 m0, s45
	s_nop 0
	global_load_lds_dwordx4 v[214:215], off
	s_waitcnt vmcnt(8) lgkmcnt(0)
	s_barrier
	s_setprio 1
	v_mfma_f32_16x16x32_bf16 v[60:63], v[120:123], v[160:163], 0
	v_mfma_f32_16x16x32_bf16 v[60:63], v[124:127], v[164:167], v[60:63]
	v_mfma_f32_16x16x32_bf16 v[44:47], v[124:127], v[172:175], 0
	v_mfma_f32_16x16x32_bf16 v[44:47], v[120:123], v[168:171], v[44:47]
	v_mfma_f32_16x16x32_bf16 v[28:31], v[120:123], v[176:179], 0
	v_mfma_f32_16x16x32_bf16 v[28:31], v[124:127], v[180:183], v[28:31]
	v_mfma_f32_16x16x32_bf16 v[12:15], v[124:127], v[204:207], 0
	v_mfma_f32_16x16x32_bf16 v[12:15], v[120:123], v[200:203], v[12:15]
	v_mfma_f32_16x16x32_bf16 v[8:11], v[136:139], v[200:203], 0
	v_mfma_f32_16x16x32_bf16 v[8:11], v[140:143], v[204:207], v[8:11]
	v_mfma_f32_16x16x32_bf16 v[24:27], v[140:143], v[180:183], 0
	v_mfma_f32_16x16x32_bf16 v[24:27], v[136:139], v[176:179], v[24:27]
	v_mfma_f32_16x16x32_bf16 v[40:43], v[136:139], v[168:171], 0
	v_mfma_f32_16x16x32_bf16 v[40:43], v[140:143], v[172:175], v[40:43]
	v_mfma_f32_16x16x32_bf16 v[56:59], v[140:143], v[164:167], 0
	v_mfma_f32_16x16x32_bf16 v[56:59], v[136:139], v[160:163], v[56:59]
	v_mfma_f32_16x16x32_bf16 v[52:55], v[144:147], v[160:163], 0
	v_mfma_f32_16x16x32_bf16 v[52:55], v[148:151], v[164:167], v[52:55]
	v_mfma_f32_16x16x32_bf16 v[36:39], v[148:151], v[172:175], 0
	v_mfma_f32_16x16x32_bf16 v[36:39], v[144:147], v[168:171], v[36:39]
	v_mfma_f32_16x16x32_bf16 v[20:23], v[144:147], v[176:179], 0
	v_mfma_f32_16x16x32_bf16 v[20:23], v[148:151], v[180:183], v[20:23]
	v_mfma_f32_16x16x32_bf16 v[4:7], v[148:151], v[204:207], 0
	v_mfma_f32_16x16x32_bf16 v[4:7], v[144:147], v[200:203], v[4:7]
	v_mfma_f32_16x16x32_bf16 v[0:3], v[152:155], v[200:203], 0
	v_mfma_f32_16x16x32_bf16 v[0:3], v[156:159], v[204:207], v[0:3]
	v_mfma_f32_16x16x32_bf16 v[16:19], v[156:159], v[180:183], 0
	v_mfma_f32_16x16x32_bf16 v[16:19], v[152:155], v[176:179], v[16:19]
	s_setprio 2
	s_barrier
	v_mfma_f32_16x16x32_bf16 v[32:35], v[152:155], v[168:171], 0
	v_mfma_f32_16x16x32_bf16 v[32:35], v[156:159], v[172:175], v[32:35]
	v_mfma_f32_16x16x32_bf16 v[48:51], v[156:159], v[164:167], 0
	v_mfma_f32_16x16x32_bf16 v[48:51], v[152:155], v[160:163], v[48:51]
	s_setprio 0
	s_add_i32 s65, 0, 0x18000
	s_add_i32 s66, 0, 0x1c000
	v_add_u32_e32 v140, s65, v232
	v_add_u32_e32 v156, s66, v232
	ds_read_b128 v[120:123], v140
	ds_read_b128 v[124:127], v140 offset:1024
	ds_read_b128 v[136:139], v140 offset:2048
	ds_read_b128 v[140:143], v140 offset:3072
	ds_read_b128 v[144:147], v156
	ds_read_b128 v[148:151], v156 offset:1024
	ds_read_b128 v[152:155], v156 offset:2048
	ds_read_b128 v[156:159], v156 offset:3072
	s_add_u32 s26, s36, 0xb0000
	s_addc_u32 s27, s37, 0
	s_mov_b32 m0, s46
	v_lshl_add_u64 v[216:217], s[26:27], 0, v[184:185]
	ds_read_b128 v[160:163], v235 offset:32768
	ds_read_b128 v[164:167], v235 offset:33792
	ds_read_b128 v[168:171], v235 offset:34816
	ds_read_b128 v[172:175], v235 offset:35840
	ds_read_b128 v[176:179], v235 offset:36864
	ds_read_b128 v[180:183], v235 offset:37888
	ds_read_b128 v[200:203], v235 offset:38912
	ds_read_b128 v[204:207], v235 offset:39936
	global_load_lds_dwordx4 v[216:217], off
	s_mov_b32 m0, s47
	v_lshl_add_u64 v[216:217], s[26:27], 0, v[188:189]
	global_load_lds_dwordx4 v[216:217], off
	s_waitcnt vmcnt(8) lgkmcnt(0)
	s_barrier
	s_setprio 1
	v_mfma_f32_16x16x32_bf16 v[132:135], v[120:123], v[160:163], v[132:135]
	v_mfma_f32_16x16x32_bf16 v[132:135], v[124:127], v[164:167], v[132:135]
	v_mfma_f32_16x16x32_bf16 v[108:111], v[124:127], v[172:175], v[108:111]
	v_mfma_f32_16x16x32_bf16 v[108:111], v[120:123], v[168:171], v[108:111]
	v_mfma_f32_16x16x32_bf16 v[92:95], v[120:123], v[176:179], v[92:95]
	v_mfma_f32_16x16x32_bf16 v[92:95], v[124:127], v[180:183], v[92:95]
	v_mfma_f32_16x16x32_bf16 v[76:79], v[124:127], v[204:207], v[76:79]
	v_mfma_f32_16x16x32_bf16 v[76:79], v[120:123], v[200:203], v[76:79]
	v_mfma_f32_16x16x32_bf16 v[72:75], v[136:139], v[200:203], v[72:75]
	v_mfma_f32_16x16x32_bf16 v[72:75], v[140:143], v[204:207], v[72:75]
	v_mfma_f32_16x16x32_bf16 v[88:91], v[140:143], v[180:183], v[88:91]
	v_mfma_f32_16x16x32_bf16 v[88:91], v[136:139], v[176:179], v[88:91]
	v_mfma_f32_16x16x32_bf16 v[104:107], v[136:139], v[168:171], v[104:107]
	v_mfma_f32_16x16x32_bf16 v[104:107], v[140:143], v[172:175], v[104:107]
	v_mfma_f32_16x16x32_bf16 v[128:131], v[140:143], v[164:167], v[128:131]
	v_mfma_f32_16x16x32_bf16 v[128:131], v[136:139], v[160:163], v[128:131]
	v_mfma_f32_16x16x32_bf16 v[116:119], v[144:147], v[160:163], v[116:119]
	v_mfma_f32_16x16x32_bf16 v[116:119], v[148:151], v[164:167], v[116:119]
	v_mfma_f32_16x16x32_bf16 v[100:103], v[148:151], v[172:175], v[100:103]
	v_mfma_f32_16x16x32_bf16 v[100:103], v[144:147], v[168:171], v[100:103]
	v_mfma_f32_16x16x32_bf16 v[84:87], v[144:147], v[176:179], v[84:87]
	v_mfma_f32_16x16x32_bf16 v[84:87], v[148:151], v[180:183], v[84:87]
	v_mfma_f32_16x16x32_bf16 v[68:71], v[148:151], v[204:207], v[68:71]
	v_mfma_f32_16x16x32_bf16 v[68:71], v[144:147], v[200:203], v[68:71]
	v_mfma_f32_16x16x32_bf16 v[64:67], v[152:155], v[200:203], v[64:67]
	v_mfma_f32_16x16x32_bf16 v[64:67], v[156:159], v[204:207], v[64:67]
	v_mfma_f32_16x16x32_bf16 v[80:83], v[156:159], v[180:183], v[80:83]
	v_mfma_f32_16x16x32_bf16 v[80:83], v[152:155], v[176:179], v[80:83]
	s_setprio 2
	s_barrier
	v_mfma_f32_16x16x32_bf16 v[96:99], v[152:155], v[168:171], v[96:99]
	v_mfma_f32_16x16x32_bf16 v[96:99], v[156:159], v[172:175], v[96:99]
	v_mfma_f32_16x16x32_bf16 v[112:115], v[156:159], v[164:167], v[112:115]
	v_mfma_f32_16x16x32_bf16 v[112:115], v[152:155], v[160:163], v[112:115]
	s_setprio 2
	s_add_i32 s26, s65, s43
	v_lshl_add_u64 v[208:209], v[208:209], 0, s[20:21]
	s_mov_b32 m0, s26
	ds_read_b128 v[160:163], v235 offset:49152
	ds_read_b128 v[164:167], v235 offset:50176
	ds_read_b128 v[168:171], v235 offset:51200
	ds_read_b128 v[172:175], v235 offset:52224
	ds_read_b128 v[176:179], v235 offset:53248
	ds_read_b128 v[180:183], v235 offset:54272
	ds_read_b128 v[200:203], v235 offset:55296
	ds_read_b128 v[204:207], v235 offset:56320
	global_load_lds_dwordx4 v[208:209], off
	s_add_i32 m0, s26, 0x2000
	s_add_u32 s26, s30, 0xb0080
	v_lshl_add_u64 v[208:209], v[210:211], 0, s[20:21]
	s_addc_u32 s27, s31, 0
	s_add_i32 s30, s66, s43
	global_load_lds_dwordx4 v[208:209], off
	s_mov_b32 m0, s30
	v_lshl_add_u64 v[208:209], s[26:27], 0, v[186:187]
	global_load_lds_dwordx4 v[208:209], off
	s_add_i32 m0, s30, 0x2000
	v_lshl_add_u64 v[208:209], s[26:27], 0, v[190:191]
	global_load_lds_dwordx4 v[208:209], off
	s_mov_b32 m0, s49
	v_lshl_add_u64 v[208:209], v[212:213], 0, s[20:21]
	global_load_lds_dwordx4 v[208:209], off
	s_mov_b32 m0, s50
	v_lshl_add_u64 v[208:209], v[214:215], 0, s[20:21]
	global_load_lds_dwordx4 v[208:209], off
	s_waitcnt vmcnt(8) lgkmcnt(0)
	s_barrier
	s_setprio 1
	v_mfma_f32_16x16x32_bf16 v[60:63], v[120:123], v[160:163], v[60:63]
	v_mfma_f32_16x16x32_bf16 v[60:63], v[124:127], v[164:167], v[60:63]
	v_mfma_f32_16x16x32_bf16 v[44:47], v[124:127], v[172:175], v[44:47]
	v_mfma_f32_16x16x32_bf16 v[44:47], v[120:123], v[168:171], v[44:47]
	v_mfma_f32_16x16x32_bf16 v[28:31], v[120:123], v[176:179], v[28:31]
	v_mfma_f32_16x16x32_bf16 v[28:31], v[124:127], v[180:183], v[28:31]
	v_mfma_f32_16x16x32_bf16 v[12:15], v[124:127], v[204:207], v[12:15]
	v_mfma_f32_16x16x32_bf16 v[12:15], v[120:123], v[200:203], v[12:15]
	v_mfma_f32_16x16x32_bf16 v[8:11], v[136:139], v[200:203], v[8:11]
	v_mfma_f32_16x16x32_bf16 v[8:11], v[140:143], v[204:207], v[8:11]
	v_mfma_f32_16x16x32_bf16 v[24:27], v[140:143], v[180:183], v[24:27]
	v_mfma_f32_16x16x32_bf16 v[24:27], v[136:139], v[176:179], v[24:27]
	v_mfma_f32_16x16x32_bf16 v[40:43], v[136:139], v[168:171], v[40:43]
	v_mfma_f32_16x16x32_bf16 v[40:43], v[140:143], v[172:175], v[40:43]
	v_mfma_f32_16x16x32_bf16 v[56:59], v[140:143], v[164:167], v[56:59]
	v_mfma_f32_16x16x32_bf16 v[56:59], v[136:139], v[160:163], v[56:59]
	v_mfma_f32_16x16x32_bf16 v[52:55], v[144:147], v[160:163], v[52:55]
	v_mfma_f32_16x16x32_bf16 v[52:55], v[148:151], v[164:167], v[52:55]
	v_mfma_f32_16x16x32_bf16 v[36:39], v[148:151], v[172:175], v[36:39]
	v_mfma_f32_16x16x32_bf16 v[36:39], v[144:147], v[168:171], v[36:39]
	v_mfma_f32_16x16x32_bf16 v[20:23], v[144:147], v[176:179], v[20:23]
	v_mfma_f32_16x16x32_bf16 v[20:23], v[148:151], v[180:183], v[20:23]
	v_mfma_f32_16x16x32_bf16 v[4:7], v[148:151], v[204:207], v[4:7]
	v_mfma_f32_16x16x32_bf16 v[4:7], v[144:147], v[200:203], v[4:7]
	v_mfma_f32_16x16x32_bf16 v[0:3], v[152:155], v[200:203], v[0:3]
	v_mfma_f32_16x16x32_bf16 v[0:3], v[156:159], v[204:207], v[0:3]
	v_mfma_f32_16x16x32_bf16 v[16:19], v[156:159], v[180:183], v[16:19]
	v_mfma_f32_16x16x32_bf16 v[16:19], v[152:155], v[176:179], v[16:19]
	s_setprio 2
	s_barrier
	v_mfma_f32_16x16x32_bf16 v[32:35], v[152:155], v[168:171], v[32:35]
	v_mfma_f32_16x16x32_bf16 v[32:35], v[156:159], v[172:175], v[32:35]
	v_mfma_f32_16x16x32_bf16 v[48:51], v[156:159], v[164:167], v[48:51]
	v_mfma_f32_16x16x32_bf16 v[48:51], v[152:155], v[160:163], v[48:51]
	s_setprio 0
	s_add_i32 s64, s64, 2
	s_add_u32 s62, s62, 0x100
	s_addc_u32 s63, s63, 0
	s_cmp_gt_u32 s64, 41
	s_mov_b64 s[26:27], s[28:29]
.LBB0_866:
	ds_read_b128 v[120:123], v233
	ds_read_b128 v[124:127], v233 offset:1024
	ds_read_b128 v[136:139], v233 offset:2048
	ds_read_b128 v[140:143], v233 offset:3072
	ds_read_b128 v[144:147], v234
	ds_read_b128 v[148:151], v234 offset:1024
	ds_read_b128 v[152:155], v234 offset:2048
	ds_read_b128 v[156:159], v234 offset:3072
	s_add_u32 s28, s26, 0x100
	s_addc_u32 s29, s27, 0
	s_cmp_eq_u32 s64, 40
	s_cselect_b32 s37, s7, s29
	s_cselect_b32 s36, s6, s28
	s_cselect_b32 s31, s25, s63
	s_cselect_b32 s30, s24, s62
	v_lshl_add_u64 v[208:209], s[26:27], 0, v[192:193]
	s_add_i32 m0, s44, 0xc000
	ds_read_b128 v[160:163], v235
	ds_read_b128 v[164:167], v235 offset:1024
	ds_read_b128 v[168:171], v235 offset:2048
	ds_read_b128 v[172:175], v235 offset:3072
	ds_read_b128 v[176:179], v235 offset:4096
	ds_read_b128 v[180:183], v235 offset:5120
	ds_read_b128 v[200:203], v235 offset:6144
	ds_read_b128 v[204:207], v235 offset:7168
	global_load_lds_dwordx4 v[208:209], off
	s_add_i32 m0, s44, 0xe000
	v_lshl_add_u64 v[208:209], s[26:27], 0, v[194:195]
	global_load_lds_dwordx4 v[208:209], off
	s_waitcnt vmcnt(8) lgkmcnt(0)
	s_barrier
	s_setprio 1
	v_mfma_f32_16x16x32_bf16 v[132:135], v[120:123], v[160:163], v[132:135]
	v_mfma_f32_16x16x32_bf16 v[132:135], v[124:127], v[164:167], v[132:135]
	v_mfma_f32_16x16x32_bf16 v[108:111], v[124:127], v[172:175], v[108:111]
	v_mfma_f32_16x16x32_bf16 v[108:111], v[120:123], v[168:171], v[108:111]
	v_mfma_f32_16x16x32_bf16 v[92:95], v[120:123], v[176:179], v[92:95]
	v_mfma_f32_16x16x32_bf16 v[92:95], v[124:127], v[180:183], v[92:95]
	v_mfma_f32_16x16x32_bf16 v[76:79], v[124:127], v[204:207], v[76:79]
	v_mfma_f32_16x16x32_bf16 v[76:79], v[120:123], v[200:203], v[76:79]
	v_mfma_f32_16x16x32_bf16 v[72:75], v[136:139], v[200:203], v[72:75]
	v_mfma_f32_16x16x32_bf16 v[72:75], v[140:143], v[204:207], v[72:75]
	v_mfma_f32_16x16x32_bf16 v[88:91], v[140:143], v[180:183], v[88:91]
	v_mfma_f32_16x16x32_bf16 v[88:91], v[136:139], v[176:179], v[88:91]
	v_mfma_f32_16x16x32_bf16 v[104:107], v[136:139], v[168:171], v[104:107]
	v_mfma_f32_16x16x32_bf16 v[104:107], v[140:143], v[172:175], v[104:107]
	v_mfma_f32_16x16x32_bf16 v[128:131], v[140:143], v[164:167], v[128:131]
	v_mfma_f32_16x16x32_bf16 v[128:131], v[136:139], v[160:163], v[128:131]
	v_mfma_f32_16x16x32_bf16 v[116:119], v[144:147], v[160:163], v[116:119]
	v_mfma_f32_16x16x32_bf16 v[116:119], v[148:151], v[164:167], v[116:119]
	v_mfma_f32_16x16x32_bf16 v[100:103], v[148:151], v[172:175], v[100:103]
	v_mfma_f32_16x16x32_bf16 v[100:103], v[144:147], v[168:171], v[100:103]
	v_mfma_f32_16x16x32_bf16 v[84:87], v[144:147], v[176:179], v[84:87]
	v_mfma_f32_16x16x32_bf16 v[84:87], v[148:151], v[180:183], v[84:87]
	v_mfma_f32_16x16x32_bf16 v[68:71], v[148:151], v[204:207], v[68:71]
	v_mfma_f32_16x16x32_bf16 v[68:71], v[144:147], v[200:203], v[68:71]
	v_mfma_f32_16x16x32_bf16 v[64:67], v[152:155], v[200:203], v[64:67]
	v_mfma_f32_16x16x32_bf16 v[64:67], v[156:159], v[204:207], v[64:67]
	v_mfma_f32_16x16x32_bf16 v[80:83], v[156:159], v[180:183], v[80:83]
	v_mfma_f32_16x16x32_bf16 v[80:83], v[152:155], v[176:179], v[80:83]
	s_setprio 2
	s_barrier
	v_mfma_f32_16x16x32_bf16 v[96:99], v[152:155], v[168:171], v[96:99]
	v_mfma_f32_16x16x32_bf16 v[96:99], v[156:159], v[172:175], v[96:99]
	v_mfma_f32_16x16x32_bf16 v[112:115], v[156:159], v[164:167], v[112:115]
	v_mfma_f32_16x16x32_bf16 v[112:115], v[152:155], v[160:163], v[112:115]
	s_setprio 2
	s_add_i32 s26, s56, s43
	v_lshl_add_u64 v[208:209], s[30:31], 0, v[186:187]
	s_mov_b32 m0, s26
	ds_read_b128 v[160:163], v235 offset:16384
	ds_read_b128 v[164:167], v235 offset:17408
	ds_read_b128 v[168:171], v235 offset:18432
	ds_read_b128 v[172:175], v235 offset:19456
	ds_read_b128 v[176:179], v235 offset:20480
	ds_read_b128 v[180:183], v235 offset:21504
	ds_read_b128 v[200:203], v235 offset:22528
	ds_read_b128 v[204:207], v235 offset:23552
	global_load_lds_dwordx4 v[208:209], off
	s_add_i32 m0, s26, 0x2000
	s_add_u32 s26, s30, 0xb0000
	v_lshl_add_u64 v[210:211], s[30:31], 0, v[190:191]
	s_addc_u32 s27, s31, 0
	s_add_i32 s65, s57, s43
	global_load_lds_dwordx4 v[210:211], off
	v_lshl_add_u64 v[212:213], s[26:27], 0, v[186:187]
	s_mov_b32 m0, s65
	v_lshl_add_u64 v[214:215], s[36:37], 0, v[188:189]
	global_load_lds_dwordx4 v[212:213], off
	s_add_i32 m0, s65, 0x2000
	v_lshl_add_u64 v[212:213], s[26:27], 0, v[190:191]
	global_load_lds_dwordx4 v[212:213], off
	s_mov_b32 m0, s44
	v_lshl_add_u64 v[212:213], s[36:37], 0, v[184:185]
	global_load_lds_dwordx4 v[212:213], off
	s_mov_b32 m0, s45
	s_nop 0
	global_load_lds_dwordx4 v[214:215], off
	s_waitcnt vmcnt(8) lgkmcnt(0)
	s_barrier
	s_setprio 1
	v_mfma_f32_16x16x32_bf16 v[60:63], v[120:123], v[160:163], v[60:63]
	v_mfma_f32_16x16x32_bf16 v[60:63], v[124:127], v[164:167], v[60:63]
	v_mfma_f32_16x16x32_bf16 v[44:47], v[124:127], v[172:175], v[44:47]
	v_mfma_f32_16x16x32_bf16 v[44:47], v[120:123], v[168:171], v[44:47]
	v_mfma_f32_16x16x32_bf16 v[28:31], v[120:123], v[176:179], v[28:31]
	v_mfma_f32_16x16x32_bf16 v[28:31], v[124:127], v[180:183], v[28:31]
	v_mfma_f32_16x16x32_bf16 v[12:15], v[124:127], v[204:207], v[12:15]
	v_mfma_f32_16x16x32_bf16 v[12:15], v[120:123], v[200:203], v[12:15]
	v_mfma_f32_16x16x32_bf16 v[8:11], v[136:139], v[200:203], v[8:11]
	v_mfma_f32_16x16x32_bf16 v[8:11], v[140:143], v[204:207], v[8:11]
	v_mfma_f32_16x16x32_bf16 v[24:27], v[140:143], v[180:183], v[24:27]
	v_mfma_f32_16x16x32_bf16 v[24:27], v[136:139], v[176:179], v[24:27]
	v_mfma_f32_16x16x32_bf16 v[40:43], v[136:139], v[168:171], v[40:43]
	v_mfma_f32_16x16x32_bf16 v[40:43], v[140:143], v[172:175], v[40:43]
	v_mfma_f32_16x16x32_bf16 v[56:59], v[140:143], v[164:167], v[56:59]
	v_mfma_f32_16x16x32_bf16 v[56:59], v[136:139], v[160:163], v[56:59]
	v_mfma_f32_16x16x32_bf16 v[52:55], v[144:147], v[160:163], v[52:55]
	v_mfma_f32_16x16x32_bf16 v[52:55], v[148:151], v[164:167], v[52:55]
	v_mfma_f32_16x16x32_bf16 v[36:39], v[148:151], v[172:175], v[36:39]
	v_mfma_f32_16x16x32_bf16 v[36:39], v[144:147], v[168:171], v[36:39]
	v_mfma_f32_16x16x32_bf16 v[20:23], v[144:147], v[176:179], v[20:23]
	v_mfma_f32_16x16x32_bf16 v[20:23], v[148:151], v[180:183], v[20:23]
	v_mfma_f32_16x16x32_bf16 v[4:7], v[148:151], v[204:207], v[4:7]
	v_mfma_f32_16x16x32_bf16 v[4:7], v[144:147], v[200:203], v[4:7]
	v_mfma_f32_16x16x32_bf16 v[0:3], v[152:155], v[200:203], v[0:3]
	v_mfma_f32_16x16x32_bf16 v[0:3], v[156:159], v[204:207], v[0:3]
	v_mfma_f32_16x16x32_bf16 v[16:19], v[156:159], v[180:183], v[16:19]
	v_mfma_f32_16x16x32_bf16 v[16:19], v[152:155], v[176:179], v[16:19]
	s_setprio 2
	s_barrier
	v_mfma_f32_16x16x32_bf16 v[32:35], v[152:155], v[168:171], v[32:35]
	v_mfma_f32_16x16x32_bf16 v[32:35], v[156:159], v[172:175], v[32:35]
	v_mfma_f32_16x16x32_bf16 v[48:51], v[156:159], v[164:167], v[48:51]
	v_mfma_f32_16x16x32_bf16 v[48:51], v[152:155], v[160:163], v[48:51]
	s_setprio 0
	s_add_i32 s65, 0, 0x18000
	s_add_i32 s66, 0, 0x1c000
	v_add_u32_e32 v140, s65, v232
	v_add_u32_e32 v156, s66, v232
	ds_read_b128 v[120:123], v140
	ds_read_b128 v[124:127], v140 offset:1024
	ds_read_b128 v[136:139], v140 offset:2048
	ds_read_b128 v[140:143], v140 offset:3072
	ds_read_b128 v[144:147], v156
	ds_read_b128 v[148:151], v156 offset:1024
	ds_read_b128 v[152:155], v156 offset:2048
	ds_read_b128 v[156:159], v156 offset:3072
	s_add_u32 s26, s36, 0xb0000
	s_addc_u32 s27, s37, 0
	s_mov_b32 m0, s46
	v_lshl_add_u64 v[216:217], s[26:27], 0, v[184:185]
	ds_read_b128 v[160:163], v235 offset:32768
	ds_read_b128 v[164:167], v235 offset:33792
	ds_read_b128 v[168:171], v235 offset:34816
	ds_read_b128 v[172:175], v235 offset:35840
	ds_read_b128 v[176:179], v235 offset:36864
	ds_read_b128 v[180:183], v235 offset:37888
	ds_read_b128 v[200:203], v235 offset:38912
	ds_read_b128 v[204:207], v235 offset:39936
	global_load_lds_dwordx4 v[216:217], off
	s_mov_b32 m0, s47
	v_lshl_add_u64 v[216:217], s[26:27], 0, v[188:189]
	global_load_lds_dwordx4 v[216:217], off
	s_waitcnt vmcnt(8) lgkmcnt(0)
	s_barrier
	s_setprio 1
	v_mfma_f32_16x16x32_bf16 v[132:135], v[120:123], v[160:163], v[132:135]
	v_mfma_f32_16x16x32_bf16 v[132:135], v[124:127], v[164:167], v[132:135]
	v_mfma_f32_16x16x32_bf16 v[108:111], v[124:127], v[172:175], v[108:111]
	v_mfma_f32_16x16x32_bf16 v[108:111], v[120:123], v[168:171], v[108:111]
	v_mfma_f32_16x16x32_bf16 v[92:95], v[120:123], v[176:179], v[92:95]
	v_mfma_f32_16x16x32_bf16 v[92:95], v[124:127], v[180:183], v[92:95]
	v_mfma_f32_16x16x32_bf16 v[76:79], v[124:127], v[204:207], v[76:79]
	v_mfma_f32_16x16x32_bf16 v[76:79], v[120:123], v[200:203], v[76:79]
	v_mfma_f32_16x16x32_bf16 v[72:75], v[136:139], v[200:203], v[72:75]
	v_mfma_f32_16x16x32_bf16 v[72:75], v[140:143], v[204:207], v[72:75]
	v_mfma_f32_16x16x32_bf16 v[88:91], v[140:143], v[180:183], v[88:91]
	v_mfma_f32_16x16x32_bf16 v[88:91], v[136:139], v[176:179], v[88:91]
	v_mfma_f32_16x16x32_bf16 v[104:107], v[136:139], v[168:171], v[104:107]
	v_mfma_f32_16x16x32_bf16 v[104:107], v[140:143], v[172:175], v[104:107]
	v_mfma_f32_16x16x32_bf16 v[128:131], v[140:143], v[164:167], v[128:131]
	v_mfma_f32_16x16x32_bf16 v[128:131], v[136:139], v[160:163], v[128:131]
	v_mfma_f32_16x16x32_bf16 v[116:119], v[144:147], v[160:163], v[116:119]
	v_mfma_f32_16x16x32_bf16 v[116:119], v[148:151], v[164:167], v[116:119]
	v_mfma_f32_16x16x32_bf16 v[100:103], v[148:151], v[172:175], v[100:103]
	v_mfma_f32_16x16x32_bf16 v[100:103], v[144:147], v[168:171], v[100:103]
	v_mfma_f32_16x16x32_bf16 v[84:87], v[144:147], v[176:179], v[84:87]
	v_mfma_f32_16x16x32_bf16 v[84:87], v[148:151], v[180:183], v[84:87]
	v_mfma_f32_16x16x32_bf16 v[68:71], v[148:151], v[204:207], v[68:71]
	v_mfma_f32_16x16x32_bf16 v[68:71], v[144:147], v[200:203], v[68:71]
	v_mfma_f32_16x16x32_bf16 v[64:67], v[152:155], v[200:203], v[64:67]
	v_mfma_f32_16x16x32_bf16 v[64:67], v[156:159], v[204:207], v[64:67]
	v_mfma_f32_16x16x32_bf16 v[80:83], v[156:159], v[180:183], v[80:83]
	v_mfma_f32_16x16x32_bf16 v[80:83], v[152:155], v[176:179], v[80:83]
	s_setprio 2
	s_barrier
	v_mfma_f32_16x16x32_bf16 v[96:99], v[152:155], v[168:171], v[96:99]
	v_mfma_f32_16x16x32_bf16 v[96:99], v[156:159], v[172:175], v[96:99]
	v_mfma_f32_16x16x32_bf16 v[112:115], v[156:159], v[164:167], v[112:115]
	v_mfma_f32_16x16x32_bf16 v[112:115], v[152:155], v[160:163], v[112:115]
	s_setprio 2
	s_add_i32 s26, s65, s43
	v_lshl_add_u64 v[208:209], v[208:209], 0, s[20:21]
	s_mov_b32 m0, s26
	ds_read_b128 v[160:163], v235 offset:49152
	ds_read_b128 v[164:167], v235 offset:50176
	ds_read_b128 v[168:171], v235 offset:51200
	ds_read_b128 v[172:175], v235 offset:52224
	ds_read_b128 v[176:179], v235 offset:53248
	ds_read_b128 v[180:183], v235 offset:54272
	ds_read_b128 v[200:203], v235 offset:55296
	ds_read_b128 v[204:207], v235 offset:56320
	global_load_lds_dwordx4 v[208:209], off
	s_add_i32 m0, s26, 0x2000
	s_add_u32 s26, s30, 0xb0080
	v_lshl_add_u64 v[208:209], v[210:211], 0, s[20:21]
	s_addc_u32 s27, s31, 0
	s_add_i32 s30, s66, s43
	global_load_lds_dwordx4 v[208:209], off
	s_mov_b32 m0, s30
	v_lshl_add_u64 v[208:209], s[26:27], 0, v[186:187]
	global_load_lds_dwordx4 v[208:209], off
	s_add_i32 m0, s30, 0x2000
	v_lshl_add_u64 v[208:209], s[26:27], 0, v[190:191]
	global_load_lds_dwordx4 v[208:209], off
	s_mov_b32 m0, s49
	v_lshl_add_u64 v[208:209], v[212:213], 0, s[20:21]
	global_load_lds_dwordx4 v[208:209], off
	s_mov_b32 m0, s50
	v_lshl_add_u64 v[208:209], v[214:215], 0, s[20:21]
	global_load_lds_dwordx4 v[208:209], off
	s_waitcnt vmcnt(8) lgkmcnt(0)
	s_barrier
	s_setprio 1
	v_mfma_f32_16x16x32_bf16 v[60:63], v[120:123], v[160:163], v[60:63]
	v_mfma_f32_16x16x32_bf16 v[60:63], v[124:127], v[164:167], v[60:63]
	v_mfma_f32_16x16x32_bf16 v[44:47], v[124:127], v[172:175], v[44:47]
	v_mfma_f32_16x16x32_bf16 v[44:47], v[120:123], v[168:171], v[44:47]
	v_mfma_f32_16x16x32_bf16 v[28:31], v[120:123], v[176:179], v[28:31]
	v_mfma_f32_16x16x32_bf16 v[28:31], v[124:127], v[180:183], v[28:31]
	v_mfma_f32_16x16x32_bf16 v[12:15], v[124:127], v[204:207], v[12:15]
	v_mfma_f32_16x16x32_bf16 v[12:15], v[120:123], v[200:203], v[12:15]
	v_mfma_f32_16x16x32_bf16 v[8:11], v[136:139], v[200:203], v[8:11]
	v_mfma_f32_16x16x32_bf16 v[8:11], v[140:143], v[204:207], v[8:11]
	v_mfma_f32_16x16x32_bf16 v[24:27], v[140:143], v[180:183], v[24:27]
	v_mfma_f32_16x16x32_bf16 v[24:27], v[136:139], v[176:179], v[24:27]
	v_mfma_f32_16x16x32_bf16 v[40:43], v[136:139], v[168:171], v[40:43]
	v_mfma_f32_16x16x32_bf16 v[40:43], v[140:143], v[172:175], v[40:43]
	v_mfma_f32_16x16x32_bf16 v[56:59], v[140:143], v[164:167], v[56:59]
	v_mfma_f32_16x16x32_bf16 v[56:59], v[136:139], v[160:163], v[56:59]
	v_mfma_f32_16x16x32_bf16 v[52:55], v[144:147], v[160:163], v[52:55]
	v_mfma_f32_16x16x32_bf16 v[52:55], v[148:151], v[164:167], v[52:55]
	v_mfma_f32_16x16x32_bf16 v[36:39], v[148:151], v[172:175], v[36:39]
	v_mfma_f32_16x16x32_bf16 v[36:39], v[144:147], v[168:171], v[36:39]
	v_mfma_f32_16x16x32_bf16 v[20:23], v[144:147], v[176:179], v[20:23]
	v_mfma_f32_16x16x32_bf16 v[20:23], v[148:151], v[180:183], v[20:23]
	v_mfma_f32_16x16x32_bf16 v[4:7], v[148:151], v[204:207], v[4:7]
	v_mfma_f32_16x16x32_bf16 v[4:7], v[144:147], v[200:203], v[4:7]
	v_mfma_f32_16x16x32_bf16 v[0:3], v[152:155], v[200:203], v[0:3]
	v_mfma_f32_16x16x32_bf16 v[0:3], v[156:159], v[204:207], v[0:3]
	v_mfma_f32_16x16x32_bf16 v[16:19], v[156:159], v[180:183], v[16:19]
	v_mfma_f32_16x16x32_bf16 v[16:19], v[152:155], v[176:179], v[16:19]
	s_setprio 2
	s_barrier
	v_mfma_f32_16x16x32_bf16 v[32:35], v[152:155], v[168:171], v[32:35]
	v_mfma_f32_16x16x32_bf16 v[32:35], v[156:159], v[172:175], v[32:35]
	v_mfma_f32_16x16x32_bf16 v[48:51], v[156:159], v[164:167], v[48:51]
	v_mfma_f32_16x16x32_bf16 v[48:51], v[152:155], v[160:163], v[48:51]
	s_setprio 0
	s_add_i32 s64, s64, 2
	s_add_u32 s62, s62, 0x100
	s_addc_u32 s63, s63, 0
	s_cmp_gt_u32 s64, 41
	s_mov_b64 s[26:27], s[28:29]
	s_cbranch_scc0 .LBB0_866

.LBB0_951:
	s_ashr_i32 s27, s26, 31
	s_lshl_b64 s[30:31], s[26:27], 19
	s_add_u32 s30, s47, s30
	s_addc_u32 s31, s48, s31
	s_and_b64 s[36:37], s[4:5], exec
	s_cselect_b32 s27, s31, s7
	s_cselect_b32 s39, s30, s6
	s_ashr_i32 s29, s28, 31
	s_lshl_b64 s[36:37], s[28:29], 19
	s_add_u32 s36, s49, s36
	s_addc_u32 s37, s50, s37
	s_and_b64 s[44:45], s[4:5], exec
	s_cselect_b32 s29, s37, s41
	s_cselect_b32 s43, s36, s40
	s_add_u32 s6, s6, 0x40080
	s_addc_u32 s7, s7, 0
	s_add_u32 s71, s40, 0x100
	s_addc_u32 s72, s41, 0
	s_mov_b32 s73, -2
	ds_read_b128 v[144:147], v179
	ds_read_b128 v[148:151], v179 offset:1024
	ds_read_b128 v[152:155], v179 offset:2048
	ds_read_b128 v[156:159], v179 offset:3072
	ds_read_b128 v[160:163], v180
	ds_read_b128 v[164:167], v180 offset:1024
	ds_read_b128 v[168:171], v180 offset:2048
	ds_read_b128 v[172:175], v180 offset:3072
	s_add_u32 s40, s6, 0xfffc0080
	s_addc_u32 s41, s7, -1
	s_cmp_eq_u32 s73, 12
	s_cselect_b32 s45, s27, s41
	s_cselect_b32 s44, s39, s40
	s_cselect_b32 s41, s29, s72
	s_cselect_b32 s40, s43, s71
	v_lshl_add_u64 v[176:177], s[6:7], 0, v[136:137]
	s_add_i32 m0, s54, 0xc000
	ds_read_b128 v[184:187], v181
	ds_read_b128 v[188:191], v181 offset:1024
	ds_read_b128 v[192:195], v181 offset:2048
	ds_read_b128 v[196:199], v181 offset:3072
	ds_read_b128 v[200:203], v181 offset:4096
	ds_read_b128 v[204:207], v181 offset:5120
	ds_read_b128 v[208:211], v181 offset:6144
	ds_read_b128 v[212:215], v181 offset:7168
	global_load_lds_dwordx4 v[176:177], off
	s_add_i32 m0, s54, 0xe000
	v_lshl_add_u64 v[176:177], s[6:7], 0, v[138:139]
	global_load_lds_dwordx4 v[176:177], off
	s_waitcnt vmcnt(8) lgkmcnt(0)
	s_barrier
	s_setprio 1
	v_mfma_f32_16x16x32_bf16 v[124:127], v[144:147], v[184:187], 0
	v_mfma_f32_16x16x32_bf16 v[124:127], v[148:151], v[188:191], v[124:127]
	v_mfma_f32_16x16x32_bf16 v[108:111], v[148:151], v[196:199], 0
	v_mfma_f32_16x16x32_bf16 v[108:111], v[144:147], v[192:195], v[108:111]
	v_mfma_f32_16x16x32_bf16 v[92:95], v[144:147], v[200:203], 0
	v_mfma_f32_16x16x32_bf16 v[92:95], v[148:151], v[204:207], v[92:95]
	v_mfma_f32_16x16x32_bf16 v[76:79], v[148:151], v[212:215], 0
	v_mfma_f32_16x16x32_bf16 v[76:79], v[144:147], v[208:211], v[76:79]
	v_mfma_f32_16x16x32_bf16 v[72:75], v[152:155], v[208:211], 0
	v_mfma_f32_16x16x32_bf16 v[72:75], v[156:159], v[212:215], v[72:75]
	v_mfma_f32_16x16x32_bf16 v[88:91], v[156:159], v[204:207], 0
	v_mfma_f32_16x16x32_bf16 v[88:91], v[152:155], v[200:203], v[88:91]
	v_mfma_f32_16x16x32_bf16 v[104:107], v[152:155], v[192:195], 0
	v_mfma_f32_16x16x32_bf16 v[104:107], v[156:159], v[196:199], v[104:107]
	v_mfma_f32_16x16x32_bf16 v[120:123], v[156:159], v[188:191], 0
	v_mfma_f32_16x16x32_bf16 v[120:123], v[152:155], v[184:187], v[120:123]
	v_mfma_f32_16x16x32_bf16 v[116:119], v[160:163], v[184:187], 0
	v_mfma_f32_16x16x32_bf16 v[116:119], v[164:167], v[188:191], v[116:119]
	v_mfma_f32_16x16x32_bf16 v[100:103], v[164:167], v[196:199], 0
	v_mfma_f32_16x16x32_bf16 v[100:103], v[160:163], v[192:195], v[100:103]
	v_mfma_f32_16x16x32_bf16 v[84:87], v[160:163], v[200:203], 0
	v_mfma_f32_16x16x32_bf16 v[84:87], v[164:167], v[204:207], v[84:87]
	v_mfma_f32_16x16x32_bf16 v[68:71], v[164:167], v[212:215], 0
	v_mfma_f32_16x16x32_bf16 v[68:71], v[160:163], v[208:211], v[68:71]
	v_mfma_f32_16x16x32_bf16 v[64:67], v[168:171], v[208:211], 0
	v_mfma_f32_16x16x32_bf16 v[64:67], v[172:175], v[212:215], v[64:67]
	v_mfma_f32_16x16x32_bf16 v[80:83], v[172:175], v[204:207], 0
	v_mfma_f32_16x16x32_bf16 v[80:83], v[168:171], v[200:203], v[80:83]
	s_setprio 2
	s_barrier
	v_mfma_f32_16x16x32_bf16 v[96:99], v[168:171], v[192:195], 0
	v_mfma_f32_16x16x32_bf16 v[96:99], v[172:175], v[196:199], v[96:99]
	v_mfma_f32_16x16x32_bf16 v[112:115], v[172:175], v[188:191], 0
	v_mfma_f32_16x16x32_bf16 v[112:115], v[168:171], v[184:187], v[112:115]
	s_setprio 2
	s_add_i32 s74, s69, s51
	v_lshl_add_u64 v[176:177], s[40:41], 0, v[130:131]
	s_mov_b32 m0, s74
	ds_read_b128 v[184:187], v181 offset:16384
	ds_read_b128 v[188:191], v181 offset:17408
	ds_read_b128 v[192:195], v181 offset:18432
	ds_read_b128 v[196:199], v181 offset:19456
	ds_read_b128 v[200:203], v181 offset:20480
	ds_read_b128 v[204:207], v181 offset:21504
	ds_read_b128 v[208:211], v181 offset:22528
	ds_read_b128 v[212:215], v181 offset:23552
	global_load_lds_dwordx4 v[176:177], off
	s_add_i32 m0, s74, 0x2000
	s_add_u32 s74, s40, 0x40000
	v_lshl_add_u64 v[216:217], s[40:41], 0, v[134:135]
	s_addc_u32 s75, s41, 0
	s_add_i32 s76, s70, s51
	global_load_lds_dwordx4 v[216:217], off
	v_lshl_add_u64 v[218:219], s[74:75], 0, v[130:131]
	s_mov_b32 m0, s76
	v_lshl_add_u64 v[220:221], s[44:45], 0, v[132:133]
	global_load_lds_dwordx4 v[218:219], off
	s_add_i32 m0, s76, 0x2000
	v_lshl_add_u64 v[218:219], s[74:75], 0, v[134:135]
	global_load_lds_dwordx4 v[218:219], off
	s_mov_b32 m0, s54
	v_lshl_add_u64 v[218:219], s[44:45], 0, v[128:129]
	global_load_lds_dwordx4 v[218:219], off
	s_mov_b32 m0, s55
	s_nop 0
	global_load_lds_dwordx4 v[220:221], off
	s_waitcnt vmcnt(8) lgkmcnt(0)
	s_barrier
	s_setprio 1
	v_mfma_f32_16x16x32_bf16 v[60:63], v[144:147], v[184:187], 0
	v_mfma_f32_16x16x32_bf16 v[60:63], v[148:151], v[188:191], v[60:63]
	v_mfma_f32_16x16x32_bf16 v[44:47], v[148:151], v[196:199], 0
	v_mfma_f32_16x16x32_bf16 v[44:47], v[144:147], v[192:195], v[44:47]
	v_mfma_f32_16x16x32_bf16 v[28:31], v[144:147], v[200:203], 0
	v_mfma_f32_16x16x32_bf16 v[28:31], v[148:151], v[204:207], v[28:31]
	v_mfma_f32_16x16x32_bf16 v[12:15], v[148:151], v[212:215], 0
	v_mfma_f32_16x16x32_bf16 v[12:15], v[144:147], v[208:211], v[12:15]
	v_mfma_f32_16x16x32_bf16 v[8:11], v[152:155], v[208:211], 0
	v_mfma_f32_16x16x32_bf16 v[8:11], v[156:159], v[212:215], v[8:11]
	v_mfma_f32_16x16x32_bf16 v[24:27], v[156:159], v[204:207], 0
	v_mfma_f32_16x16x32_bf16 v[24:27], v[152:155], v[200:203], v[24:27]
	v_mfma_f32_16x16x32_bf16 v[40:43], v[152:155], v[192:195], 0
	v_mfma_f32_16x16x32_bf16 v[40:43], v[156:159], v[196:199], v[40:43]
	v_mfma_f32_16x16x32_bf16 v[56:59], v[156:159], v[188:191], 0
	v_mfma_f32_16x16x32_bf16 v[56:59], v[152:155], v[184:187], v[56:59]
	v_mfma_f32_16x16x32_bf16 v[52:55], v[160:163], v[184:187], 0
	v_mfma_f32_16x16x32_bf16 v[52:55], v[164:167], v[188:191], v[52:55]
	v_mfma_f32_16x16x32_bf16 v[36:39], v[164:167], v[196:199], 0
	v_mfma_f32_16x16x32_bf16 v[36:39], v[160:163], v[192:195], v[36:39]
	v_mfma_f32_16x16x32_bf16 v[20:23], v[160:163], v[200:203], 0
	v_mfma_f32_16x16x32_bf16 v[20:23], v[164:167], v[204:207], v[20:23]
	v_mfma_f32_16x16x32_bf16 v[4:7], v[164:167], v[212:215], 0
	v_mfma_f32_16x16x32_bf16 v[4:7], v[160:163], v[208:211], v[4:7]
	v_mfma_f32_16x16x32_bf16 v[0:3], v[168:171], v[208:211], 0
	v_mfma_f32_16x16x32_bf16 v[0:3], v[172:175], v[212:215], v[0:3]
	v_mfma_f32_16x16x32_bf16 v[16:19], v[172:175], v[204:207], 0
	v_mfma_f32_16x16x32_bf16 v[16:19], v[168:171], v[200:203], v[16:19]
	s_setprio 2
	s_barrier
	v_mfma_f32_16x16x32_bf16 v[32:35], v[168:171], v[192:195], 0
	v_mfma_f32_16x16x32_bf16 v[32:35], v[172:175], v[196:199], v[32:35]
	v_mfma_f32_16x16x32_bf16 v[48:51], v[172:175], v[188:191], 0
	v_mfma_f32_16x16x32_bf16 v[48:51], v[168:171], v[184:187], v[48:51]
	s_setprio 0
	s_add_i32 s74, 0, 0x18000
	s_add_i32 s75, 0, 0x1c000
	v_add_u32_e32 v156, s74, v178
	v_add_u32_e32 v172, s75, v178
	ds_read_b128 v[144:147], v156
	ds_read_b128 v[148:151], v156 offset:1024
	ds_read_b128 v[152:155], v156 offset:2048
	ds_read_b128 v[156:159], v156 offset:3072
	ds_read_b128 v[160:163], v172
	ds_read_b128 v[164:167], v172 offset:1024
	ds_read_b128 v[168:171], v172 offset:2048
	ds_read_b128 v[172:175], v172 offset:3072
	s_add_u32 s44, s44, 0x40000
	s_addc_u32 s45, s45, 0
	s_mov_b32 m0, s56
	v_lshl_add_u64 v[222:223], s[44:45], 0, v[128:129]
	ds_read_b128 v[184:187], v181 offset:32768
	ds_read_b128 v[188:191], v181 offset:33792
	ds_read_b128 v[192:195], v181 offset:34816
	ds_read_b128 v[196:199], v181 offset:35840
	ds_read_b128 v[200:203], v181 offset:36864
	ds_read_b128 v[204:207], v181 offset:37888
	ds_read_b128 v[208:211], v181 offset:38912
	ds_read_b128 v[212:215], v181 offset:39936
	global_load_lds_dwordx4 v[222:223], off
	s_mov_b32 m0, s57
	v_lshl_add_u64 v[222:223], s[44:45], 0, v[132:133]
	global_load_lds_dwordx4 v[222:223], off
	s_waitcnt vmcnt(8) lgkmcnt(0)
	s_barrier
	s_setprio 1
	v_mfma_f32_16x16x32_bf16 v[124:127], v[144:147], v[184:187], v[124:127]
	v_mfma_f32_16x16x32_bf16 v[124:127], v[148:151], v[188:191], v[124:127]
	v_mfma_f32_16x16x32_bf16 v[108:111], v[148:151], v[196:199], v[108:111]
	v_mfma_f32_16x16x32_bf16 v[108:111], v[144:147], v[192:195], v[108:111]
	v_mfma_f32_16x16x32_bf16 v[92:95], v[144:147], v[200:203], v[92:95]
	v_mfma_f32_16x16x32_bf16 v[92:95], v[148:151], v[204:207], v[92:95]
	v_mfma_f32_16x16x32_bf16 v[76:79], v[148:151], v[212:215], v[76:79]
	v_mfma_f32_16x16x32_bf16 v[76:79], v[144:147], v[208:211], v[76:79]
	v_mfma_f32_16x16x32_bf16 v[72:75], v[152:155], v[208:211], v[72:75]
	v_mfma_f32_16x16x32_bf16 v[72:75], v[156:159], v[212:215], v[72:75]
	v_mfma_f32_16x16x32_bf16 v[88:91], v[156:159], v[204:207], v[88:91]
	v_mfma_f32_16x16x32_bf16 v[88:91], v[152:155], v[200:203], v[88:91]
	v_mfma_f32_16x16x32_bf16 v[104:107], v[152:155], v[192:195], v[104:107]
	v_mfma_f32_16x16x32_bf16 v[104:107], v[156:159], v[196:199], v[104:107]
	v_mfma_f32_16x16x32_bf16 v[120:123], v[156:159], v[188:191], v[120:123]
	v_mfma_f32_16x16x32_bf16 v[120:123], v[152:155], v[184:187], v[120:123]
	v_mfma_f32_16x16x32_bf16 v[116:119], v[160:163], v[184:187], v[116:119]
	v_mfma_f32_16x16x32_bf16 v[116:119], v[164:167], v[188:191], v[116:119]
	v_mfma_f32_16x16x32_bf16 v[100:103], v[164:167], v[196:199], v[100:103]
	v_mfma_f32_16x16x32_bf16 v[100:103], v[160:163], v[192:195], v[100:103]
	v_mfma_f32_16x16x32_bf16 v[84:87], v[160:163], v[200:203], v[84:87]
	v_mfma_f32_16x16x32_bf16 v[84:87], v[164:167], v[204:207], v[84:87]
	v_mfma_f32_16x16x32_bf16 v[68:71], v[164:167], v[212:215], v[68:71]
	v_mfma_f32_16x16x32_bf16 v[68:71], v[160:163], v[208:211], v[68:71]
	v_mfma_f32_16x16x32_bf16 v[64:67], v[168:171], v[208:211], v[64:67]
	v_mfma_f32_16x16x32_bf16 v[64:67], v[172:175], v[212:215], v[64:67]
	v_mfma_f32_16x16x32_bf16 v[80:83], v[172:175], v[204:207], v[80:83]
	v_mfma_f32_16x16x32_bf16 v[80:83], v[168:171], v[200:203], v[80:83]
	s_setprio 2
	s_barrier
	v_mfma_f32_16x16x32_bf16 v[96:99], v[168:171], v[192:195], v[96:99]
	v_mfma_f32_16x16x32_bf16 v[96:99], v[172:175], v[196:199], v[96:99]
	v_mfma_f32_16x16x32_bf16 v[112:115], v[172:175], v[188:191], v[112:115]
	v_mfma_f32_16x16x32_bf16 v[112:115], v[168:171], v[184:187], v[112:115]
	s_setprio 2
	s_add_i32 s44, s74, s51
	v_lshl_add_u64 v[176:177], v[176:177], 0, s[22:23]
	s_mov_b32 m0, s44
	ds_read_b128 v[184:187], v181 offset:49152
	ds_read_b128 v[188:191], v181 offset:50176
	ds_read_b128 v[192:195], v181 offset:51200
	ds_read_b128 v[196:199], v181 offset:52224
	ds_read_b128 v[200:203], v181 offset:53248
	ds_read_b128 v[204:207], v181 offset:54272
	ds_read_b128 v[208:211], v181 offset:55296
	ds_read_b128 v[212:215], v181 offset:56320
	global_load_lds_dwordx4 v[176:177], off
	s_add_i32 m0, s44, 0x2000
	s_add_u32 s40, s40, 0x40080
	v_lshl_add_u64 v[176:177], v[216:217], 0, s[22:23]
	s_addc_u32 s41, s41, 0
	s_add_i32 s44, s75, s51
	global_load_lds_dwordx4 v[176:177], off
	s_mov_b32 m0, s44
	v_lshl_add_u64 v[176:177], s[40:41], 0, v[130:131]
	global_load_lds_dwordx4 v[176:177], off
	s_add_i32 m0, s44, 0x2000
	v_lshl_add_u64 v[176:177], s[40:41], 0, v[134:135]
	global_load_lds_dwordx4 v[176:177], off
	s_mov_b32 m0, s64
	v_lshl_add_u64 v[176:177], v[218:219], 0, s[22:23]
	global_load_lds_dwordx4 v[176:177], off
	s_mov_b32 m0, s65
	v_lshl_add_u64 v[176:177], v[220:221], 0, s[22:23]
	global_load_lds_dwordx4 v[176:177], off
	s_waitcnt vmcnt(8) lgkmcnt(0)
	s_barrier
	s_setprio 1
	v_mfma_f32_16x16x32_bf16 v[60:63], v[144:147], v[184:187], v[60:63]
	v_mfma_f32_16x16x32_bf16 v[60:63], v[148:151], v[188:191], v[60:63]
	v_mfma_f32_16x16x32_bf16 v[44:47], v[148:151], v[196:199], v[44:47]
	v_mfma_f32_16x16x32_bf16 v[44:47], v[144:147], v[192:195], v[44:47]
	v_mfma_f32_16x16x32_bf16 v[28:31], v[144:147], v[200:203], v[28:31]
	v_mfma_f32_16x16x32_bf16 v[28:31], v[148:151], v[204:207], v[28:31]
	v_mfma_f32_16x16x32_bf16 v[12:15], v[148:151], v[212:215], v[12:15]
	v_mfma_f32_16x16x32_bf16 v[12:15], v[144:147], v[208:211], v[12:15]
	v_mfma_f32_16x16x32_bf16 v[8:11], v[152:155], v[208:211], v[8:11]
	v_mfma_f32_16x16x32_bf16 v[8:11], v[156:159], v[212:215], v[8:11]
	v_mfma_f32_16x16x32_bf16 v[24:27], v[156:159], v[204:207], v[24:27]
	v_mfma_f32_16x16x32_bf16 v[24:27], v[152:155], v[200:203], v[24:27]
	v_mfma_f32_16x16x32_bf16 v[40:43], v[152:155], v[192:195], v[40:43]
	v_mfma_f32_16x16x32_bf16 v[40:43], v[156:159], v[196:199], v[40:43]
	v_mfma_f32_16x16x32_bf16 v[56:59], v[156:159], v[188:191], v[56:59]
	v_mfma_f32_16x16x32_bf16 v[56:59], v[152:155], v[184:187], v[56:59]
	v_mfma_f32_16x16x32_bf16 v[52:55], v[160:163], v[184:187], v[52:55]
	v_mfma_f32_16x16x32_bf16 v[52:55], v[164:167], v[188:191], v[52:55]
	v_mfma_f32_16x16x32_bf16 v[36:39], v[164:167], v[196:199], v[36:39]
	v_mfma_f32_16x16x32_bf16 v[36:39], v[160:163], v[192:195], v[36:39]
	v_mfma_f32_16x16x32_bf16 v[20:23], v[160:163], v[200:203], v[20:23]
	v_mfma_f32_16x16x32_bf16 v[20:23], v[164:167], v[204:207], v[20:23]
	v_mfma_f32_16x16x32_bf16 v[4:7], v[164:167], v[212:215], v[4:7]
	v_mfma_f32_16x16x32_bf16 v[4:7], v[160:163], v[208:211], v[4:7]
	v_mfma_f32_16x16x32_bf16 v[0:3], v[168:171], v[208:211], v[0:3]
	v_mfma_f32_16x16x32_bf16 v[0:3], v[172:175], v[212:215], v[0:3]
	v_mfma_f32_16x16x32_bf16 v[16:19], v[172:175], v[204:207], v[16:19]
	v_mfma_f32_16x16x32_bf16 v[16:19], v[168:171], v[200:203], v[16:19]
	s_setprio 2
	s_barrier
	v_mfma_f32_16x16x32_bf16 v[32:35], v[168:171], v[192:195], v[32:35]
	v_mfma_f32_16x16x32_bf16 v[32:35], v[172:175], v[196:199], v[32:35]
	v_mfma_f32_16x16x32_bf16 v[48:51], v[172:175], v[188:191], v[48:51]
	v_mfma_f32_16x16x32_bf16 v[48:51], v[168:171], v[184:187], v[48:51]
	s_setprio 0
	s_add_i32 s73, s73, 2
	s_add_u32 s6, s6, 0x100
	s_addc_u32 s7, s7, 0
	s_add_u32 s71, s71, 0x100
	s_addc_u32 s72, s72, 0
	s_cmp_gt_u32 s73, 13
.LBB0_952:
	ds_read_b128 v[144:147], v179
	ds_read_b128 v[148:151], v179 offset:1024
	ds_read_b128 v[152:155], v179 offset:2048
	ds_read_b128 v[156:159], v179 offset:3072
	ds_read_b128 v[160:163], v180
	ds_read_b128 v[164:167], v180 offset:1024
	ds_read_b128 v[168:171], v180 offset:2048
	ds_read_b128 v[172:175], v180 offset:3072
	s_add_u32 s40, s6, 0xfffc0080
	s_addc_u32 s41, s7, -1
	s_cmp_eq_u32 s73, 12
	s_cselect_b32 s45, s27, s41
	s_cselect_b32 s44, s39, s40
	s_cselect_b32 s41, s29, s72
	s_cselect_b32 s40, s43, s71
	v_lshl_add_u64 v[176:177], s[6:7], 0, v[136:137]
	s_add_i32 m0, s54, 0xc000
	ds_read_b128 v[184:187], v181
	ds_read_b128 v[188:191], v181 offset:1024
	ds_read_b128 v[192:195], v181 offset:2048
	ds_read_b128 v[196:199], v181 offset:3072
	ds_read_b128 v[200:203], v181 offset:4096
	ds_read_b128 v[204:207], v181 offset:5120
	ds_read_b128 v[208:211], v181 offset:6144
	ds_read_b128 v[212:215], v181 offset:7168
	global_load_lds_dwordx4 v[176:177], off
	s_add_i32 m0, s54, 0xe000
	v_lshl_add_u64 v[176:177], s[6:7], 0, v[138:139]
	global_load_lds_dwordx4 v[176:177], off
	s_waitcnt vmcnt(8) lgkmcnt(0)
	s_barrier
	s_setprio 1
	v_mfma_f32_16x16x32_bf16 v[124:127], v[144:147], v[184:187], v[124:127]
	v_mfma_f32_16x16x32_bf16 v[124:127], v[148:151], v[188:191], v[124:127]
	v_mfma_f32_16x16x32_bf16 v[108:111], v[148:151], v[196:199], v[108:111]
	v_mfma_f32_16x16x32_bf16 v[108:111], v[144:147], v[192:195], v[108:111]
	v_mfma_f32_16x16x32_bf16 v[92:95], v[144:147], v[200:203], v[92:95]
	v_mfma_f32_16x16x32_bf16 v[92:95], v[148:151], v[204:207], v[92:95]
	v_mfma_f32_16x16x32_bf16 v[76:79], v[148:151], v[212:215], v[76:79]
	v_mfma_f32_16x16x32_bf16 v[76:79], v[144:147], v[208:211], v[76:79]
	v_mfma_f32_16x16x32_bf16 v[72:75], v[152:155], v[208:211], v[72:75]
	v_mfma_f32_16x16x32_bf16 v[72:75], v[156:159], v[212:215], v[72:75]
	v_mfma_f32_16x16x32_bf16 v[88:91], v[156:159], v[204:207], v[88:91]
	v_mfma_f32_16x16x32_bf16 v[88:91], v[152:155], v[200:203], v[88:91]
	v_mfma_f32_16x16x32_bf16 v[104:107], v[152:155], v[192:195], v[104:107]
	v_mfma_f32_16x16x32_bf16 v[104:107], v[156:159], v[196:199], v[104:107]
	v_mfma_f32_16x16x32_bf16 v[120:123], v[156:159], v[188:191], v[120:123]
	v_mfma_f32_16x16x32_bf16 v[120:123], v[152:155], v[184:187], v[120:123]
	v_mfma_f32_16x16x32_bf16 v[116:119], v[160:163], v[184:187], v[116:119]
	v_mfma_f32_16x16x32_bf16 v[116:119], v[164:167], v[188:191], v[116:119]
	v_mfma_f32_16x16x32_bf16 v[100:103], v[164:167], v[196:199], v[100:103]
	v_mfma_f32_16x16x32_bf16 v[100:103], v[160:163], v[192:195], v[100:103]
	v_mfma_f32_16x16x32_bf16 v[84:87], v[160:163], v[200:203], v[84:87]
	v_mfma_f32_16x16x32_bf16 v[84:87], v[164:167], v[204:207], v[84:87]
	v_mfma_f32_16x16x32_bf16 v[68:71], v[164:167], v[212:215], v[68:71]
	v_mfma_f32_16x16x32_bf16 v[68:71], v[160:163], v[208:211], v[68:71]
	v_mfma_f32_16x16x32_bf16 v[64:67], v[168:171], v[208:211], v[64:67]
	v_mfma_f32_16x16x32_bf16 v[64:67], v[172:175], v[212:215], v[64:67]
	v_mfma_f32_16x16x32_bf16 v[80:83], v[172:175], v[204:207], v[80:83]
	v_mfma_f32_16x16x32_bf16 v[80:83], v[168:171], v[200:203], v[80:83]
	s_setprio 2
	s_barrier
	v_mfma_f32_16x16x32_bf16 v[96:99], v[168:171], v[192:195], v[96:99]
	v_mfma_f32_16x16x32_bf16 v[96:99], v[172:175], v[196:199], v[96:99]
	v_mfma_f32_16x16x32_bf16 v[112:115], v[172:175], v[188:191], v[112:115]
	v_mfma_f32_16x16x32_bf16 v[112:115], v[168:171], v[184:187], v[112:115]
	s_setprio 2
	s_add_i32 s74, s69, s51
	v_lshl_add_u64 v[176:177], s[40:41], 0, v[130:131]
	s_mov_b32 m0, s74
	ds_read_b128 v[184:187], v181 offset:16384
	ds_read_b128 v[188:191], v181 offset:17408
	ds_read_b128 v[192:195], v181 offset:18432
	ds_read_b128 v[196:199], v181 offset:19456
	ds_read_b128 v[200:203], v181 offset:20480
	ds_read_b128 v[204:207], v181 offset:21504
	ds_read_b128 v[208:211], v181 offset:22528
	ds_read_b128 v[212:215], v181 offset:23552
	global_load_lds_dwordx4 v[176:177], off
	s_add_i32 m0, s74, 0x2000
	s_add_u32 s74, s40, 0x40000
	v_lshl_add_u64 v[216:217], s[40:41], 0, v[134:135]
	s_addc_u32 s75, s41, 0
	s_add_i32 s76, s70, s51
	global_load_lds_dwordx4 v[216:217], off
	v_lshl_add_u64 v[218:219], s[74:75], 0, v[130:131]
	s_mov_b32 m0, s76
	v_lshl_add_u64 v[220:221], s[44:45], 0, v[132:133]
	global_load_lds_dwordx4 v[218:219], off
	s_add_i32 m0, s76, 0x2000
	v_lshl_add_u64 v[218:219], s[74:75], 0, v[134:135]
	global_load_lds_dwordx4 v[218:219], off
	s_mov_b32 m0, s54
	v_lshl_add_u64 v[218:219], s[44:45], 0, v[128:129]
	global_load_lds_dwordx4 v[218:219], off
	s_mov_b32 m0, s55
	s_nop 0
	global_load_lds_dwordx4 v[220:221], off
	s_waitcnt vmcnt(8) lgkmcnt(0)
	s_barrier
	s_setprio 1
	v_mfma_f32_16x16x32_bf16 v[60:63], v[144:147], v[184:187], v[60:63]
	v_mfma_f32_16x16x32_bf16 v[60:63], v[148:151], v[188:191], v[60:63]
	v_mfma_f32_16x16x32_bf16 v[44:47], v[148:151], v[196:199], v[44:47]
	v_mfma_f32_16x16x32_bf16 v[44:47], v[144:147], v[192:195], v[44:47]
	v_mfma_f32_16x16x32_bf16 v[28:31], v[144:147], v[200:203], v[28:31]
	v_mfma_f32_16x16x32_bf16 v[28:31], v[148:151], v[204:207], v[28:31]
	v_mfma_f32_16x16x32_bf16 v[12:15], v[148:151], v[212:215], v[12:15]
	v_mfma_f32_16x16x32_bf16 v[12:15], v[144:147], v[208:211], v[12:15]
	v_mfma_f32_16x16x32_bf16 v[8:11], v[152:155], v[208:211], v[8:11]
	v_mfma_f32_16x16x32_bf16 v[8:11], v[156:159], v[212:215], v[8:11]
	v_mfma_f32_16x16x32_bf16 v[24:27], v[156:159], v[204:207], v[24:27]
	v_mfma_f32_16x16x32_bf16 v[24:27], v[152:155], v[200:203], v[24:27]
	v_mfma_f32_16x16x32_bf16 v[40:43], v[152:155], v[192:195], v[40:43]
	v_mfma_f32_16x16x32_bf16 v[40:43], v[156:159], v[196:199], v[40:43]
	v_mfma_f32_16x16x32_bf16 v[56:59], v[156:159], v[188:191], v[56:59]
	v_mfma_f32_16x16x32_bf16 v[56:59], v[152:155], v[184:187], v[56:59]
	v_mfma_f32_16x16x32_bf16 v[52:55], v[160:163], v[184:187], v[52:55]
	v_mfma_f32_16x16x32_bf16 v[52:55], v[164:167], v[188:191], v[52:55]
	v_mfma_f32_16x16x32_bf16 v[36:39], v[164:167], v[196:199], v[36:39]
	v_mfma_f32_16x16x32_bf16 v[36:39], v[160:163], v[192:195], v[36:39]
	v_mfma_f32_16x16x32_bf16 v[20:23], v[160:163], v[200:203], v[20:23]
	v_mfma_f32_16x16x32_bf16 v[20:23], v[164:167], v[204:207], v[20:23]
	v_mfma_f32_16x16x32_bf16 v[4:7], v[164:167], v[212:215], v[4:7]
	v_mfma_f32_16x16x32_bf16 v[4:7], v[160:163], v[208:211], v[4:7]
	v_mfma_f32_16x16x32_bf16 v[0:3], v[168:171], v[208:211], v[0:3]
	v_mfma_f32_16x16x32_bf16 v[0:3], v[172:175], v[212:215], v[0:3]
	v_mfma_f32_16x16x32_bf16 v[16:19], v[172:175], v[204:207], v[16:19]
	v_mfma_f32_16x16x32_bf16 v[16:19], v[168:171], v[200:203], v[16:19]
	s_setprio 2
	s_barrier
	v_mfma_f32_16x16x32_bf16 v[32:35], v[168:171], v[192:195], v[32:35]
	v_mfma_f32_16x16x32_bf16 v[32:35], v[172:175], v[196:199], v[32:35]
	v_mfma_f32_16x16x32_bf16 v[48:51], v[172:175], v[188:191], v[48:51]
	v_mfma_f32_16x16x32_bf16 v[48:51], v[168:171], v[184:187], v[48:51]
	s_setprio 0
	s_add_i32 s74, 0, 0x18000
	s_add_i32 s75, 0, 0x1c000
	v_add_u32_e32 v156, s74, v178
	v_add_u32_e32 v172, s75, v178
	ds_read_b128 v[144:147], v156
	ds_read_b128 v[148:151], v156 offset:1024
	ds_read_b128 v[152:155], v156 offset:2048
	ds_read_b128 v[156:159], v156 offset:3072
	ds_read_b128 v[160:163], v172
	ds_read_b128 v[164:167], v172 offset:1024
	ds_read_b128 v[168:171], v172 offset:2048
	ds_read_b128 v[172:175], v172 offset:3072
	s_add_u32 s44, s44, 0x40000
	s_addc_u32 s45, s45, 0
	s_mov_b32 m0, s56
	v_lshl_add_u64 v[222:223], s[44:45], 0, v[128:129]
	ds_read_b128 v[184:187], v181 offset:32768
	ds_read_b128 v[188:191], v181 offset:33792
	ds_read_b128 v[192:195], v181 offset:34816
	ds_read_b128 v[196:199], v181 offset:35840
	ds_read_b128 v[200:203], v181 offset:36864
	ds_read_b128 v[204:207], v181 offset:37888
	ds_read_b128 v[208:211], v181 offset:38912
	ds_read_b128 v[212:215], v181 offset:39936
	global_load_lds_dwordx4 v[222:223], off
	s_mov_b32 m0, s57
	v_lshl_add_u64 v[222:223], s[44:45], 0, v[132:133]
	global_load_lds_dwordx4 v[222:223], off
	s_waitcnt vmcnt(8) lgkmcnt(0)
	s_barrier
	s_setprio 1
	v_mfma_f32_16x16x32_bf16 v[124:127], v[144:147], v[184:187], v[124:127]
	v_mfma_f32_16x16x32_bf16 v[124:127], v[148:151], v[188:191], v[124:127]
	v_mfma_f32_16x16x32_bf16 v[108:111], v[148:151], v[196:199], v[108:111]
	v_mfma_f32_16x16x32_bf16 v[108:111], v[144:147], v[192:195], v[108:111]
	v_mfma_f32_16x16x32_bf16 v[92:95], v[144:147], v[200:203], v[92:95]
	v_mfma_f32_16x16x32_bf16 v[92:95], v[148:151], v[204:207], v[92:95]
	v_mfma_f32_16x16x32_bf16 v[76:79], v[148:151], v[212:215], v[76:79]
	v_mfma_f32_16x16x32_bf16 v[76:79], v[144:147], v[208:211], v[76:79]
	v_mfma_f32_16x16x32_bf16 v[72:75], v[152:155], v[208:211], v[72:75]
	v_mfma_f32_16x16x32_bf16 v[72:75], v[156:159], v[212:215], v[72:75]
	v_mfma_f32_16x16x32_bf16 v[88:91], v[156:159], v[204:207], v[88:91]
	v_mfma_f32_16x16x32_bf16 v[88:91], v[152:155], v[200:203], v[88:91]
	v_mfma_f32_16x16x32_bf16 v[104:107], v[152:155], v[192:195], v[104:107]
	v_mfma_f32_16x16x32_bf16 v[104:107], v[156:159], v[196:199], v[104:107]
	v_mfma_f32_16x16x32_bf16 v[120:123], v[156:159], v[188:191], v[120:123]
	v_mfma_f32_16x16x32_bf16 v[120:123], v[152:155], v[184:187], v[120:123]
	v_mfma_f32_16x16x32_bf16 v[116:119], v[160:163], v[184:187], v[116:119]
	v_mfma_f32_16x16x32_bf16 v[116:119], v[164:167], v[188:191], v[116:119]
	v_mfma_f32_16x16x32_bf16 v[100:103], v[164:167], v[196:199], v[100:103]
	v_mfma_f32_16x16x32_bf16 v[100:103], v[160:163], v[192:195], v[100:103]
	v_mfma_f32_16x16x32_bf16 v[84:87], v[160:163], v[200:203], v[84:87]
	v_mfma_f32_16x16x32_bf16 v[84:87], v[164:167], v[204:207], v[84:87]
	v_mfma_f32_16x16x32_bf16 v[68:71], v[164:167], v[212:215], v[68:71]
	v_mfma_f32_16x16x32_bf16 v[68:71], v[160:163], v[208:211], v[68:71]
	v_mfma_f32_16x16x32_bf16 v[64:67], v[168:171], v[208:211], v[64:67]
	v_mfma_f32_16x16x32_bf16 v[64:67], v[172:175], v[212:215], v[64:67]
	v_mfma_f32_16x16x32_bf16 v[80:83], v[172:175], v[204:207], v[80:83]
	v_mfma_f32_16x16x32_bf16 v[80:83], v[168:171], v[200:203], v[80:83]
	s_setprio 2
	s_barrier
	v_mfma_f32_16x16x32_bf16 v[96:99], v[168:171], v[192:195], v[96:99]
	v_mfma_f32_16x16x32_bf16 v[96:99], v[172:175], v[196:199], v[96:99]
	v_mfma_f32_16x16x32_bf16 v[112:115], v[172:175], v[188:191], v[112:115]
	v_mfma_f32_16x16x32_bf16 v[112:115], v[168:171], v[184:187], v[112:115]
	s_setprio 2
	s_add_i32 s44, s74, s51
	v_lshl_add_u64 v[176:177], v[176:177], 0, s[22:23]
	s_mov_b32 m0, s44
	ds_read_b128 v[184:187], v181 offset:49152
	ds_read_b128 v[188:191], v181 offset:50176
	ds_read_b128 v[192:195], v181 offset:51200
	ds_read_b128 v[196:199], v181 offset:52224
	ds_read_b128 v[200:203], v181 offset:53248
	ds_read_b128 v[204:207], v181 offset:54272
	ds_read_b128 v[208:211], v181 offset:55296
	ds_read_b128 v[212:215], v181 offset:56320
	global_load_lds_dwordx4 v[176:177], off
	s_add_i32 m0, s44, 0x2000
	s_add_u32 s40, s40, 0x40080
	v_lshl_add_u64 v[176:177], v[216:217], 0, s[22:23]
	s_addc_u32 s41, s41, 0
	s_add_i32 s44, s75, s51
	global_load_lds_dwordx4 v[176:177], off
	s_mov_b32 m0, s44
	v_lshl_add_u64 v[176:177], s[40:41], 0, v[130:131]
	global_load_lds_dwordx4 v[176:177], off
	s_add_i32 m0, s44, 0x2000
	v_lshl_add_u64 v[176:177], s[40:41], 0, v[134:135]
	global_load_lds_dwordx4 v[176:177], off
	s_mov_b32 m0, s64
	v_lshl_add_u64 v[176:177], v[218:219], 0, s[22:23]
	global_load_lds_dwordx4 v[176:177], off
	s_mov_b32 m0, s65
	v_lshl_add_u64 v[176:177], v[220:221], 0, s[22:23]
	global_load_lds_dwordx4 v[176:177], off
	s_waitcnt vmcnt(8) lgkmcnt(0)
	s_barrier
	s_setprio 1
	v_mfma_f32_16x16x32_bf16 v[60:63], v[144:147], v[184:187], v[60:63]
	v_mfma_f32_16x16x32_bf16 v[60:63], v[148:151], v[188:191], v[60:63]
	v_mfma_f32_16x16x32_bf16 v[44:47], v[148:151], v[196:199], v[44:47]
	v_mfma_f32_16x16x32_bf16 v[44:47], v[144:147], v[192:195], v[44:47]
	v_mfma_f32_16x16x32_bf16 v[28:31], v[144:147], v[200:203], v[28:31]
	v_mfma_f32_16x16x32_bf16 v[28:31], v[148:151], v[204:207], v[28:31]
	v_mfma_f32_16x16x32_bf16 v[12:15], v[148:151], v[212:215], v[12:15]
	v_mfma_f32_16x16x32_bf16 v[12:15], v[144:147], v[208:211], v[12:15]
	v_mfma_f32_16x16x32_bf16 v[8:11], v[152:155], v[208:211], v[8:11]
	v_mfma_f32_16x16x32_bf16 v[8:11], v[156:159], v[212:215], v[8:11]
	v_mfma_f32_16x16x32_bf16 v[24:27], v[156:159], v[204:207], v[24:27]
	v_mfma_f32_16x16x32_bf16 v[24:27], v[152:155], v[200:203], v[24:27]
	v_mfma_f32_16x16x32_bf16 v[40:43], v[152:155], v[192:195], v[40:43]
	v_mfma_f32_16x16x32_bf16 v[40:43], v[156:159], v[196:199], v[40:43]
	v_mfma_f32_16x16x32_bf16 v[56:59], v[156:159], v[188:191], v[56:59]
	v_mfma_f32_16x16x32_bf16 v[56:59], v[152:155], v[184:187], v[56:59]
	v_mfma_f32_16x16x32_bf16 v[52:55], v[160:163], v[184:187], v[52:55]
	v_mfma_f32_16x16x32_bf16 v[52:55], v[164:167], v[188:191], v[52:55]
	v_mfma_f32_16x16x32_bf16 v[36:39], v[164:167], v[196:199], v[36:39]
	v_mfma_f32_16x16x32_bf16 v[36:39], v[160:163], v[192:195], v[36:39]
	v_mfma_f32_16x16x32_bf16 v[20:23], v[160:163], v[200:203], v[20:23]
	v_mfma_f32_16x16x32_bf16 v[20:23], v[164:167], v[204:207], v[20:23]
	v_mfma_f32_16x16x32_bf16 v[4:7], v[164:167], v[212:215], v[4:7]
	v_mfma_f32_16x16x32_bf16 v[4:7], v[160:163], v[208:211], v[4:7]
	v_mfma_f32_16x16x32_bf16 v[0:3], v[168:171], v[208:211], v[0:3]
	v_mfma_f32_16x16x32_bf16 v[0:3], v[172:175], v[212:215], v[0:3]
	v_mfma_f32_16x16x32_bf16 v[16:19], v[172:175], v[204:207], v[16:19]
	v_mfma_f32_16x16x32_bf16 v[16:19], v[168:171], v[200:203], v[16:19]
	s_setprio 2
	s_barrier
	v_mfma_f32_16x16x32_bf16 v[32:35], v[168:171], v[192:195], v[32:35]
	v_mfma_f32_16x16x32_bf16 v[32:35], v[172:175], v[196:199], v[32:35]
	v_mfma_f32_16x16x32_bf16 v[48:51], v[172:175], v[188:191], v[48:51]
	v_mfma_f32_16x16x32_bf16 v[48:51], v[168:171], v[184:187], v[48:51]
	s_setprio 0
	s_add_i32 s73, s73, 2
	s_add_u32 s6, s6, 0x100
	s_addc_u32 s7, s7, 0
	s_add_u32 s71, s71, 0x100
	s_addc_u32 s72, s72, 0
	s_cmp_gt_u32 s73, 13
	s_cbranch_scc0 .LBB0_952

.LBB0_1145:
	s_ashr_i32 s23, s22, 31
	s_lshl_b64 s[26:27], s[22:23], 19
	s_add_u32 s26, s45, s26
	s_addc_u32 s27, s46, s27
	s_and_b64 s[28:29], s[4:5], exec
	s_cselect_b32 s23, s27, s39
	s_cselect_b32 s31, s26, s38
	s_ashr_i32 s25, s24, 31
	s_lshl_b64 s[28:29], s[24:25], 19
	s_add_u32 s28, s47, s28
	s_addc_u32 s29, s48, s29
	s_and_b64 s[42:43], s[4:5], exec
	s_cselect_b32 s25, s29, s41
	s_cselect_b32 s37, s28, s40
	s_add_u32 s38, s38, 0x40080
	s_addc_u32 s39, s39, 0
	s_add_u32 s64, s40, 0x100
	s_addc_u32 s65, s41, 0
	s_mov_b32 s66, -2
	ds_read_b128 v[120:123], v233
	ds_read_b128 v[132:135], v233 offset:1024
	ds_read_b128 v[136:139], v233 offset:2048
	ds_read_b128 v[140:143], v233 offset:3072
	ds_read_b128 v[144:147], v234
	ds_read_b128 v[148:151], v234 offset:1024
	ds_read_b128 v[152:155], v234 offset:2048
	ds_read_b128 v[156:159], v234 offset:3072
	s_add_u32 s40, s38, 0xfffc0080
	s_addc_u32 s41, s39, -1
	s_cmp_eq_u32 s66, 12
	s_cselect_b32 s43, s23, s41
	s_cselect_b32 s42, s31, s40
	s_cselect_b32 s41, s25, s65
	s_cselect_b32 s40, s37, s64
	v_lshl_add_u64 v[208:209], s[38:39], 0, v[192:193]
	s_add_i32 m0, s50, 0xc000
	ds_read_b128 v[160:163], v235
	ds_read_b128 v[164:167], v235 offset:1024
	ds_read_b128 v[168:171], v235 offset:2048
	ds_read_b128 v[172:175], v235 offset:3072
	ds_read_b128 v[176:179], v235 offset:4096
	ds_read_b128 v[180:183], v235 offset:5120
	ds_read_b128 v[200:203], v235 offset:6144
	ds_read_b128 v[204:207], v235 offset:7168
	global_load_lds_dwordx4 v[208:209], off
	s_add_i32 m0, s50, 0xe000
	v_lshl_add_u64 v[208:209], s[38:39], 0, v[194:195]
	global_load_lds_dwordx4 v[208:209], off
	s_waitcnt vmcnt(8) lgkmcnt(0)
	s_barrier
	s_setprio 1
	v_mfma_f32_16x16x32_bf16 v[128:131], v[120:123], v[160:163], 0
	v_mfma_f32_16x16x32_bf16 v[128:131], v[132:135], v[164:167], v[128:131]
	v_mfma_f32_16x16x32_bf16 v[108:111], v[132:135], v[172:175], 0
	v_mfma_f32_16x16x32_bf16 v[108:111], v[120:123], v[168:171], v[108:111]
	v_mfma_f32_16x16x32_bf16 v[92:95], v[120:123], v[176:179], 0
	v_mfma_f32_16x16x32_bf16 v[92:95], v[132:135], v[180:183], v[92:95]
	v_mfma_f32_16x16x32_bf16 v[76:79], v[132:135], v[204:207], 0
	v_mfma_f32_16x16x32_bf16 v[76:79], v[120:123], v[200:203], v[76:79]
	v_mfma_f32_16x16x32_bf16 v[72:75], v[136:139], v[200:203], 0
	v_mfma_f32_16x16x32_bf16 v[72:75], v[140:143], v[204:207], v[72:75]
	v_mfma_f32_16x16x32_bf16 v[88:91], v[140:143], v[180:183], 0
	v_mfma_f32_16x16x32_bf16 v[88:91], v[136:139], v[176:179], v[88:91]
	v_mfma_f32_16x16x32_bf16 v[104:107], v[136:139], v[168:171], 0
	v_mfma_f32_16x16x32_bf16 v[104:107], v[140:143], v[172:175], v[104:107]
	v_mfma_f32_16x16x32_bf16 v[124:127], v[140:143], v[164:167], 0
	v_mfma_f32_16x16x32_bf16 v[124:127], v[136:139], v[160:163], v[124:127]
	v_mfma_f32_16x16x32_bf16 v[116:119], v[144:147], v[160:163], 0
	v_mfma_f32_16x16x32_bf16 v[116:119], v[148:151], v[164:167], v[116:119]
	v_mfma_f32_16x16x32_bf16 v[100:103], v[148:151], v[172:175], 0
	v_mfma_f32_16x16x32_bf16 v[100:103], v[144:147], v[168:171], v[100:103]
	v_mfma_f32_16x16x32_bf16 v[84:87], v[144:147], v[176:179], 0
	v_mfma_f32_16x16x32_bf16 v[84:87], v[148:151], v[180:183], v[84:87]
	v_mfma_f32_16x16x32_bf16 v[68:71], v[148:151], v[204:207], 0
	v_mfma_f32_16x16x32_bf16 v[68:71], v[144:147], v[200:203], v[68:71]
	v_mfma_f32_16x16x32_bf16 v[64:67], v[152:155], v[200:203], 0
	v_mfma_f32_16x16x32_bf16 v[64:67], v[156:159], v[204:207], v[64:67]
	v_mfma_f32_16x16x32_bf16 v[80:83], v[156:159], v[180:183], 0
	v_mfma_f32_16x16x32_bf16 v[80:83], v[152:155], v[176:179], v[80:83]
	s_setprio 2
	s_barrier
	v_mfma_f32_16x16x32_bf16 v[96:99], v[152:155], v[168:171], 0
	v_mfma_f32_16x16x32_bf16 v[96:99], v[156:159], v[172:175], v[96:99]
	v_mfma_f32_16x16x32_bf16 v[112:115], v[156:159], v[164:167], 0
	v_mfma_f32_16x16x32_bf16 v[112:115], v[152:155], v[160:163], v[112:115]
	s_setprio 2
	s_add_i32 s67, s62, s49
	v_lshl_add_u64 v[208:209], s[40:41], 0, v[186:187]
	s_mov_b32 m0, s67
	ds_read_b128 v[160:163], v235 offset:16384
	ds_read_b128 v[164:167], v235 offset:17408
	ds_read_b128 v[168:171], v235 offset:18432
	ds_read_b128 v[172:175], v235 offset:19456
	ds_read_b128 v[176:179], v235 offset:20480
	ds_read_b128 v[180:183], v235 offset:21504
	ds_read_b128 v[200:203], v235 offset:22528
	ds_read_b128 v[204:207], v235 offset:23552
	global_load_lds_dwordx4 v[208:209], off
	s_add_i32 m0, s67, 0x2000
	s_add_u32 s68, s40, 0x40000
	v_lshl_add_u64 v[210:211], s[40:41], 0, v[190:191]
	s_addc_u32 s69, s41, 0
	s_add_i32 s67, s63, s49
	global_load_lds_dwordx4 v[210:211], off
	v_lshl_add_u64 v[212:213], s[68:69], 0, v[186:187]
	s_mov_b32 m0, s67
	v_lshl_add_u64 v[214:215], s[42:43], 0, v[188:189]
	global_load_lds_dwordx4 v[212:213], off
	s_add_i32 m0, s67, 0x2000
	v_lshl_add_u64 v[212:213], s[68:69], 0, v[190:191]
	global_load_lds_dwordx4 v[212:213], off
	s_mov_b32 m0, s50
	v_lshl_add_u64 v[212:213], s[42:43], 0, v[184:185]
	global_load_lds_dwordx4 v[212:213], off
	s_mov_b32 m0, s51
	s_nop 0
	global_load_lds_dwordx4 v[214:215], off
	s_waitcnt vmcnt(8) lgkmcnt(0)
	s_barrier
	s_setprio 1
	v_mfma_f32_16x16x32_bf16 v[60:63], v[120:123], v[160:163], 0
	v_mfma_f32_16x16x32_bf16 v[60:63], v[132:135], v[164:167], v[60:63]
	v_mfma_f32_16x16x32_bf16 v[44:47], v[132:135], v[172:175], 0
	v_mfma_f32_16x16x32_bf16 v[44:47], v[120:123], v[168:171], v[44:47]
	v_mfma_f32_16x16x32_bf16 v[28:31], v[120:123], v[176:179], 0
	v_mfma_f32_16x16x32_bf16 v[28:31], v[132:135], v[180:183], v[28:31]
	v_mfma_f32_16x16x32_bf16 v[12:15], v[132:135], v[204:207], 0
	v_mfma_f32_16x16x32_bf16 v[12:15], v[120:123], v[200:203], v[12:15]
	v_mfma_f32_16x16x32_bf16 v[8:11], v[136:139], v[200:203], 0
	v_mfma_f32_16x16x32_bf16 v[8:11], v[140:143], v[204:207], v[8:11]
	v_mfma_f32_16x16x32_bf16 v[24:27], v[140:143], v[180:183], 0
	v_mfma_f32_16x16x32_bf16 v[24:27], v[136:139], v[176:179], v[24:27]
	v_mfma_f32_16x16x32_bf16 v[40:43], v[136:139], v[168:171], 0
	v_mfma_f32_16x16x32_bf16 v[40:43], v[140:143], v[172:175], v[40:43]
	v_mfma_f32_16x16x32_bf16 v[56:59], v[140:143], v[164:167], 0
	v_mfma_f32_16x16x32_bf16 v[56:59], v[136:139], v[160:163], v[56:59]
	v_mfma_f32_16x16x32_bf16 v[52:55], v[144:147], v[160:163], 0
	v_mfma_f32_16x16x32_bf16 v[52:55], v[148:151], v[164:167], v[52:55]
	v_mfma_f32_16x16x32_bf16 v[36:39], v[148:151], v[172:175], 0
	v_mfma_f32_16x16x32_bf16 v[36:39], v[144:147], v[168:171], v[36:39]
	v_mfma_f32_16x16x32_bf16 v[20:23], v[144:147], v[176:179], 0
	v_mfma_f32_16x16x32_bf16 v[20:23], v[148:151], v[180:183], v[20:23]
	v_mfma_f32_16x16x32_bf16 v[4:7], v[148:151], v[204:207], 0
	v_mfma_f32_16x16x32_bf16 v[4:7], v[144:147], v[200:203], v[4:7]
	v_mfma_f32_16x16x32_bf16 v[0:3], v[152:155], v[200:203], 0
	v_mfma_f32_16x16x32_bf16 v[0:3], v[156:159], v[204:207], v[0:3]
	v_mfma_f32_16x16x32_bf16 v[16:19], v[156:159], v[180:183], 0
	v_mfma_f32_16x16x32_bf16 v[16:19], v[152:155], v[176:179], v[16:19]
	s_setprio 2
	s_barrier
	v_mfma_f32_16x16x32_bf16 v[32:35], v[152:155], v[168:171], 0
	v_mfma_f32_16x16x32_bf16 v[32:35], v[156:159], v[172:175], v[32:35]
	v_mfma_f32_16x16x32_bf16 v[48:51], v[156:159], v[164:167], 0
	v_mfma_f32_16x16x32_bf16 v[48:51], v[152:155], v[160:163], v[48:51]
	s_setprio 0
	s_add_i32 s67, 0, 0x18000
	s_add_i32 s68, 0, 0x1c000
	v_add_u32_e32 v140, s67, v232
	v_add_u32_e32 v156, s68, v232
	ds_read_b128 v[120:123], v140
	ds_read_b128 v[132:135], v140 offset:1024
	ds_read_b128 v[136:139], v140 offset:2048
	ds_read_b128 v[140:143], v140 offset:3072
	ds_read_b128 v[144:147], v156
	ds_read_b128 v[148:151], v156 offset:1024
	ds_read_b128 v[152:155], v156 offset:2048
	ds_read_b128 v[156:159], v156 offset:3072
	s_add_u32 s42, s42, 0x40000
	s_addc_u32 s43, s43, 0
	s_mov_b32 m0, s54
	v_lshl_add_u64 v[216:217], s[42:43], 0, v[184:185]
	ds_read_b128 v[160:163], v235 offset:32768
	ds_read_b128 v[164:167], v235 offset:33792
	ds_read_b128 v[168:171], v235 offset:34816
	ds_read_b128 v[172:175], v235 offset:35840
	ds_read_b128 v[176:179], v235 offset:36864
	ds_read_b128 v[180:183], v235 offset:37888
	ds_read_b128 v[200:203], v235 offset:38912
	ds_read_b128 v[204:207], v235 offset:39936
	global_load_lds_dwordx4 v[216:217], off
	s_mov_b32 m0, s55
	v_lshl_add_u64 v[216:217], s[42:43], 0, v[188:189]
	global_load_lds_dwordx4 v[216:217], off
	s_waitcnt vmcnt(8) lgkmcnt(0)
	s_barrier
	s_setprio 1
	v_mfma_f32_16x16x32_bf16 v[128:131], v[120:123], v[160:163], v[128:131]
	v_mfma_f32_16x16x32_bf16 v[128:131], v[132:135], v[164:167], v[128:131]
	v_mfma_f32_16x16x32_bf16 v[108:111], v[132:135], v[172:175], v[108:111]
	v_mfma_f32_16x16x32_bf16 v[108:111], v[120:123], v[168:171], v[108:111]
	v_mfma_f32_16x16x32_bf16 v[92:95], v[120:123], v[176:179], v[92:95]
	v_mfma_f32_16x16x32_bf16 v[92:95], v[132:135], v[180:183], v[92:95]
	v_mfma_f32_16x16x32_bf16 v[76:79], v[132:135], v[204:207], v[76:79]
	v_mfma_f32_16x16x32_bf16 v[76:79], v[120:123], v[200:203], v[76:79]
	v_mfma_f32_16x16x32_bf16 v[72:75], v[136:139], v[200:203], v[72:75]
	v_mfma_f32_16x16x32_bf16 v[72:75], v[140:143], v[204:207], v[72:75]
	v_mfma_f32_16x16x32_bf16 v[88:91], v[140:143], v[180:183], v[88:91]
	v_mfma_f32_16x16x32_bf16 v[88:91], v[136:139], v[176:179], v[88:91]
	v_mfma_f32_16x16x32_bf16 v[104:107], v[136:139], v[168:171], v[104:107]
	v_mfma_f32_16x16x32_bf16 v[104:107], v[140:143], v[172:175], v[104:107]
	v_mfma_f32_16x16x32_bf16 v[124:127], v[140:143], v[164:167], v[124:127]
	v_mfma_f32_16x16x32_bf16 v[124:127], v[136:139], v[160:163], v[124:127]
	v_mfma_f32_16x16x32_bf16 v[116:119], v[144:147], v[160:163], v[116:119]
	v_mfma_f32_16x16x32_bf16 v[116:119], v[148:151], v[164:167], v[116:119]
	v_mfma_f32_16x16x32_bf16 v[100:103], v[148:151], v[172:175], v[100:103]
	v_mfma_f32_16x16x32_bf16 v[100:103], v[144:147], v[168:171], v[100:103]
	v_mfma_f32_16x16x32_bf16 v[84:87], v[144:147], v[176:179], v[84:87]
	v_mfma_f32_16x16x32_bf16 v[84:87], v[148:151], v[180:183], v[84:87]
	v_mfma_f32_16x16x32_bf16 v[68:71], v[148:151], v[204:207], v[68:71]
	v_mfma_f32_16x16x32_bf16 v[68:71], v[144:147], v[200:203], v[68:71]
	v_mfma_f32_16x16x32_bf16 v[64:67], v[152:155], v[200:203], v[64:67]
	v_mfma_f32_16x16x32_bf16 v[64:67], v[156:159], v[204:207], v[64:67]
	v_mfma_f32_16x16x32_bf16 v[80:83], v[156:159], v[180:183], v[80:83]
	v_mfma_f32_16x16x32_bf16 v[80:83], v[152:155], v[176:179], v[80:83]
	s_setprio 2
	s_barrier
	v_mfma_f32_16x16x32_bf16 v[96:99], v[152:155], v[168:171], v[96:99]
	v_mfma_f32_16x16x32_bf16 v[96:99], v[156:159], v[172:175], v[96:99]
	v_mfma_f32_16x16x32_bf16 v[112:115], v[156:159], v[164:167], v[112:115]
	v_mfma_f32_16x16x32_bf16 v[112:115], v[152:155], v[160:163], v[112:115]
	s_setprio 2
	s_add_i32 s42, s67, s49
	v_lshl_add_u64 v[208:209], v[208:209], 0, s[18:19]
	s_mov_b32 m0, s42
	ds_read_b128 v[160:163], v235 offset:49152
	ds_read_b128 v[164:167], v235 offset:50176
	ds_read_b128 v[168:171], v235 offset:51200
	ds_read_b128 v[172:175], v235 offset:52224
	ds_read_b128 v[176:179], v235 offset:53248
	ds_read_b128 v[180:183], v235 offset:54272
	ds_read_b128 v[200:203], v235 offset:55296
	ds_read_b128 v[204:207], v235 offset:56320
	global_load_lds_dwordx4 v[208:209], off
	s_add_i32 m0, s42, 0x2000
	s_add_u32 s40, s40, 0x40080
	v_lshl_add_u64 v[208:209], v[210:211], 0, s[18:19]
	s_addc_u32 s41, s41, 0
	s_add_i32 s42, s68, s49
	global_load_lds_dwordx4 v[208:209], off
	s_mov_b32 m0, s42
	v_lshl_add_u64 v[208:209], s[40:41], 0, v[186:187]
	global_load_lds_dwordx4 v[208:209], off
	s_add_i32 m0, s42, 0x2000
	v_lshl_add_u64 v[208:209], s[40:41], 0, v[190:191]
	global_load_lds_dwordx4 v[208:209], off
	s_mov_b32 m0, s57
	v_lshl_add_u64 v[208:209], v[212:213], 0, s[18:19]
	global_load_lds_dwordx4 v[208:209], off
	s_mov_b32 m0, s58
	v_lshl_add_u64 v[208:209], v[214:215], 0, s[18:19]
	global_load_lds_dwordx4 v[208:209], off
	s_waitcnt vmcnt(8) lgkmcnt(0)
	s_barrier
	s_setprio 1
	v_mfma_f32_16x16x32_bf16 v[60:63], v[120:123], v[160:163], v[60:63]
	v_mfma_f32_16x16x32_bf16 v[60:63], v[132:135], v[164:167], v[60:63]
	v_mfma_f32_16x16x32_bf16 v[44:47], v[132:135], v[172:175], v[44:47]
	v_mfma_f32_16x16x32_bf16 v[44:47], v[120:123], v[168:171], v[44:47]
	v_mfma_f32_16x16x32_bf16 v[28:31], v[120:123], v[176:179], v[28:31]
	v_mfma_f32_16x16x32_bf16 v[28:31], v[132:135], v[180:183], v[28:31]
	v_mfma_f32_16x16x32_bf16 v[12:15], v[132:135], v[204:207], v[12:15]
	v_mfma_f32_16x16x32_bf16 v[12:15], v[120:123], v[200:203], v[12:15]
	v_mfma_f32_16x16x32_bf16 v[8:11], v[136:139], v[200:203], v[8:11]
	v_mfma_f32_16x16x32_bf16 v[8:11], v[140:143], v[204:207], v[8:11]
	v_mfma_f32_16x16x32_bf16 v[24:27], v[140:143], v[180:183], v[24:27]
	v_mfma_f32_16x16x32_bf16 v[24:27], v[136:139], v[176:179], v[24:27]
	v_mfma_f32_16x16x32_bf16 v[40:43], v[136:139], v[168:171], v[40:43]
	v_mfma_f32_16x16x32_bf16 v[40:43], v[140:143], v[172:175], v[40:43]
	v_mfma_f32_16x16x32_bf16 v[56:59], v[140:143], v[164:167], v[56:59]
	v_mfma_f32_16x16x32_bf16 v[56:59], v[136:139], v[160:163], v[56:59]
	v_mfma_f32_16x16x32_bf16 v[52:55], v[144:147], v[160:163], v[52:55]
	v_mfma_f32_16x16x32_bf16 v[52:55], v[148:151], v[164:167], v[52:55]
	v_mfma_f32_16x16x32_bf16 v[36:39], v[148:151], v[172:175], v[36:39]
	v_mfma_f32_16x16x32_bf16 v[36:39], v[144:147], v[168:171], v[36:39]
	v_mfma_f32_16x16x32_bf16 v[20:23], v[144:147], v[176:179], v[20:23]
	v_mfma_f32_16x16x32_bf16 v[20:23], v[148:151], v[180:183], v[20:23]
	v_mfma_f32_16x16x32_bf16 v[4:7], v[148:151], v[204:207], v[4:7]
	v_mfma_f32_16x16x32_bf16 v[4:7], v[144:147], v[200:203], v[4:7]
	v_mfma_f32_16x16x32_bf16 v[0:3], v[152:155], v[200:203], v[0:3]
	v_mfma_f32_16x16x32_bf16 v[0:3], v[156:159], v[204:207], v[0:3]
	v_mfma_f32_16x16x32_bf16 v[16:19], v[156:159], v[180:183], v[16:19]
	v_mfma_f32_16x16x32_bf16 v[16:19], v[152:155], v[176:179], v[16:19]
	s_setprio 2
	s_barrier
	v_mfma_f32_16x16x32_bf16 v[32:35], v[152:155], v[168:171], v[32:35]
	v_mfma_f32_16x16x32_bf16 v[32:35], v[156:159], v[172:175], v[32:35]
	v_mfma_f32_16x16x32_bf16 v[48:51], v[156:159], v[164:167], v[48:51]
	v_mfma_f32_16x16x32_bf16 v[48:51], v[152:155], v[160:163], v[48:51]
	s_setprio 0
	s_add_i32 s66, s66, 2
	s_add_u32 s38, s38, 0x100
	s_addc_u32 s39, s39, 0
	s_add_u32 s64, s64, 0x100
	s_addc_u32 s65, s65, 0
	s_cmp_gt_u32 s66, 13
.LBB0_1146:
	ds_read_b128 v[120:123], v233
	ds_read_b128 v[132:135], v233 offset:1024
	ds_read_b128 v[136:139], v233 offset:2048
	ds_read_b128 v[140:143], v233 offset:3072
	ds_read_b128 v[144:147], v234
	ds_read_b128 v[148:151], v234 offset:1024
	ds_read_b128 v[152:155], v234 offset:2048
	ds_read_b128 v[156:159], v234 offset:3072
	s_add_u32 s40, s38, 0xfffc0080
	s_addc_u32 s41, s39, -1
	s_cmp_eq_u32 s66, 12
	s_cselect_b32 s43, s23, s41
	s_cselect_b32 s42, s31, s40
	s_cselect_b32 s41, s25, s65
	s_cselect_b32 s40, s37, s64
	v_lshl_add_u64 v[208:209], s[38:39], 0, v[192:193]
	s_add_i32 m0, s50, 0xc000
	ds_read_b128 v[160:163], v235
	ds_read_b128 v[164:167], v235 offset:1024
	ds_read_b128 v[168:171], v235 offset:2048
	ds_read_b128 v[172:175], v235 offset:3072
	ds_read_b128 v[176:179], v235 offset:4096
	ds_read_b128 v[180:183], v235 offset:5120
	ds_read_b128 v[200:203], v235 offset:6144
	ds_read_b128 v[204:207], v235 offset:7168
	global_load_lds_dwordx4 v[208:209], off
	s_add_i32 m0, s50, 0xe000
	v_lshl_add_u64 v[208:209], s[38:39], 0, v[194:195]
	global_load_lds_dwordx4 v[208:209], off
	s_waitcnt vmcnt(8) lgkmcnt(0)
	s_barrier
	s_setprio 1
	v_mfma_f32_16x16x32_bf16 v[128:131], v[120:123], v[160:163], v[128:131]
	v_mfma_f32_16x16x32_bf16 v[128:131], v[132:135], v[164:167], v[128:131]
	v_mfma_f32_16x16x32_bf16 v[108:111], v[132:135], v[172:175], v[108:111]
	v_mfma_f32_16x16x32_bf16 v[108:111], v[120:123], v[168:171], v[108:111]
	v_mfma_f32_16x16x32_bf16 v[92:95], v[120:123], v[176:179], v[92:95]
	v_mfma_f32_16x16x32_bf16 v[92:95], v[132:135], v[180:183], v[92:95]
	v_mfma_f32_16x16x32_bf16 v[76:79], v[132:135], v[204:207], v[76:79]
	v_mfma_f32_16x16x32_bf16 v[76:79], v[120:123], v[200:203], v[76:79]
	v_mfma_f32_16x16x32_bf16 v[72:75], v[136:139], v[200:203], v[72:75]
	v_mfma_f32_16x16x32_bf16 v[72:75], v[140:143], v[204:207], v[72:75]
	v_mfma_f32_16x16x32_bf16 v[88:91], v[140:143], v[180:183], v[88:91]
	v_mfma_f32_16x16x32_bf16 v[88:91], v[136:139], v[176:179], v[88:91]
	v_mfma_f32_16x16x32_bf16 v[104:107], v[136:139], v[168:171], v[104:107]
	v_mfma_f32_16x16x32_bf16 v[104:107], v[140:143], v[172:175], v[104:107]
	v_mfma_f32_16x16x32_bf16 v[124:127], v[140:143], v[164:167], v[124:127]
	v_mfma_f32_16x16x32_bf16 v[124:127], v[136:139], v[160:163], v[124:127]
	v_mfma_f32_16x16x32_bf16 v[116:119], v[144:147], v[160:163], v[116:119]
	v_mfma_f32_16x16x32_bf16 v[116:119], v[148:151], v[164:167], v[116:119]
	v_mfma_f32_16x16x32_bf16 v[100:103], v[148:151], v[172:175], v[100:103]
	v_mfma_f32_16x16x32_bf16 v[100:103], v[144:147], v[168:171], v[100:103]
	v_mfma_f32_16x16x32_bf16 v[84:87], v[144:147], v[176:179], v[84:87]
	v_mfma_f32_16x16x32_bf16 v[84:87], v[148:151], v[180:183], v[84:87]
	v_mfma_f32_16x16x32_bf16 v[68:71], v[148:151], v[204:207], v[68:71]
	v_mfma_f32_16x16x32_bf16 v[68:71], v[144:147], v[200:203], v[68:71]
	v_mfma_f32_16x16x32_bf16 v[64:67], v[152:155], v[200:203], v[64:67]
	v_mfma_f32_16x16x32_bf16 v[64:67], v[156:159], v[204:207], v[64:67]
	v_mfma_f32_16x16x32_bf16 v[80:83], v[156:159], v[180:183], v[80:83]
	v_mfma_f32_16x16x32_bf16 v[80:83], v[152:155], v[176:179], v[80:83]
	s_setprio 2
	s_barrier
	v_mfma_f32_16x16x32_bf16 v[96:99], v[152:155], v[168:171], v[96:99]
	v_mfma_f32_16x16x32_bf16 v[96:99], v[156:159], v[172:175], v[96:99]
	v_mfma_f32_16x16x32_bf16 v[112:115], v[156:159], v[164:167], v[112:115]
	v_mfma_f32_16x16x32_bf16 v[112:115], v[152:155], v[160:163], v[112:115]
	s_setprio 2
	s_add_i32 s67, s62, s49
	v_lshl_add_u64 v[208:209], s[40:41], 0, v[186:187]
	s_mov_b32 m0, s67
	ds_read_b128 v[160:163], v235 offset:16384
	ds_read_b128 v[164:167], v235 offset:17408
	ds_read_b128 v[168:171], v235 offset:18432
	ds_read_b128 v[172:175], v235 offset:19456
	ds_read_b128 v[176:179], v235 offset:20480
	ds_read_b128 v[180:183], v235 offset:21504
	ds_read_b128 v[200:203], v235 offset:22528
	ds_read_b128 v[204:207], v235 offset:23552
	global_load_lds_dwordx4 v[208:209], off
	s_add_i32 m0, s67, 0x2000
	s_add_u32 s68, s40, 0x40000
	v_lshl_add_u64 v[210:211], s[40:41], 0, v[190:191]
	s_addc_u32 s69, s41, 0
	s_add_i32 s67, s63, s49
	global_load_lds_dwordx4 v[210:211], off
	v_lshl_add_u64 v[212:213], s[68:69], 0, v[186:187]
	s_mov_b32 m0, s67
	v_lshl_add_u64 v[214:215], s[42:43], 0, v[188:189]
	global_load_lds_dwordx4 v[212:213], off
	s_add_i32 m0, s67, 0x2000
	v_lshl_add_u64 v[212:213], s[68:69], 0, v[190:191]
	global_load_lds_dwordx4 v[212:213], off
	s_mov_b32 m0, s50
	v_lshl_add_u64 v[212:213], s[42:43], 0, v[184:185]
	global_load_lds_dwordx4 v[212:213], off
	s_mov_b32 m0, s51
	s_nop 0
	global_load_lds_dwordx4 v[214:215], off
	s_waitcnt vmcnt(8) lgkmcnt(0)
	s_barrier
	s_setprio 1
	v_mfma_f32_16x16x32_bf16 v[60:63], v[120:123], v[160:163], v[60:63]
	v_mfma_f32_16x16x32_bf16 v[60:63], v[132:135], v[164:167], v[60:63]
	v_mfma_f32_16x16x32_bf16 v[44:47], v[132:135], v[172:175], v[44:47]
	v_mfma_f32_16x16x32_bf16 v[44:47], v[120:123], v[168:171], v[44:47]
	v_mfma_f32_16x16x32_bf16 v[28:31], v[120:123], v[176:179], v[28:31]
	v_mfma_f32_16x16x32_bf16 v[28:31], v[132:135], v[180:183], v[28:31]
	v_mfma_f32_16x16x32_bf16 v[12:15], v[132:135], v[204:207], v[12:15]
	v_mfma_f32_16x16x32_bf16 v[12:15], v[120:123], v[200:203], v[12:15]
	v_mfma_f32_16x16x32_bf16 v[8:11], v[136:139], v[200:203], v[8:11]
	v_mfma_f32_16x16x32_bf16 v[8:11], v[140:143], v[204:207], v[8:11]
	v_mfma_f32_16x16x32_bf16 v[24:27], v[140:143], v[180:183], v[24:27]
	v_mfma_f32_16x16x32_bf16 v[24:27], v[136:139], v[176:179], v[24:27]
	v_mfma_f32_16x16x32_bf16 v[40:43], v[136:139], v[168:171], v[40:43]
	v_mfma_f32_16x16x32_bf16 v[40:43], v[140:143], v[172:175], v[40:43]
	v_mfma_f32_16x16x32_bf16 v[56:59], v[140:143], v[164:167], v[56:59]
	v_mfma_f32_16x16x32_bf16 v[56:59], v[136:139], v[160:163], v[56:59]
	v_mfma_f32_16x16x32_bf16 v[52:55], v[144:147], v[160:163], v[52:55]
	v_mfma_f32_16x16x32_bf16 v[52:55], v[148:151], v[164:167], v[52:55]
	v_mfma_f32_16x16x32_bf16 v[36:39], v[148:151], v[172:175], v[36:39]
	v_mfma_f32_16x16x32_bf16 v[36:39], v[144:147], v[168:171], v[36:39]
	v_mfma_f32_16x16x32_bf16 v[20:23], v[144:147], v[176:179], v[20:23]
	v_mfma_f32_16x16x32_bf16 v[20:23], v[148:151], v[180:183], v[20:23]
	v_mfma_f32_16x16x32_bf16 v[4:7], v[148:151], v[204:207], v[4:7]
	v_mfma_f32_16x16x32_bf16 v[4:7], v[144:147], v[200:203], v[4:7]
	v_mfma_f32_16x16x32_bf16 v[0:3], v[152:155], v[200:203], v[0:3]
	v_mfma_f32_16x16x32_bf16 v[0:3], v[156:159], v[204:207], v[0:3]
	v_mfma_f32_16x16x32_bf16 v[16:19], v[156:159], v[180:183], v[16:19]
	v_mfma_f32_16x16x32_bf16 v[16:19], v[152:155], v[176:179], v[16:19]
	s_setprio 2
	s_barrier
	v_mfma_f32_16x16x32_bf16 v[32:35], v[152:155], v[168:171], v[32:35]
	v_mfma_f32_16x16x32_bf16 v[32:35], v[156:159], v[172:175], v[32:35]
	v_mfma_f32_16x16x32_bf16 v[48:51], v[156:159], v[164:167], v[48:51]
	v_mfma_f32_16x16x32_bf16 v[48:51], v[152:155], v[160:163], v[48:51]
	s_setprio 0
	s_add_i32 s67, 0, 0x18000
	s_add_i32 s68, 0, 0x1c000
	v_add_u32_e32 v140, s67, v232
	v_add_u32_e32 v156, s68, v232
	ds_read_b128 v[120:123], v140
	ds_read_b128 v[132:135], v140 offset:1024
	ds_read_b128 v[136:139], v140 offset:2048
	ds_read_b128 v[140:143], v140 offset:3072
	ds_read_b128 v[144:147], v156
	ds_read_b128 v[148:151], v156 offset:1024
	ds_read_b128 v[152:155], v156 offset:2048
	ds_read_b128 v[156:159], v156 offset:3072
	s_add_u32 s42, s42, 0x40000
	s_addc_u32 s43, s43, 0
	s_mov_b32 m0, s54
	v_lshl_add_u64 v[216:217], s[42:43], 0, v[184:185]
	ds_read_b128 v[160:163], v235 offset:32768
	ds_read_b128 v[164:167], v235 offset:33792
	ds_read_b128 v[168:171], v235 offset:34816
	ds_read_b128 v[172:175], v235 offset:35840
	ds_read_b128 v[176:179], v235 offset:36864
	ds_read_b128 v[180:183], v235 offset:37888
	ds_read_b128 v[200:203], v235 offset:38912
	ds_read_b128 v[204:207], v235 offset:39936
	global_load_lds_dwordx4 v[216:217], off
	s_mov_b32 m0, s55
	v_lshl_add_u64 v[216:217], s[42:43], 0, v[188:189]
	global_load_lds_dwordx4 v[216:217], off
	s_waitcnt vmcnt(8) lgkmcnt(0)
	s_barrier
	s_setprio 1
	v_mfma_f32_16x16x32_bf16 v[128:131], v[120:123], v[160:163], v[128:131]
	v_mfma_f32_16x16x32_bf16 v[128:131], v[132:135], v[164:167], v[128:131]
	v_mfma_f32_16x16x32_bf16 v[108:111], v[132:135], v[172:175], v[108:111]
	v_mfma_f32_16x16x32_bf16 v[108:111], v[120:123], v[168:171], v[108:111]
	v_mfma_f32_16x16x32_bf16 v[92:95], v[120:123], v[176:179], v[92:95]
	v_mfma_f32_16x16x32_bf16 v[92:95], v[132:135], v[180:183], v[92:95]
	v_mfma_f32_16x16x32_bf16 v[76:79], v[132:135], v[204:207], v[76:79]
	v_mfma_f32_16x16x32_bf16 v[76:79], v[120:123], v[200:203], v[76:79]
	v_mfma_f32_16x16x32_bf16 v[72:75], v[136:139], v[200:203], v[72:75]
	v_mfma_f32_16x16x32_bf16 v[72:75], v[140:143], v[204:207], v[72:75]
	v_mfma_f32_16x16x32_bf16 v[88:91], v[140:143], v[180:183], v[88:91]
	v_mfma_f32_16x16x32_bf16 v[88:91], v[136:139], v[176:179], v[88:91]
	v_mfma_f32_16x16x32_bf16 v[104:107], v[136:139], v[168:171], v[104:107]
	v_mfma_f32_16x16x32_bf16 v[104:107], v[140:143], v[172:175], v[104:107]
	v_mfma_f32_16x16x32_bf16 v[124:127], v[140:143], v[164:167], v[124:127]
	v_mfma_f32_16x16x32_bf16 v[124:127], v[136:139], v[160:163], v[124:127]
	v_mfma_f32_16x16x32_bf16 v[116:119], v[144:147], v[160:163], v[116:119]
	v_mfma_f32_16x16x32_bf16 v[116:119], v[148:151], v[164:167], v[116:119]
	v_mfma_f32_16x16x32_bf16 v[100:103], v[148:151], v[172:175], v[100:103]
	v_mfma_f32_16x16x32_bf16 v[100:103], v[144:147], v[168:171], v[100:103]
	v_mfma_f32_16x16x32_bf16 v[84:87], v[144:147], v[176:179], v[84:87]
	v_mfma_f32_16x16x32_bf16 v[84:87], v[148:151], v[180:183], v[84:87]
	v_mfma_f32_16x16x32_bf16 v[68:71], v[148:151], v[204:207], v[68:71]
	v_mfma_f32_16x16x32_bf16 v[68:71], v[144:147], v[200:203], v[68:71]
	v_mfma_f32_16x16x32_bf16 v[64:67], v[152:155], v[200:203], v[64:67]
	v_mfma_f32_16x16x32_bf16 v[64:67], v[156:159], v[204:207], v[64:67]
	v_mfma_f32_16x16x32_bf16 v[80:83], v[156:159], v[180:183], v[80:83]
	v_mfma_f32_16x16x32_bf16 v[80:83], v[152:155], v[176:179], v[80:83]
	s_setprio 2
	s_barrier
	v_mfma_f32_16x16x32_bf16 v[96:99], v[152:155], v[168:171], v[96:99]
	v_mfma_f32_16x16x32_bf16 v[96:99], v[156:159], v[172:175], v[96:99]
	v_mfma_f32_16x16x32_bf16 v[112:115], v[156:159], v[164:167], v[112:115]
	v_mfma_f32_16x16x32_bf16 v[112:115], v[152:155], v[160:163], v[112:115]
	s_setprio 2
	s_add_i32 s42, s67, s49
	v_lshl_add_u64 v[208:209], v[208:209], 0, s[18:19]
	s_mov_b32 m0, s42
	ds_read_b128 v[160:163], v235 offset:49152
	ds_read_b128 v[164:167], v235 offset:50176
	ds_read_b128 v[168:171], v235 offset:51200
	ds_read_b128 v[172:175], v235 offset:52224
	ds_read_b128 v[176:179], v235 offset:53248
	ds_read_b128 v[180:183], v235 offset:54272
	ds_read_b128 v[200:203], v235 offset:55296
	ds_read_b128 v[204:207], v235 offset:56320
	global_load_lds_dwordx4 v[208:209], off
	s_add_i32 m0, s42, 0x2000
	s_add_u32 s40, s40, 0x40080
	v_lshl_add_u64 v[208:209], v[210:211], 0, s[18:19]
	s_addc_u32 s41, s41, 0
	s_add_i32 s42, s68, s49
	global_load_lds_dwordx4 v[208:209], off
	s_mov_b32 m0, s42
	v_lshl_add_u64 v[208:209], s[40:41], 0, v[186:187]
	global_load_lds_dwordx4 v[208:209], off
	s_add_i32 m0, s42, 0x2000
	v_lshl_add_u64 v[208:209], s[40:41], 0, v[190:191]
	global_load_lds_dwordx4 v[208:209], off
	s_mov_b32 m0, s57
	v_lshl_add_u64 v[208:209], v[212:213], 0, s[18:19]
	global_load_lds_dwordx4 v[208:209], off
	s_mov_b32 m0, s58
	v_lshl_add_u64 v[208:209], v[214:215], 0, s[18:19]
	global_load_lds_dwordx4 v[208:209], off
	s_waitcnt vmcnt(8) lgkmcnt(0)
	s_barrier
	s_setprio 1
	v_mfma_f32_16x16x32_bf16 v[60:63], v[120:123], v[160:163], v[60:63]
	v_mfma_f32_16x16x32_bf16 v[60:63], v[132:135], v[164:167], v[60:63]
	v_mfma_f32_16x16x32_bf16 v[44:47], v[132:135], v[172:175], v[44:47]
	v_mfma_f32_16x16x32_bf16 v[44:47], v[120:123], v[168:171], v[44:47]
	v_mfma_f32_16x16x32_bf16 v[28:31], v[120:123], v[176:179], v[28:31]
	v_mfma_f32_16x16x32_bf16 v[28:31], v[132:135], v[180:183], v[28:31]
	v_mfma_f32_16x16x32_bf16 v[12:15], v[132:135], v[204:207], v[12:15]
	v_mfma_f32_16x16x32_bf16 v[12:15], v[120:123], v[200:203], v[12:15]
	v_mfma_f32_16x16x32_bf16 v[8:11], v[136:139], v[200:203], v[8:11]
	v_mfma_f32_16x16x32_bf16 v[8:11], v[140:143], v[204:207], v[8:11]
	v_mfma_f32_16x16x32_bf16 v[24:27], v[140:143], v[180:183], v[24:27]
	v_mfma_f32_16x16x32_bf16 v[24:27], v[136:139], v[176:179], v[24:27]
	v_mfma_f32_16x16x32_bf16 v[40:43], v[136:139], v[168:171], v[40:43]
	v_mfma_f32_16x16x32_bf16 v[40:43], v[140:143], v[172:175], v[40:43]
	v_mfma_f32_16x16x32_bf16 v[56:59], v[140:143], v[164:167], v[56:59]
	v_mfma_f32_16x16x32_bf16 v[56:59], v[136:139], v[160:163], v[56:59]
	v_mfma_f32_16x16x32_bf16 v[52:55], v[144:147], v[160:163], v[52:55]
	v_mfma_f32_16x16x32_bf16 v[52:55], v[148:151], v[164:167], v[52:55]
	v_mfma_f32_16x16x32_bf16 v[36:39], v[148:151], v[172:175], v[36:39]
	v_mfma_f32_16x16x32_bf16 v[36:39], v[144:147], v[168:171], v[36:39]
	v_mfma_f32_16x16x32_bf16 v[20:23], v[144:147], v[176:179], v[20:23]
	v_mfma_f32_16x16x32_bf16 v[20:23], v[148:151], v[180:183], v[20:23]
	v_mfma_f32_16x16x32_bf16 v[4:7], v[148:151], v[204:207], v[4:7]
	v_mfma_f32_16x16x32_bf16 v[4:7], v[144:147], v[200:203], v[4:7]
	v_mfma_f32_16x16x32_bf16 v[0:3], v[152:155], v[200:203], v[0:3]
	v_mfma_f32_16x16x32_bf16 v[0:3], v[156:159], v[204:207], v[0:3]
	v_mfma_f32_16x16x32_bf16 v[16:19], v[156:159], v[180:183], v[16:19]
	v_mfma_f32_16x16x32_bf16 v[16:19], v[152:155], v[176:179], v[16:19]
	s_setprio 2
	s_barrier
	v_mfma_f32_16x16x32_bf16 v[32:35], v[152:155], v[168:171], v[32:35]
	v_mfma_f32_16x16x32_bf16 v[32:35], v[156:159], v[172:175], v[32:35]
	v_mfma_f32_16x16x32_bf16 v[48:51], v[156:159], v[164:167], v[48:51]
	v_mfma_f32_16x16x32_bf16 v[48:51], v[152:155], v[160:163], v[48:51]
	s_setprio 0
	s_add_i32 s66, s66, 2
	s_add_u32 s38, s38, 0x100
	s_addc_u32 s39, s39, 0
	s_add_u32 s64, s64, 0x100
	s_addc_u32 s65, s65, 0
	s_cmp_gt_u32 s66, 13
	s_cbranch_scc0 .LBB0_1146

.LBB0_1309:
	s_add_u32 s51, s26, 0x100
	s_addc_u32 s52, s27, 0
	s_mov_b32 s53, -2
	ds_read_b128 v[128:131], v197
	ds_read_b128 v[132:135], v197 offset:1024
	ds_read_b128 v[136:139], v197 offset:2048
	ds_read_b128 v[140:143], v197 offset:3072
	ds_read_b128 v[144:147], v198
	ds_read_b128 v[148:151], v198 offset:1024
	ds_read_b128 v[152:155], v198 offset:2048
	ds_read_b128 v[156:159], v198 offset:3072
	s_add_u32 s4, s24, 0x100
	s_addc_u32 s5, s25, 0
	s_cmp_eq_u32 s53, 40
	s_cselect_b32 s29, s21, s5
	s_cselect_b32 s28, s20, s4
	s_cselect_b32 s27, s23, s52
	s_cselect_b32 s26, s22, s51
	v_lshl_add_u64 v[212:213], s[24:25], 0, v[172:173]
	s_add_i32 m0, s36, 0xc000
	ds_read_b128 v[160:163], v199
	ds_read_b128 v[180:183], v199 offset:1024
	ds_read_b128 v[184:187], v199 offset:2048
	ds_read_b128 v[188:191], v199 offset:3072
	ds_read_b128 v[192:195], v199 offset:4096
	ds_read_b128 v[200:203], v199 offset:5120
	ds_read_b128 v[204:207], v199 offset:6144
	ds_read_b128 v[208:211], v199 offset:7168
	global_load_lds_dwordx4 v[212:213], off
	s_add_i32 m0, s36, 0xe000
	v_lshl_add_u64 v[212:213], s[24:25], 0, v[174:175]
	global_load_lds_dwordx4 v[212:213], off
	s_waitcnt vmcnt(8) lgkmcnt(0)
	s_barrier
	s_setprio 1
	v_mfma_f32_16x16x32_bf16 v[124:127], v[128:131], v[160:163], 0
	v_mfma_f32_16x16x32_bf16 v[124:127], v[132:135], v[180:183], v[124:127]
	v_mfma_f32_16x16x32_bf16 v[116:119], v[132:135], v[188:191], 0
	v_mfma_f32_16x16x32_bf16 v[116:119], v[128:131], v[184:187], v[116:119]
	v_mfma_f32_16x16x32_bf16 v[88:91], v[128:131], v[192:195], 0
	v_mfma_f32_16x16x32_bf16 v[88:91], v[132:135], v[200:203], v[88:91]
	v_mfma_f32_16x16x32_bf16 v[72:75], v[132:135], v[208:211], 0
	v_mfma_f32_16x16x32_bf16 v[72:75], v[128:131], v[204:207], v[72:75]
	v_mfma_f32_16x16x32_bf16 v[76:79], v[136:139], v[204:207], 0
	v_mfma_f32_16x16x32_bf16 v[76:79], v[140:143], v[208:211], v[76:79]
	v_mfma_f32_16x16x32_bf16 v[100:103], v[140:143], v[200:203], 0
	v_mfma_f32_16x16x32_bf16 v[100:103], v[136:139], v[192:195], v[100:103]
	v_mfma_f32_16x16x32_bf16 v[108:111], v[136:139], v[184:187], 0
	v_mfma_f32_16x16x32_bf16 v[108:111], v[140:143], v[188:191], v[108:111]
	v_mfma_f32_16x16x32_bf16 v[120:123], v[140:143], v[180:183], 0
	v_mfma_f32_16x16x32_bf16 v[120:123], v[136:139], v[160:163], v[120:123]
	v_mfma_f32_16x16x32_bf16 v[112:115], v[144:147], v[160:163], 0
	v_mfma_f32_16x16x32_bf16 v[112:115], v[148:151], v[180:183], v[112:115]
	v_mfma_f32_16x16x32_bf16 v[96:99], v[148:151], v[188:191], 0
	v_mfma_f32_16x16x32_bf16 v[96:99], v[144:147], v[184:187], v[96:99]
	v_mfma_f32_16x16x32_bf16 v[80:83], v[144:147], v[192:195], 0
	v_mfma_f32_16x16x32_bf16 v[80:83], v[148:151], v[200:203], v[80:83]
	v_mfma_f32_16x16x32_bf16 v[64:67], v[148:151], v[208:211], 0
	v_mfma_f32_16x16x32_bf16 v[64:67], v[144:147], v[204:207], v[64:67]
	v_mfma_f32_16x16x32_bf16 v[68:71], v[152:155], v[204:207], 0
	v_mfma_f32_16x16x32_bf16 v[68:71], v[156:159], v[208:211], v[68:71]
	v_mfma_f32_16x16x32_bf16 v[84:87], v[156:159], v[200:203], 0
	v_mfma_f32_16x16x32_bf16 v[84:87], v[152:155], v[192:195], v[84:87]
	s_setprio 2
	s_barrier
	v_mfma_f32_16x16x32_bf16 v[92:95], v[152:155], v[184:187], 0
	v_mfma_f32_16x16x32_bf16 v[92:95], v[156:159], v[188:191], v[92:95]
	v_mfma_f32_16x16x32_bf16 v[104:107], v[156:159], v[180:183], 0
	v_mfma_f32_16x16x32_bf16 v[104:107], v[152:155], v[160:163], v[104:107]
	s_setprio 2
	s_add_i32 s24, s45, s35
	v_lshl_add_u64 v[212:213], s[26:27], 0, v[166:167]
	s_mov_b32 m0, s24
	ds_read_b128 v[160:163], v199 offset:16384
	ds_read_b128 v[180:183], v199 offset:17408
	ds_read_b128 v[184:187], v199 offset:18432
	ds_read_b128 v[188:191], v199 offset:19456
	ds_read_b128 v[192:195], v199 offset:20480
	ds_read_b128 v[200:203], v199 offset:21504
	ds_read_b128 v[204:207], v199 offset:22528
	ds_read_b128 v[208:211], v199 offset:23552
	global_load_lds_dwordx4 v[212:213], off
	s_add_i32 m0, s24, 0x2000
	s_add_u32 s24, s26, 0xb0000
	v_lshl_add_u64 v[214:215], s[26:27], 0, v[170:171]
	s_addc_u32 s25, s27, 0
	s_add_i32 s54, s46, s35
	global_load_lds_dwordx4 v[214:215], off
	v_lshl_add_u64 v[216:217], s[24:25], 0, v[166:167]
	s_mov_b32 m0, s54
	v_lshl_add_u64 v[218:219], s[28:29], 0, v[168:169]
	global_load_lds_dwordx4 v[216:217], off
	s_add_i32 m0, s54, 0x2000
	v_lshl_add_u64 v[216:217], s[24:25], 0, v[170:171]
	global_load_lds_dwordx4 v[216:217], off
	s_mov_b32 m0, s36
	v_lshl_add_u64 v[216:217], s[28:29], 0, v[164:165]
	global_load_lds_dwordx4 v[216:217], off
	s_mov_b32 m0, s37
	s_nop 0
	global_load_lds_dwordx4 v[218:219], off
	s_waitcnt vmcnt(8) lgkmcnt(0)
	s_barrier
	s_setprio 1
	v_mfma_f32_16x16x32_bf16 v[56:59], v[128:131], v[160:163], 0
	v_mfma_f32_16x16x32_bf16 v[56:59], v[132:135], v[180:183], v[56:59]
	v_mfma_f32_16x16x32_bf16 v[40:43], v[132:135], v[188:191], 0
	v_mfma_f32_16x16x32_bf16 v[40:43], v[128:131], v[184:187], v[40:43]
	v_mfma_f32_16x16x32_bf16 v[24:27], v[128:131], v[192:195], 0
	v_mfma_f32_16x16x32_bf16 v[24:27], v[132:135], v[200:203], v[24:27]
	v_mfma_f32_16x16x32_bf16 v[8:11], v[132:135], v[208:211], 0
	v_mfma_f32_16x16x32_bf16 v[8:11], v[128:131], v[204:207], v[8:11]
	v_mfma_f32_16x16x32_bf16 v[12:15], v[136:139], v[204:207], 0
	v_mfma_f32_16x16x32_bf16 v[12:15], v[140:143], v[208:211], v[12:15]
	v_mfma_f32_16x16x32_bf16 v[28:31], v[140:143], v[200:203], 0
	v_mfma_f32_16x16x32_bf16 v[28:31], v[136:139], v[192:195], v[28:31]
	v_mfma_f32_16x16x32_bf16 v[44:47], v[136:139], v[184:187], 0
	v_mfma_f32_16x16x32_bf16 v[44:47], v[140:143], v[188:191], v[44:47]
	v_mfma_f32_16x16x32_bf16 v[60:63], v[140:143], v[180:183], 0
	v_mfma_f32_16x16x32_bf16 v[60:63], v[136:139], v[160:163], v[60:63]
	v_mfma_f32_16x16x32_bf16 v[48:51], v[144:147], v[160:163], 0
	v_mfma_f32_16x16x32_bf16 v[48:51], v[148:151], v[180:183], v[48:51]
	v_mfma_f32_16x16x32_bf16 v[32:35], v[148:151], v[188:191], 0
	v_mfma_f32_16x16x32_bf16 v[32:35], v[144:147], v[184:187], v[32:35]
	v_mfma_f32_16x16x32_bf16 v[16:19], v[144:147], v[192:195], 0
	v_mfma_f32_16x16x32_bf16 v[16:19], v[148:151], v[200:203], v[16:19]
	v_mfma_f32_16x16x32_bf16 v[0:3], v[148:151], v[208:211], 0
	v_mfma_f32_16x16x32_bf16 v[0:3], v[144:147], v[204:207], v[0:3]
	v_mfma_f32_16x16x32_bf16 v[4:7], v[152:155], v[204:207], 0
	v_mfma_f32_16x16x32_bf16 v[4:7], v[156:159], v[208:211], v[4:7]
	v_mfma_f32_16x16x32_bf16 v[20:23], v[156:159], v[200:203], 0
	v_mfma_f32_16x16x32_bf16 v[20:23], v[152:155], v[192:195], v[20:23]
	s_setprio 2
	s_barrier
	v_mfma_f32_16x16x32_bf16 v[36:39], v[152:155], v[184:187], 0
	v_mfma_f32_16x16x32_bf16 v[36:39], v[156:159], v[188:191], v[36:39]
	v_mfma_f32_16x16x32_bf16 v[52:55], v[156:159], v[180:183], 0
	v_mfma_f32_16x16x32_bf16 v[52:55], v[152:155], v[160:163], v[52:55]
	s_setprio 0
	s_add_i32 s54, 0, 0x18000
	s_add_i32 s55, 0, 0x1c000
	v_add_u32_e32 v140, s54, v196
	v_add_u32_e32 v156, s55, v196
	ds_read_b128 v[128:131], v140
	ds_read_b128 v[132:135], v140 offset:1024
	ds_read_b128 v[136:139], v140 offset:2048
	ds_read_b128 v[140:143], v140 offset:3072
	ds_read_b128 v[144:147], v156
	ds_read_b128 v[148:151], v156 offset:1024
	ds_read_b128 v[152:155], v156 offset:2048
	ds_read_b128 v[156:159], v156 offset:3072
	s_add_u32 s24, s28, 0xb0000
	s_addc_u32 s25, s29, 0
	s_mov_b32 m0, s38
	v_lshl_add_u64 v[220:221], s[24:25], 0, v[164:165]
	ds_read_b128 v[160:163], v199 offset:32768
	ds_read_b128 v[180:183], v199 offset:33792
	ds_read_b128 v[184:187], v199 offset:34816
	ds_read_b128 v[188:191], v199 offset:35840
	ds_read_b128 v[192:195], v199 offset:36864
	ds_read_b128 v[200:203], v199 offset:37888
	ds_read_b128 v[204:207], v199 offset:38912
	ds_read_b128 v[208:211], v199 offset:39936
	global_load_lds_dwordx4 v[220:221], off
	s_mov_b32 m0, s39
	v_lshl_add_u64 v[220:221], s[24:25], 0, v[168:169]
	global_load_lds_dwordx4 v[220:221], off
	s_waitcnt vmcnt(8) lgkmcnt(0)
	s_barrier
	s_setprio 1
	v_mfma_f32_16x16x32_bf16 v[124:127], v[128:131], v[160:163], v[124:127]
	v_mfma_f32_16x16x32_bf16 v[124:127], v[132:135], v[180:183], v[124:127]
	v_mfma_f32_16x16x32_bf16 v[116:119], v[132:135], v[188:191], v[116:119]
	v_mfma_f32_16x16x32_bf16 v[116:119], v[128:131], v[184:187], v[116:119]
	v_mfma_f32_16x16x32_bf16 v[88:91], v[128:131], v[192:195], v[88:91]
	v_mfma_f32_16x16x32_bf16 v[88:91], v[132:135], v[200:203], v[88:91]
	v_mfma_f32_16x16x32_bf16 v[72:75], v[132:135], v[208:211], v[72:75]
	v_mfma_f32_16x16x32_bf16 v[72:75], v[128:131], v[204:207], v[72:75]
	v_mfma_f32_16x16x32_bf16 v[76:79], v[136:139], v[204:207], v[76:79]
	v_mfma_f32_16x16x32_bf16 v[76:79], v[140:143], v[208:211], v[76:79]
	v_mfma_f32_16x16x32_bf16 v[100:103], v[140:143], v[200:203], v[100:103]
	v_mfma_f32_16x16x32_bf16 v[100:103], v[136:139], v[192:195], v[100:103]
	v_mfma_f32_16x16x32_bf16 v[108:111], v[136:139], v[184:187], v[108:111]
	v_mfma_f32_16x16x32_bf16 v[108:111], v[140:143], v[188:191], v[108:111]
	v_mfma_f32_16x16x32_bf16 v[120:123], v[140:143], v[180:183], v[120:123]
	v_mfma_f32_16x16x32_bf16 v[120:123], v[136:139], v[160:163], v[120:123]
	v_mfma_f32_16x16x32_bf16 v[112:115], v[144:147], v[160:163], v[112:115]
	v_mfma_f32_16x16x32_bf16 v[112:115], v[148:151], v[180:183], v[112:115]
	v_mfma_f32_16x16x32_bf16 v[96:99], v[148:151], v[188:191], v[96:99]
	v_mfma_f32_16x16x32_bf16 v[96:99], v[144:147], v[184:187], v[96:99]
	v_mfma_f32_16x16x32_bf16 v[80:83], v[144:147], v[192:195], v[80:83]
	v_mfma_f32_16x16x32_bf16 v[80:83], v[148:151], v[200:203], v[80:83]
	v_mfma_f32_16x16x32_bf16 v[64:67], v[148:151], v[208:211], v[64:67]
	v_mfma_f32_16x16x32_bf16 v[64:67], v[144:147], v[204:207], v[64:67]
	v_mfma_f32_16x16x32_bf16 v[68:71], v[152:155], v[204:207], v[68:71]
	v_mfma_f32_16x16x32_bf16 v[68:71], v[156:159], v[208:211], v[68:71]
	v_mfma_f32_16x16x32_bf16 v[84:87], v[156:159], v[200:203], v[84:87]
	v_mfma_f32_16x16x32_bf16 v[84:87], v[152:155], v[192:195], v[84:87]
	s_setprio 2
	s_barrier
	v_mfma_f32_16x16x32_bf16 v[92:95], v[152:155], v[184:187], v[92:95]
	v_mfma_f32_16x16x32_bf16 v[92:95], v[156:159], v[188:191], v[92:95]
	v_mfma_f32_16x16x32_bf16 v[104:107], v[156:159], v[180:183], v[104:107]
	v_mfma_f32_16x16x32_bf16 v[104:107], v[152:155], v[160:163], v[104:107]
	s_setprio 2
	s_add_i32 s24, s54, s35
	v_lshl_add_u64 v[212:213], v[212:213], 0, s[16:17]
	s_mov_b32 m0, s24
	ds_read_b128 v[160:163], v199 offset:49152
	ds_read_b128 v[180:183], v199 offset:50176
	ds_read_b128 v[184:187], v199 offset:51200
	ds_read_b128 v[188:191], v199 offset:52224
	ds_read_b128 v[192:195], v199 offset:53248
	ds_read_b128 v[200:203], v199 offset:54272
	ds_read_b128 v[204:207], v199 offset:55296
	ds_read_b128 v[208:211], v199 offset:56320
	global_load_lds_dwordx4 v[212:213], off
	s_add_i32 m0, s24, 0x2000
	s_add_u32 s24, s26, 0xb0080
	v_lshl_add_u64 v[212:213], v[214:215], 0, s[16:17]
	s_addc_u32 s25, s27, 0
	s_add_i32 s26, s55, s35
	global_load_lds_dwordx4 v[212:213], off
	s_mov_b32 m0, s26
	v_lshl_add_u64 v[212:213], s[24:25], 0, v[166:167]
	global_load_lds_dwordx4 v[212:213], off
	s_add_i32 m0, s26, 0x2000
	v_lshl_add_u64 v[212:213], s[24:25], 0, v[170:171]
	global_load_lds_dwordx4 v[212:213], off
	s_mov_b32 m0, s41
	v_lshl_add_u64 v[212:213], v[216:217], 0, s[16:17]
	global_load_lds_dwordx4 v[212:213], off
	s_mov_b32 m0, s42
	v_lshl_add_u64 v[212:213], v[218:219], 0, s[16:17]
	global_load_lds_dwordx4 v[212:213], off
	s_waitcnt vmcnt(8) lgkmcnt(0)
	s_barrier
	s_setprio 1
	v_mfma_f32_16x16x32_bf16 v[56:59], v[128:131], v[160:163], v[56:59]
	v_mfma_f32_16x16x32_bf16 v[56:59], v[132:135], v[180:183], v[56:59]
	v_mfma_f32_16x16x32_bf16 v[40:43], v[132:135], v[188:191], v[40:43]
	v_mfma_f32_16x16x32_bf16 v[40:43], v[128:131], v[184:187], v[40:43]
	v_mfma_f32_16x16x32_bf16 v[24:27], v[128:131], v[192:195], v[24:27]
	v_mfma_f32_16x16x32_bf16 v[24:27], v[132:135], v[200:203], v[24:27]
	v_mfma_f32_16x16x32_bf16 v[8:11], v[132:135], v[208:211], v[8:11]
	v_mfma_f32_16x16x32_bf16 v[8:11], v[128:131], v[204:207], v[8:11]
	v_mfma_f32_16x16x32_bf16 v[12:15], v[136:139], v[204:207], v[12:15]
	v_mfma_f32_16x16x32_bf16 v[12:15], v[140:143], v[208:211], v[12:15]
	v_mfma_f32_16x16x32_bf16 v[28:31], v[140:143], v[200:203], v[28:31]
	v_mfma_f32_16x16x32_bf16 v[28:31], v[136:139], v[192:195], v[28:31]
	v_mfma_f32_16x16x32_bf16 v[44:47], v[136:139], v[184:187], v[44:47]
	v_mfma_f32_16x16x32_bf16 v[44:47], v[140:143], v[188:191], v[44:47]
	v_mfma_f32_16x16x32_bf16 v[60:63], v[140:143], v[180:183], v[60:63]
	v_mfma_f32_16x16x32_bf16 v[60:63], v[136:139], v[160:163], v[60:63]
	v_mfma_f32_16x16x32_bf16 v[48:51], v[144:147], v[160:163], v[48:51]
	v_mfma_f32_16x16x32_bf16 v[48:51], v[148:151], v[180:183], v[48:51]
	v_mfma_f32_16x16x32_bf16 v[32:35], v[148:151], v[188:191], v[32:35]
	v_mfma_f32_16x16x32_bf16 v[32:35], v[144:147], v[184:187], v[32:35]
	v_mfma_f32_16x16x32_bf16 v[16:19], v[144:147], v[192:195], v[16:19]
	v_mfma_f32_16x16x32_bf16 v[16:19], v[148:151], v[200:203], v[16:19]
	v_mfma_f32_16x16x32_bf16 v[0:3], v[148:151], v[208:211], v[0:3]
	v_mfma_f32_16x16x32_bf16 v[0:3], v[144:147], v[204:207], v[0:3]
	v_mfma_f32_16x16x32_bf16 v[4:7], v[152:155], v[204:207], v[4:7]
	v_mfma_f32_16x16x32_bf16 v[4:7], v[156:159], v[208:211], v[4:7]
	v_mfma_f32_16x16x32_bf16 v[20:23], v[156:159], v[200:203], v[20:23]
	v_mfma_f32_16x16x32_bf16 v[20:23], v[152:155], v[192:195], v[20:23]
	s_setprio 2
	s_barrier
	v_mfma_f32_16x16x32_bf16 v[36:39], v[152:155], v[184:187], v[36:39]
	v_mfma_f32_16x16x32_bf16 v[36:39], v[156:159], v[188:191], v[36:39]
	v_mfma_f32_16x16x32_bf16 v[52:55], v[156:159], v[180:183], v[52:55]
	v_mfma_f32_16x16x32_bf16 v[52:55], v[152:155], v[160:163], v[52:55]
	s_setprio 0
	s_add_i32 s53, s53, 2
	s_add_u32 s51, s51, 0x100
	s_addc_u32 s52, s52, 0
	s_cmp_gt_u32 s53, 41
	s_mov_b64 s[24:25], s[4:5]
.LBB0_1310:
	ds_read_b128 v[128:131], v197
	ds_read_b128 v[132:135], v197 offset:1024
	ds_read_b128 v[136:139], v197 offset:2048
	ds_read_b128 v[140:143], v197 offset:3072
	ds_read_b128 v[144:147], v198
	ds_read_b128 v[148:151], v198 offset:1024
	ds_read_b128 v[152:155], v198 offset:2048
	ds_read_b128 v[156:159], v198 offset:3072
	s_add_u32 s4, s24, 0x100
	s_addc_u32 s5, s25, 0
	s_cmp_eq_u32 s53, 40
	s_cselect_b32 s29, s21, s5
	s_cselect_b32 s28, s20, s4
	s_cselect_b32 s27, s23, s52
	s_cselect_b32 s26, s22, s51
	v_lshl_add_u64 v[212:213], s[24:25], 0, v[172:173]
	s_add_i32 m0, s36, 0xc000
	ds_read_b128 v[160:163], v199
	ds_read_b128 v[180:183], v199 offset:1024
	ds_read_b128 v[184:187], v199 offset:2048
	ds_read_b128 v[188:191], v199 offset:3072
	ds_read_b128 v[192:195], v199 offset:4096
	ds_read_b128 v[200:203], v199 offset:5120
	ds_read_b128 v[204:207], v199 offset:6144
	ds_read_b128 v[208:211], v199 offset:7168
	global_load_lds_dwordx4 v[212:213], off
	s_add_i32 m0, s36, 0xe000
	v_lshl_add_u64 v[212:213], s[24:25], 0, v[174:175]
	global_load_lds_dwordx4 v[212:213], off
	s_waitcnt vmcnt(8) lgkmcnt(0)
	s_barrier
	s_setprio 1
	v_mfma_f32_16x16x32_bf16 v[124:127], v[128:131], v[160:163], v[124:127]
	v_mfma_f32_16x16x32_bf16 v[124:127], v[132:135], v[180:183], v[124:127]
	v_mfma_f32_16x16x32_bf16 v[116:119], v[132:135], v[188:191], v[116:119]
	v_mfma_f32_16x16x32_bf16 v[116:119], v[128:131], v[184:187], v[116:119]
	v_mfma_f32_16x16x32_bf16 v[88:91], v[128:131], v[192:195], v[88:91]
	v_mfma_f32_16x16x32_bf16 v[88:91], v[132:135], v[200:203], v[88:91]
	v_mfma_f32_16x16x32_bf16 v[72:75], v[132:135], v[208:211], v[72:75]
	v_mfma_f32_16x16x32_bf16 v[72:75], v[128:131], v[204:207], v[72:75]
	v_mfma_f32_16x16x32_bf16 v[76:79], v[136:139], v[204:207], v[76:79]
	v_mfma_f32_16x16x32_bf16 v[76:79], v[140:143], v[208:211], v[76:79]
	v_mfma_f32_16x16x32_bf16 v[100:103], v[140:143], v[200:203], v[100:103]
	v_mfma_f32_16x16x32_bf16 v[100:103], v[136:139], v[192:195], v[100:103]
	v_mfma_f32_16x16x32_bf16 v[108:111], v[136:139], v[184:187], v[108:111]
	v_mfma_f32_16x16x32_bf16 v[108:111], v[140:143], v[188:191], v[108:111]
	v_mfma_f32_16x16x32_bf16 v[120:123], v[140:143], v[180:183], v[120:123]
	v_mfma_f32_16x16x32_bf16 v[120:123], v[136:139], v[160:163], v[120:123]
	v_mfma_f32_16x16x32_bf16 v[112:115], v[144:147], v[160:163], v[112:115]
	v_mfma_f32_16x16x32_bf16 v[112:115], v[148:151], v[180:183], v[112:115]
	v_mfma_f32_16x16x32_bf16 v[96:99], v[148:151], v[188:191], v[96:99]
	v_mfma_f32_16x16x32_bf16 v[96:99], v[144:147], v[184:187], v[96:99]
	v_mfma_f32_16x16x32_bf16 v[80:83], v[144:147], v[192:195], v[80:83]
	v_mfma_f32_16x16x32_bf16 v[80:83], v[148:151], v[200:203], v[80:83]
	v_mfma_f32_16x16x32_bf16 v[64:67], v[148:151], v[208:211], v[64:67]
	v_mfma_f32_16x16x32_bf16 v[64:67], v[144:147], v[204:207], v[64:67]
	v_mfma_f32_16x16x32_bf16 v[68:71], v[152:155], v[204:207], v[68:71]
	v_mfma_f32_16x16x32_bf16 v[68:71], v[156:159], v[208:211], v[68:71]
	v_mfma_f32_16x16x32_bf16 v[84:87], v[156:159], v[200:203], v[84:87]
	v_mfma_f32_16x16x32_bf16 v[84:87], v[152:155], v[192:195], v[84:87]
	s_setprio 2
	s_barrier
	v_mfma_f32_16x16x32_bf16 v[92:95], v[152:155], v[184:187], v[92:95]
	v_mfma_f32_16x16x32_bf16 v[92:95], v[156:159], v[188:191], v[92:95]
	v_mfma_f32_16x16x32_bf16 v[104:107], v[156:159], v[180:183], v[104:107]
	v_mfma_f32_16x16x32_bf16 v[104:107], v[152:155], v[160:163], v[104:107]
	s_setprio 2
	s_add_i32 s24, s45, s35
	v_lshl_add_u64 v[212:213], s[26:27], 0, v[166:167]
	s_mov_b32 m0, s24
	ds_read_b128 v[160:163], v199 offset:16384
	ds_read_b128 v[180:183], v199 offset:17408
	ds_read_b128 v[184:187], v199 offset:18432
	ds_read_b128 v[188:191], v199 offset:19456
	ds_read_b128 v[192:195], v199 offset:20480
	ds_read_b128 v[200:203], v199 offset:21504
	ds_read_b128 v[204:207], v199 offset:22528
	ds_read_b128 v[208:211], v199 offset:23552
	global_load_lds_dwordx4 v[212:213], off
	s_add_i32 m0, s24, 0x2000
	s_add_u32 s24, s26, 0xb0000
	v_lshl_add_u64 v[214:215], s[26:27], 0, v[170:171]
	s_addc_u32 s25, s27, 0
	s_add_i32 s54, s46, s35
	global_load_lds_dwordx4 v[214:215], off
	v_lshl_add_u64 v[216:217], s[24:25], 0, v[166:167]
	s_mov_b32 m0, s54
	v_lshl_add_u64 v[218:219], s[28:29], 0, v[168:169]
	global_load_lds_dwordx4 v[216:217], off
	s_add_i32 m0, s54, 0x2000
	v_lshl_add_u64 v[216:217], s[24:25], 0, v[170:171]
	global_load_lds_dwordx4 v[216:217], off
	s_mov_b32 m0, s36
	v_lshl_add_u64 v[216:217], s[28:29], 0, v[164:165]
	global_load_lds_dwordx4 v[216:217], off
	s_mov_b32 m0, s37
	s_nop 0
	global_load_lds_dwordx4 v[218:219], off
	s_waitcnt vmcnt(8) lgkmcnt(0)
	s_barrier
	s_setprio 1
	v_mfma_f32_16x16x32_bf16 v[56:59], v[128:131], v[160:163], v[56:59]
	v_mfma_f32_16x16x32_bf16 v[56:59], v[132:135], v[180:183], v[56:59]
	v_mfma_f32_16x16x32_bf16 v[40:43], v[132:135], v[188:191], v[40:43]
	v_mfma_f32_16x16x32_bf16 v[40:43], v[128:131], v[184:187], v[40:43]
	v_mfma_f32_16x16x32_bf16 v[24:27], v[128:131], v[192:195], v[24:27]
	v_mfma_f32_16x16x32_bf16 v[24:27], v[132:135], v[200:203], v[24:27]
	v_mfma_f32_16x16x32_bf16 v[8:11], v[132:135], v[208:211], v[8:11]
	v_mfma_f32_16x16x32_bf16 v[8:11], v[128:131], v[204:207], v[8:11]
	v_mfma_f32_16x16x32_bf16 v[12:15], v[136:139], v[204:207], v[12:15]
	v_mfma_f32_16x16x32_bf16 v[12:15], v[140:143], v[208:211], v[12:15]
	v_mfma_f32_16x16x32_bf16 v[28:31], v[140:143], v[200:203], v[28:31]
	v_mfma_f32_16x16x32_bf16 v[28:31], v[136:139], v[192:195], v[28:31]
	v_mfma_f32_16x16x32_bf16 v[44:47], v[136:139], v[184:187], v[44:47]
	v_mfma_f32_16x16x32_bf16 v[44:47], v[140:143], v[188:191], v[44:47]
	v_mfma_f32_16x16x32_bf16 v[60:63], v[140:143], v[180:183], v[60:63]
	v_mfma_f32_16x16x32_bf16 v[60:63], v[136:139], v[160:163], v[60:63]
	v_mfma_f32_16x16x32_bf16 v[48:51], v[144:147], v[160:163], v[48:51]
	v_mfma_f32_16x16x32_bf16 v[48:51], v[148:151], v[180:183], v[48:51]
	v_mfma_f32_16x16x32_bf16 v[32:35], v[148:151], v[188:191], v[32:35]
	v_mfma_f32_16x16x32_bf16 v[32:35], v[144:147], v[184:187], v[32:35]
	v_mfma_f32_16x16x32_bf16 v[16:19], v[144:147], v[192:195], v[16:19]
	v_mfma_f32_16x16x32_bf16 v[16:19], v[148:151], v[200:203], v[16:19]
	v_mfma_f32_16x16x32_bf16 v[0:3], v[148:151], v[208:211], v[0:3]
	v_mfma_f32_16x16x32_bf16 v[0:3], v[144:147], v[204:207], v[0:3]
	v_mfma_f32_16x16x32_bf16 v[4:7], v[152:155], v[204:207], v[4:7]
	v_mfma_f32_16x16x32_bf16 v[4:7], v[156:159], v[208:211], v[4:7]
	v_mfma_f32_16x16x32_bf16 v[20:23], v[156:159], v[200:203], v[20:23]
	v_mfma_f32_16x16x32_bf16 v[20:23], v[152:155], v[192:195], v[20:23]
	s_setprio 2
	s_barrier
	v_mfma_f32_16x16x32_bf16 v[36:39], v[152:155], v[184:187], v[36:39]
	v_mfma_f32_16x16x32_bf16 v[36:39], v[156:159], v[188:191], v[36:39]
	v_mfma_f32_16x16x32_bf16 v[52:55], v[156:159], v[180:183], v[52:55]
	v_mfma_f32_16x16x32_bf16 v[52:55], v[152:155], v[160:163], v[52:55]
	s_setprio 0
	s_add_i32 s54, 0, 0x18000
	s_add_i32 s55, 0, 0x1c000
	v_add_u32_e32 v140, s54, v196
	v_add_u32_e32 v156, s55, v196
	ds_read_b128 v[128:131], v140
	ds_read_b128 v[132:135], v140 offset:1024
	ds_read_b128 v[136:139], v140 offset:2048
	ds_read_b128 v[140:143], v140 offset:3072
	ds_read_b128 v[144:147], v156
	ds_read_b128 v[148:151], v156 offset:1024
	ds_read_b128 v[152:155], v156 offset:2048
	ds_read_b128 v[156:159], v156 offset:3072
	s_add_u32 s24, s28, 0xb0000
	s_addc_u32 s25, s29, 0
	s_mov_b32 m0, s38
	v_lshl_add_u64 v[220:221], s[24:25], 0, v[164:165]
	ds_read_b128 v[160:163], v199 offset:32768
	ds_read_b128 v[180:183], v199 offset:33792
	ds_read_b128 v[184:187], v199 offset:34816
	ds_read_b128 v[188:191], v199 offset:35840
	ds_read_b128 v[192:195], v199 offset:36864
	ds_read_b128 v[200:203], v199 offset:37888
	ds_read_b128 v[204:207], v199 offset:38912
	ds_read_b128 v[208:211], v199 offset:39936
	global_load_lds_dwordx4 v[220:221], off
	s_mov_b32 m0, s39
	v_lshl_add_u64 v[220:221], s[24:25], 0, v[168:169]
	global_load_lds_dwordx4 v[220:221], off
	s_waitcnt vmcnt(8) lgkmcnt(0)
	s_barrier
	s_setprio 1
	v_mfma_f32_16x16x32_bf16 v[124:127], v[128:131], v[160:163], v[124:127]
	v_mfma_f32_16x16x32_bf16 v[124:127], v[132:135], v[180:183], v[124:127]
	v_mfma_f32_16x16x32_bf16 v[116:119], v[132:135], v[188:191], v[116:119]
	v_mfma_f32_16x16x32_bf16 v[116:119], v[128:131], v[184:187], v[116:119]
	v_mfma_f32_16x16x32_bf16 v[88:91], v[128:131], v[192:195], v[88:91]
	v_mfma_f32_16x16x32_bf16 v[88:91], v[132:135], v[200:203], v[88:91]
	v_mfma_f32_16x16x32_bf16 v[72:75], v[132:135], v[208:211], v[72:75]
	v_mfma_f32_16x16x32_bf16 v[72:75], v[128:131], v[204:207], v[72:75]
	v_mfma_f32_16x16x32_bf16 v[76:79], v[136:139], v[204:207], v[76:79]
	v_mfma_f32_16x16x32_bf16 v[76:79], v[140:143], v[208:211], v[76:79]
	v_mfma_f32_16x16x32_bf16 v[100:103], v[140:143], v[200:203], v[100:103]
	v_mfma_f32_16x16x32_bf16 v[100:103], v[136:139], v[192:195], v[100:103]
	v_mfma_f32_16x16x32_bf16 v[108:111], v[136:139], v[184:187], v[108:111]
	v_mfma_f32_16x16x32_bf16 v[108:111], v[140:143], v[188:191], v[108:111]
	v_mfma_f32_16x16x32_bf16 v[120:123], v[140:143], v[180:183], v[120:123]
	v_mfma_f32_16x16x32_bf16 v[120:123], v[136:139], v[160:163], v[120:123]
	v_mfma_f32_16x16x32_bf16 v[112:115], v[144:147], v[160:163], v[112:115]
	v_mfma_f32_16x16x32_bf16 v[112:115], v[148:151], v[180:183], v[112:115]
	v_mfma_f32_16x16x32_bf16 v[96:99], v[148:151], v[188:191], v[96:99]
	v_mfma_f32_16x16x32_bf16 v[96:99], v[144:147], v[184:187], v[96:99]
	v_mfma_f32_16x16x32_bf16 v[80:83], v[144:147], v[192:195], v[80:83]
	v_mfma_f32_16x16x32_bf16 v[80:83], v[148:151], v[200:203], v[80:83]
	v_mfma_f32_16x16x32_bf16 v[64:67], v[148:151], v[208:211], v[64:67]
	v_mfma_f32_16x16x32_bf16 v[64:67], v[144:147], v[204:207], v[64:67]
	v_mfma_f32_16x16x32_bf16 v[68:71], v[152:155], v[204:207], v[68:71]
	v_mfma_f32_16x16x32_bf16 v[68:71], v[156:159], v[208:211], v[68:71]
	v_mfma_f32_16x16x32_bf16 v[84:87], v[156:159], v[200:203], v[84:87]
	v_mfma_f32_16x16x32_bf16 v[84:87], v[152:155], v[192:195], v[84:87]
	s_setprio 2
	s_barrier
	v_mfma_f32_16x16x32_bf16 v[92:95], v[152:155], v[184:187], v[92:95]
	v_mfma_f32_16x16x32_bf16 v[92:95], v[156:159], v[188:191], v[92:95]
	v_mfma_f32_16x16x32_bf16 v[104:107], v[156:159], v[180:183], v[104:107]
	v_mfma_f32_16x16x32_bf16 v[104:107], v[152:155], v[160:163], v[104:107]
	s_setprio 2
	s_add_i32 s24, s54, s35
	v_lshl_add_u64 v[212:213], v[212:213], 0, s[16:17]
	s_mov_b32 m0, s24
	ds_read_b128 v[160:163], v199 offset:49152
	ds_read_b128 v[180:183], v199 offset:50176
	ds_read_b128 v[184:187], v199 offset:51200
	ds_read_b128 v[188:191], v199 offset:52224
	ds_read_b128 v[192:195], v199 offset:53248
	ds_read_b128 v[200:203], v199 offset:54272
	ds_read_b128 v[204:207], v199 offset:55296
	ds_read_b128 v[208:211], v199 offset:56320
	global_load_lds_dwordx4 v[212:213], off
	s_add_i32 m0, s24, 0x2000
	s_add_u32 s24, s26, 0xb0080
	v_lshl_add_u64 v[212:213], v[214:215], 0, s[16:17]
	s_addc_u32 s25, s27, 0
	s_add_i32 s26, s55, s35
	global_load_lds_dwordx4 v[212:213], off
	s_mov_b32 m0, s26
	v_lshl_add_u64 v[212:213], s[24:25], 0, v[166:167]
	global_load_lds_dwordx4 v[212:213], off
	s_add_i32 m0, s26, 0x2000
	v_lshl_add_u64 v[212:213], s[24:25], 0, v[170:171]
	global_load_lds_dwordx4 v[212:213], off
	s_mov_b32 m0, s41
	v_lshl_add_u64 v[212:213], v[216:217], 0, s[16:17]
	global_load_lds_dwordx4 v[212:213], off
	s_mov_b32 m0, s42
	v_lshl_add_u64 v[212:213], v[218:219], 0, s[16:17]
	global_load_lds_dwordx4 v[212:213], off
	s_waitcnt vmcnt(8) lgkmcnt(0)
	s_barrier
	s_setprio 1
	v_mfma_f32_16x16x32_bf16 v[56:59], v[128:131], v[160:163], v[56:59]
	v_mfma_f32_16x16x32_bf16 v[56:59], v[132:135], v[180:183], v[56:59]
	v_mfma_f32_16x16x32_bf16 v[40:43], v[132:135], v[188:191], v[40:43]
	v_mfma_f32_16x16x32_bf16 v[40:43], v[128:131], v[184:187], v[40:43]
	v_mfma_f32_16x16x32_bf16 v[24:27], v[128:131], v[192:195], v[24:27]
	v_mfma_f32_16x16x32_bf16 v[24:27], v[132:135], v[200:203], v[24:27]
	v_mfma_f32_16x16x32_bf16 v[8:11], v[132:135], v[208:211], v[8:11]
	v_mfma_f32_16x16x32_bf16 v[8:11], v[128:131], v[204:207], v[8:11]
	v_mfma_f32_16x16x32_bf16 v[12:15], v[136:139], v[204:207], v[12:15]
	v_mfma_f32_16x16x32_bf16 v[12:15], v[140:143], v[208:211], v[12:15]
	v_mfma_f32_16x16x32_bf16 v[28:31], v[140:143], v[200:203], v[28:31]
	v_mfma_f32_16x16x32_bf16 v[28:31], v[136:139], v[192:195], v[28:31]
	v_mfma_f32_16x16x32_bf16 v[44:47], v[136:139], v[184:187], v[44:47]
	v_mfma_f32_16x16x32_bf16 v[44:47], v[140:143], v[188:191], v[44:47]
	v_mfma_f32_16x16x32_bf16 v[60:63], v[140:143], v[180:183], v[60:63]
	v_mfma_f32_16x16x32_bf16 v[60:63], v[136:139], v[160:163], v[60:63]
	v_mfma_f32_16x16x32_bf16 v[48:51], v[144:147], v[160:163], v[48:51]
	v_mfma_f32_16x16x32_bf16 v[48:51], v[148:151], v[180:183], v[48:51]
	v_mfma_f32_16x16x32_bf16 v[32:35], v[148:151], v[188:191], v[32:35]
	v_mfma_f32_16x16x32_bf16 v[32:35], v[144:147], v[184:187], v[32:35]
	v_mfma_f32_16x16x32_bf16 v[16:19], v[144:147], v[192:195], v[16:19]
	v_mfma_f32_16x16x32_bf16 v[16:19], v[148:151], v[200:203], v[16:19]
	v_mfma_f32_16x16x32_bf16 v[0:3], v[148:151], v[208:211], v[0:3]
	v_mfma_f32_16x16x32_bf16 v[0:3], v[144:147], v[204:207], v[0:3]
	v_mfma_f32_16x16x32_bf16 v[4:7], v[152:155], v[204:207], v[4:7]
	v_mfma_f32_16x16x32_bf16 v[4:7], v[156:159], v[208:211], v[4:7]
	v_mfma_f32_16x16x32_bf16 v[20:23], v[156:159], v[200:203], v[20:23]
	v_mfma_f32_16x16x32_bf16 v[20:23], v[152:155], v[192:195], v[20:23]
	s_setprio 2
	s_barrier
	v_mfma_f32_16x16x32_bf16 v[36:39], v[152:155], v[184:187], v[36:39]
	v_mfma_f32_16x16x32_bf16 v[36:39], v[156:159], v[188:191], v[36:39]
	v_mfma_f32_16x16x32_bf16 v[52:55], v[156:159], v[180:183], v[52:55]
	v_mfma_f32_16x16x32_bf16 v[52:55], v[152:155], v[160:163], v[52:55]
	s_setprio 0
	s_add_i32 s53, s53, 2
	s_add_u32 s51, s51, 0x100
	s_addc_u32 s52, s52, 0
	s_cmp_gt_u32 s53, 41
	s_mov_b64 s[24:25], s[4:5]
	s_cbranch_scc0 .LBB0_1310
